# mfma_runs_pinned_to_8B_phase0
# speedup vs baseline: 1.0021x; 1.0013x over previous
.LBB0_224:
	s_add_u32 s33, s16, 0x100
	s_addc_u32 s42, s17, 0
	s_mov_b32 s18, -2
	s_mov_b64 s[4:5], 0
	s_add_i32 s43, s18, 2
	s_lshr_b32 s44, s43, 2
	s_add_i32 s16, s18, 4
	s_lshl_b64 s[60:61], s[44:45], 9
	s_lshr_b32 s44, s16, 2
	s_and_b32 s47, s4, 0x100
	s_lshl_b64 s[16:17], s[44:45], 9
	s_add_u32 s19, s14, s16
	s_addc_u32 s44, s15, s17
	s_add_u32 s16, s4, 0x100
	s_addc_u32 s17, s5, 0
	s_and_b32 s49, s16, 0x100
	s_add_u32 s49, s19, s49
	s_addc_u32 s19, s44, 0
	s_add_u32 s4, s33, s4
	s_addc_u32 s5, s42, s5
	s_add_i32 s44, 0, 0x10000
	s_add_u32 s59, s14, s60
	s_addc_u32 s60, s15, s61
	s_cmp_eq_u32 s18, 28
	s_cselect_b32 s19, s11, s19
	s_cselect_b32 s18, s10, s49
	s_cselect_b32 s5, s13, s5
	s_cselect_b32 s4, s12, s4
	s_add_i32 s49, 0, 0x14000
	v_add_u32_e32 v154, s44, v152
	v_add_u32_e32 v170, s49, v152
	ds_read_b128 v[140:143], v154
	ds_read_b128 v[144:147], v154 offset:1024
	ds_read_b128 v[148:151], v154 offset:2048
	ds_read_b128 v[154:157], v154 offset:3072
	ds_read_b128 v[158:161], v170
	ds_read_b128 v[162:165], v170 offset:1024
	ds_read_b128 v[166:169], v170 offset:2048
	ds_read_b128 v[170:173], v170 offset:3072
	s_add_u32 s47, s59, s47
	s_addc_u32 s59, s60, 0
	s_add_u32 s60, s47, 0x80080
	s_addc_u32 s61, s59, 0
	v_lshl_add_u64 v[194:195], s[60:61], 0, v[130:131]
	s_add_i32 m0, s27, 0xc000
	ds_read_b128 v[174:177], v153
	ds_read_b128 v[178:181], v153 offset:1024
	ds_read_b128 v[182:185], v153 offset:2048
	ds_read_b128 v[186:189], v153 offset:3072
	ds_read_b128 v[190:193], v153 offset:4096
	ds_read_b128 v[198:201], v153 offset:5120
	ds_read_b128 v[202:205], v153 offset:6144
	ds_read_b128 v[206:209], v153 offset:7168
	global_load_lds_dwordx4 v[194:195], off
	v_lshl_add_u64 v[194:195], s[60:61], 0, v[134:135]
	s_add_i32 m0, s27, 0xe000
	s_nop 0
	global_load_lds_dwordx4 v[194:195], off
	s_waitcnt vmcnt(8)
	s_waitcnt lgkmcnt(0)
	s_barrier
	s_setprio 1
	s_waitcnt lgkmcnt(0)
	v_mfma_f32_16x16x32_bf16 v[126:129], v[140:143], v[174:177], 0
	v_mfma_f32_16x16x32_bf16 v[126:129], v[144:147], v[178:181], v[126:129]
	v_mfma_f32_16x16x32_bf16 v[122:125], v[154:157], v[178:181], 0
	v_mfma_f32_16x16x32_bf16 v[122:125], v[148:151], v[174:177], v[122:125]
	v_mfma_f32_16x16x32_bf16 v[106:109], v[148:151], v[182:185], 0
	v_mfma_f32_16x16x32_bf16 v[106:109], v[154:157], v[186:189], v[106:109]
	v_mfma_f32_16x16x32_bf16 v[110:113], v[144:147], v[186:189], 0
	v_mfma_f32_16x16x32_bf16 v[110:113], v[140:143], v[182:185], v[110:113]
	v_mfma_f32_16x16x32_bf16 v[94:97], v[140:143], v[190:193], 0
	v_mfma_f32_16x16x32_bf16 v[94:97], v[144:147], v[198:201], v[94:97]
	v_mfma_f32_16x16x32_bf16 v[90:93], v[154:157], v[198:201], 0
	v_mfma_f32_16x16x32_bf16 v[90:93], v[148:151], v[190:193], v[90:93]
	v_mfma_f32_16x16x32_bf16 v[74:77], v[148:151], v[202:205], 0
	v_mfma_f32_16x16x32_bf16 v[74:77], v[154:157], v[206:209], v[74:77]
	v_mfma_f32_16x16x32_bf16 v[78:81], v[144:147], v[206:209], 0
	v_mfma_f32_16x16x32_bf16 v[78:81], v[140:143], v[202:205], v[78:81]
	s_setprio 0
	s_setprio 1
	v_mfma_f32_16x16x32_bf16 v[118:121], v[158:161], v[174:177], 0
	v_mfma_f32_16x16x32_bf16 v[118:121], v[162:165], v[178:181], v[118:121]
	v_mfma_f32_16x16x32_bf16 v[114:117], v[170:173], v[178:181], 0
	v_mfma_f32_16x16x32_bf16 v[114:117], v[166:169], v[174:177], v[114:117]
	v_mfma_f32_16x16x32_bf16 v[98:101], v[166:169], v[182:185], 0
	v_mfma_f32_16x16x32_bf16 v[98:101], v[170:173], v[186:189], v[98:101]
	v_mfma_f32_16x16x32_bf16 v[102:105], v[162:165], v[186:189], 0
	v_mfma_f32_16x16x32_bf16 v[102:105], v[158:161], v[182:185], v[102:105]
	v_mfma_f32_16x16x32_bf16 v[86:89], v[158:161], v[190:193], 0
	v_mfma_f32_16x16x32_bf16 v[86:89], v[162:165], v[198:201], v[86:89]
	v_mfma_f32_16x16x32_bf16 v[82:85], v[170:173], v[198:201], 0
	v_mfma_f32_16x16x32_bf16 v[82:85], v[166:169], v[190:193], v[82:85]
	v_mfma_f32_16x16x32_bf16 v[66:69], v[166:169], v[202:205], 0
	v_mfma_f32_16x16x32_bf16 v[66:69], v[170:173], v[206:209], v[66:69]
	v_mfma_f32_16x16x32_bf16 v[70:73], v[162:165], v[206:209], 0
	v_mfma_f32_16x16x32_bf16 v[70:73], v[158:161], v[202:205], v[70:73]
	s_setprio 0
	s_barrier
	s_add_i32 s44, s44, s9
	v_lshl_add_u64 v[194:195], s[4:5], 0, v[132:133]
	s_mov_b32 m0, s44
	ds_read_b128 v[174:177], v153 offset:16384
	ds_read_b128 v[178:181], v153 offset:17408
	ds_read_b128 v[182:185], v153 offset:18432
	ds_read_b128 v[186:189], v153 offset:19456
	ds_read_b128 v[190:193], v153 offset:20480
	ds_read_b128 v[198:201], v153 offset:21504
	ds_read_b128 v[202:205], v153 offset:22528
	ds_read_b128 v[206:209], v153 offset:23552
	global_load_lds_dwordx4 v[194:195], off
	s_add_i32 m0, s44, 0x2000
	s_add_u32 s60, s4, 0x80000
	v_lshl_add_u64 v[210:211], s[4:5], 0, v[136:137]
	s_addc_u32 s61, s5, 0
	s_add_i32 s44, s49, s9
	global_load_lds_dwordx4 v[210:211], off
	v_lshl_add_u64 v[212:213], s[60:61], 0, v[132:133]
	s_mov_b32 m0, s44
	v_lshl_add_u64 v[214:215], s[18:19], 0, v[134:135]
	global_load_lds_dwordx4 v[212:213], off
	v_lshl_add_u64 v[212:213], s[60:61], 0, v[136:137]
	s_add_i32 m0, s44, 0x2000
	s_nop 0
	global_load_lds_dwordx4 v[212:213], off
	v_lshl_add_u64 v[212:213], s[18:19], 0, v[130:131]
	s_mov_b32 m0, s27
	s_nop 0
	global_load_lds_dwordx4 v[212:213], off
	s_mov_b32 m0, s28
	s_nop 0
	global_load_lds_dwordx4 v[214:215], off
	s_waitcnt vmcnt(8)
	s_waitcnt lgkmcnt(0)
	s_barrier
	s_setprio 1
	v_mfma_f32_16x16x32_bf16 v[62:65], v[140:143], v[174:177], 0
	v_mfma_f32_16x16x32_bf16 v[62:65], v[144:147], v[178:181], v[62:65]
	v_mfma_f32_16x16x32_bf16 v[58:61], v[154:157], v[178:181], 0
	v_mfma_f32_16x16x32_bf16 v[58:61], v[148:151], v[174:177], v[58:61]
	v_mfma_f32_16x16x32_bf16 v[42:45], v[148:151], v[182:185], 0
	v_mfma_f32_16x16x32_bf16 v[42:45], v[154:157], v[186:189], v[42:45]
	v_mfma_f32_16x16x32_bf16 v[46:49], v[144:147], v[186:189], 0
	v_mfma_f32_16x16x32_bf16 v[46:49], v[140:143], v[182:185], v[46:49]
	v_mfma_f32_16x16x32_bf16 v[30:33], v[140:143], v[190:193], 0
	v_mfma_f32_16x16x32_bf16 v[30:33], v[144:147], v[198:201], v[30:33]
	v_mfma_f32_16x16x32_bf16 v[26:29], v[154:157], v[198:201], 0
	v_mfma_f32_16x16x32_bf16 v[26:29], v[148:151], v[190:193], v[26:29]
	v_mfma_f32_16x16x32_bf16 v[10:13], v[148:151], v[202:205], 0
	v_mfma_f32_16x16x32_bf16 v[10:13], v[154:157], v[206:209], v[10:13]
	v_mfma_f32_16x16x32_bf16 v[14:17], v[144:147], v[206:209], 0
	v_mfma_f32_16x16x32_bf16 v[14:17], v[140:143], v[202:205], v[14:17]
	s_setprio 0
	s_setprio 1
	v_mfma_f32_16x16x32_bf16 v[54:57], v[158:161], v[174:177], 0
	v_mfma_f32_16x16x32_bf16 v[54:57], v[162:165], v[178:181], v[54:57]
	v_mfma_f32_16x16x32_bf16 v[50:53], v[170:173], v[178:181], 0
	v_mfma_f32_16x16x32_bf16 v[50:53], v[166:169], v[174:177], v[50:53]
	v_mfma_f32_16x16x32_bf16 v[34:37], v[166:169], v[182:185], 0
	v_mfma_f32_16x16x32_bf16 v[34:37], v[170:173], v[186:189], v[34:37]
	v_mfma_f32_16x16x32_bf16 v[38:41], v[162:165], v[186:189], 0
	v_mfma_f32_16x16x32_bf16 v[38:41], v[158:161], v[182:185], v[38:41]
	v_mfma_f32_16x16x32_bf16 v[22:25], v[158:161], v[190:193], 0
	v_mfma_f32_16x16x32_bf16 v[22:25], v[162:165], v[198:201], v[22:25]
	v_mfma_f32_16x16x32_bf16 v[18:21], v[170:173], v[198:201], 0
	v_mfma_f32_16x16x32_bf16 v[18:21], v[166:169], v[190:193], v[18:21]
	v_mfma_f32_16x16x32_bf16 v[2:5], v[166:169], v[202:205], 0
	v_mfma_f32_16x16x32_bf16 v[2:5], v[170:173], v[206:209], v[2:5]
	v_mfma_f32_16x16x32_bf16 v[6:9], v[162:165], v[206:209], 0
	v_mfma_f32_16x16x32_bf16 v[6:9], v[158:161], v[202:205], v[6:9]
	s_setprio 0
	s_barrier
	s_add_i32 s44, 0, 0x18000
	s_add_i32 s47, 0, 0x1c000
	v_add_u32_e32 v154, s44, v152
	v_add_u32_e32 v170, s47, v152
	ds_read_b128 v[140:143], v154
	ds_read_b128 v[144:147], v154 offset:1024
	ds_read_b128 v[148:151], v154 offset:2048
	ds_read_b128 v[154:157], v154 offset:3072
	ds_read_b128 v[158:161], v170
	ds_read_b128 v[162:165], v170 offset:1024
	ds_read_b128 v[166:169], v170 offset:2048
	ds_read_b128 v[170:173], v170 offset:3072
	s_add_u32 s18, s18, 0x80000
	s_addc_u32 s19, s19, 0
	s_mov_b32 m0, s29
	v_lshl_add_u64 v[216:217], s[18:19], 0, v[130:131]
	ds_read_b128 v[174:177], v153 offset:32768
	ds_read_b128 v[178:181], v153 offset:33792
	ds_read_b128 v[182:185], v153 offset:34816
	ds_read_b128 v[186:189], v153 offset:35840
	ds_read_b128 v[190:193], v153 offset:36864
	ds_read_b128 v[198:201], v153 offset:37888
	ds_read_b128 v[202:205], v153 offset:38912
	ds_read_b128 v[206:209], v153 offset:39936
	global_load_lds_dwordx4 v[216:217], off
	v_lshl_add_u64 v[216:217], s[18:19], 0, v[134:135]
	s_mov_b32 m0, s30
	s_nop 0
	global_load_lds_dwordx4 v[216:217], off
	s_waitcnt vmcnt(8)
	s_waitcnt lgkmcnt(0)
	s_barrier
	s_setprio 1
	v_mfma_f32_16x16x32_bf16 v[126:129], v[140:143], v[174:177], v[126:129]
	v_mfma_f32_16x16x32_bf16 v[126:129], v[144:147], v[178:181], v[126:129]
	v_mfma_f32_16x16x32_bf16 v[122:125], v[154:157], v[178:181], v[122:125]
	v_mfma_f32_16x16x32_bf16 v[122:125], v[148:151], v[174:177], v[122:125]
	v_mfma_f32_16x16x32_bf16 v[106:109], v[148:151], v[182:185], v[106:109]
	v_mfma_f32_16x16x32_bf16 v[106:109], v[154:157], v[186:189], v[106:109]
	v_mfma_f32_16x16x32_bf16 v[110:113], v[144:147], v[186:189], v[110:113]
	v_mfma_f32_16x16x32_bf16 v[110:113], v[140:143], v[182:185], v[110:113]
	v_mfma_f32_16x16x32_bf16 v[94:97], v[140:143], v[190:193], v[94:97]
	v_mfma_f32_16x16x32_bf16 v[94:97], v[144:147], v[198:201], v[94:97]
	v_mfma_f32_16x16x32_bf16 v[90:93], v[154:157], v[198:201], v[90:93]
	v_mfma_f32_16x16x32_bf16 v[90:93], v[148:151], v[190:193], v[90:93]
	v_mfma_f32_16x16x32_bf16 v[74:77], v[148:151], v[202:205], v[74:77]
	v_mfma_f32_16x16x32_bf16 v[74:77], v[154:157], v[206:209], v[74:77]
	v_mfma_f32_16x16x32_bf16 v[78:81], v[144:147], v[206:209], v[78:81]
	v_mfma_f32_16x16x32_bf16 v[78:81], v[140:143], v[202:205], v[78:81]
	s_setprio 0
	s_setprio 1
	v_mfma_f32_16x16x32_bf16 v[118:121], v[158:161], v[174:177], v[118:121]
	v_mfma_f32_16x16x32_bf16 v[118:121], v[162:165], v[178:181], v[118:121]
	v_mfma_f32_16x16x32_bf16 v[114:117], v[170:173], v[178:181], v[114:117]
	v_mfma_f32_16x16x32_bf16 v[114:117], v[166:169], v[174:177], v[114:117]
	v_mfma_f32_16x16x32_bf16 v[98:101], v[166:169], v[182:185], v[98:101]
	v_mfma_f32_16x16x32_bf16 v[98:101], v[170:173], v[186:189], v[98:101]
	v_mfma_f32_16x16x32_bf16 v[102:105], v[162:165], v[186:189], v[102:105]
	v_mfma_f32_16x16x32_bf16 v[102:105], v[158:161], v[182:185], v[102:105]
	v_mfma_f32_16x16x32_bf16 v[86:89], v[158:161], v[190:193], v[86:89]
	v_mfma_f32_16x16x32_bf16 v[86:89], v[162:165], v[198:201], v[86:89]
	v_mfma_f32_16x16x32_bf16 v[82:85], v[170:173], v[198:201], v[82:85]
	v_mfma_f32_16x16x32_bf16 v[82:85], v[166:169], v[190:193], v[82:85]
	v_mfma_f32_16x16x32_bf16 v[66:69], v[166:169], v[202:205], v[66:69]
	v_mfma_f32_16x16x32_bf16 v[66:69], v[170:173], v[206:209], v[66:69]
	v_mfma_f32_16x16x32_bf16 v[70:73], v[162:165], v[206:209], v[70:73]
	v_mfma_f32_16x16x32_bf16 v[70:73], v[158:161], v[202:205], v[70:73]
	s_setprio 0
	s_barrier
	s_add_i32 s18, s44, s9
	v_lshl_add_u64 v[194:195], v[194:195], 0, s[2:3]
	s_mov_b32 m0, s18
	ds_read_b128 v[174:177], v153 offset:49152
	ds_read_b128 v[178:181], v153 offset:50176
	ds_read_b128 v[182:185], v153 offset:51200
	ds_read_b128 v[186:189], v153 offset:52224
	ds_read_b128 v[190:193], v153 offset:53248
	ds_read_b128 v[198:201], v153 offset:54272
	ds_read_b128 v[202:205], v153 offset:55296
	ds_read_b128 v[206:209], v153 offset:56320
	global_load_lds_dwordx4 v[194:195], off
	s_add_i32 m0, s18, 0x2000
	s_add_u32 s4, s4, 0x80080
	v_lshl_add_u64 v[194:195], v[210:211], 0, s[2:3]
	s_addc_u32 s5, s5, 0
	s_add_i32 s18, s47, s9
	global_load_lds_dwordx4 v[194:195], off
	v_lshl_add_u64 v[194:195], s[4:5], 0, v[132:133]
	s_mov_b32 m0, s18
	s_nop 0
	global_load_lds_dwordx4 v[194:195], off
	v_lshl_add_u64 v[194:195], s[4:5], 0, v[136:137]
	s_add_i32 m0, s18, 0x2000
	s_nop 0
	global_load_lds_dwordx4 v[194:195], off
	v_lshl_add_u64 v[194:195], v[212:213], 0, s[2:3]
	s_mov_b32 m0, s51
	s_nop 0
	global_load_lds_dwordx4 v[194:195], off
	v_lshl_add_u64 v[194:195], v[214:215], 0, s[2:3]
	s_mov_b32 m0, s52
	s_nop 0
	global_load_lds_dwordx4 v[194:195], off
	s_waitcnt vmcnt(8)
	s_waitcnt lgkmcnt(0)
	s_barrier
	s_setprio 1
	s_waitcnt lgkmcnt(0)
	v_mfma_f32_16x16x32_bf16 v[62:65], v[140:143], v[174:177], v[62:65]
	v_mfma_f32_16x16x32_bf16 v[62:65], v[144:147], v[178:181], v[62:65]
	v_mfma_f32_16x16x32_bf16 v[58:61], v[154:157], v[178:181], v[58:61]
	v_mfma_f32_16x16x32_bf16 v[58:61], v[148:151], v[174:177], v[58:61]
	v_mfma_f32_16x16x32_bf16 v[42:45], v[148:151], v[182:185], v[42:45]
	v_mfma_f32_16x16x32_bf16 v[42:45], v[154:157], v[186:189], v[42:45]
	v_mfma_f32_16x16x32_bf16 v[46:49], v[144:147], v[186:189], v[46:49]
	v_mfma_f32_16x16x32_bf16 v[46:49], v[140:143], v[182:185], v[46:49]
	v_mfma_f32_16x16x32_bf16 v[30:33], v[140:143], v[190:193], v[30:33]
	v_mfma_f32_16x16x32_bf16 v[30:33], v[144:147], v[198:201], v[30:33]
	v_mfma_f32_16x16x32_bf16 v[26:29], v[154:157], v[198:201], v[26:29]
	v_mfma_f32_16x16x32_bf16 v[26:29], v[148:151], v[190:193], v[26:29]
	v_mfma_f32_16x16x32_bf16 v[10:13], v[148:151], v[202:205], v[10:13]
	v_mfma_f32_16x16x32_bf16 v[10:13], v[154:157], v[206:209], v[10:13]
	v_mfma_f32_16x16x32_bf16 v[14:17], v[144:147], v[206:209], v[14:17]
	v_mfma_f32_16x16x32_bf16 v[14:17], v[140:143], v[202:205], v[14:17]
	s_setprio 0
	s_setprio 1
	v_mfma_f32_16x16x32_bf16 v[54:57], v[158:161], v[174:177], v[54:57]
	v_mfma_f32_16x16x32_bf16 v[54:57], v[162:165], v[178:181], v[54:57]
	v_mfma_f32_16x16x32_bf16 v[50:53], v[170:173], v[178:181], v[50:53]
	v_mfma_f32_16x16x32_bf16 v[50:53], v[166:169], v[174:177], v[50:53]
	v_mfma_f32_16x16x32_bf16 v[34:37], v[166:169], v[182:185], v[34:37]
	v_mfma_f32_16x16x32_bf16 v[34:37], v[170:173], v[186:189], v[34:37]
	v_mfma_f32_16x16x32_bf16 v[38:41], v[162:165], v[186:189], v[38:41]
	v_mfma_f32_16x16x32_bf16 v[38:41], v[158:161], v[182:185], v[38:41]
	v_mfma_f32_16x16x32_bf16 v[22:25], v[158:161], v[190:193], v[22:25]
	v_mfma_f32_16x16x32_bf16 v[22:25], v[162:165], v[198:201], v[22:25]
	v_mfma_f32_16x16x32_bf16 v[18:21], v[170:173], v[198:201], v[18:21]
	v_mfma_f32_16x16x32_bf16 v[18:21], v[166:169], v[190:193], v[18:21]
	v_mfma_f32_16x16x32_bf16 v[2:5], v[166:169], v[202:205], v[2:5]
	v_mfma_f32_16x16x32_bf16 v[2:5], v[170:173], v[206:209], v[2:5]
	v_mfma_f32_16x16x32_bf16 v[6:9], v[162:165], v[206:209], v[6:9]
	v_mfma_f32_16x16x32_bf16 v[6:9], v[158:161], v[202:205], v[6:9]
	s_setprio 0
	s_barrier
	s_cmp_gt_u32 s43, 29
	s_mov_b64 s[4:5], s[16:17]
	s_mov_b32 s18, s43
	s_cbranch_scc1 .Lpeel_exit_proj
.LBB0_225:
	s_add_i32 s43, s18, 2
	s_lshr_b32 s44, s43, 2
	s_add_i32 s16, s18, 4
	s_lshl_b64 s[60:61], s[44:45], 9
	s_lshr_b32 s44, s16, 2
	s_and_b32 s47, s4, 0x100
	s_lshl_b64 s[16:17], s[44:45], 9
	s_add_u32 s19, s14, s16
	s_addc_u32 s44, s15, s17
	s_add_u32 s16, s4, 0x100
	s_addc_u32 s17, s5, 0
	s_and_b32 s49, s16, 0x100
	s_add_u32 s49, s19, s49
	s_addc_u32 s19, s44, 0
	s_add_u32 s4, s33, s4
	s_addc_u32 s5, s42, s5
	s_add_i32 s44, 0, 0x10000
	s_add_u32 s59, s14, s60
	s_addc_u32 s60, s15, s61
	s_cmp_eq_u32 s18, 28
	s_cselect_b32 s19, s11, s19
	s_cselect_b32 s18, s10, s49
	s_cselect_b32 s5, s13, s5
	s_cselect_b32 s4, s12, s4
	s_add_i32 s49, 0, 0x14000
	v_add_u32_e32 v154, s44, v152
	v_add_u32_e32 v170, s49, v152
	ds_read_b128 v[140:143], v154
	ds_read_b128 v[144:147], v154 offset:1024
	ds_read_b128 v[148:151], v154 offset:2048
	ds_read_b128 v[154:157], v154 offset:3072
	ds_read_b128 v[158:161], v170
	ds_read_b128 v[162:165], v170 offset:1024
	ds_read_b128 v[166:169], v170 offset:2048
	ds_read_b128 v[170:173], v170 offset:3072
	s_add_u32 s47, s59, s47
	s_addc_u32 s59, s60, 0
	s_add_u32 s60, s47, 0x80080
	s_addc_u32 s61, s59, 0
	v_lshl_add_u64 v[194:195], s[60:61], 0, v[130:131]
	s_add_i32 m0, s27, 0xc000
	ds_read_b128 v[174:177], v153
	ds_read_b128 v[178:181], v153 offset:1024
	ds_read_b128 v[182:185], v153 offset:2048
	ds_read_b128 v[186:189], v153 offset:3072
	ds_read_b128 v[190:193], v153 offset:4096
	ds_read_b128 v[198:201], v153 offset:5120
	ds_read_b128 v[202:205], v153 offset:6144
	ds_read_b128 v[206:209], v153 offset:7168
	global_load_lds_dwordx4 v[194:195], off
	v_lshl_add_u64 v[194:195], s[60:61], 0, v[134:135]
	s_add_i32 m0, s27, 0xe000
	s_nop 0
	global_load_lds_dwordx4 v[194:195], off
	s_waitcnt vmcnt(8)
	s_waitcnt lgkmcnt(0)
	s_barrier
	s_setprio 1
	v_mfma_f32_16x16x32_bf16 v[126:129], v[140:143], v[174:177], v[126:129]
	v_mfma_f32_16x16x32_bf16 v[126:129], v[144:147], v[178:181], v[126:129]
	v_mfma_f32_16x16x32_bf16 v[122:125], v[154:157], v[178:181], v[122:125]
	v_mfma_f32_16x16x32_bf16 v[122:125], v[148:151], v[174:177], v[122:125]
	v_mfma_f32_16x16x32_bf16 v[106:109], v[148:151], v[182:185], v[106:109]
	v_mfma_f32_16x16x32_bf16 v[106:109], v[154:157], v[186:189], v[106:109]
	v_mfma_f32_16x16x32_bf16 v[110:113], v[144:147], v[186:189], v[110:113]
	v_mfma_f32_16x16x32_bf16 v[110:113], v[140:143], v[182:185], v[110:113]
	v_mfma_f32_16x16x32_bf16 v[94:97], v[140:143], v[190:193], v[94:97]
	v_mfma_f32_16x16x32_bf16 v[94:97], v[144:147], v[198:201], v[94:97]
	v_mfma_f32_16x16x32_bf16 v[90:93], v[154:157], v[198:201], v[90:93]
	v_mfma_f32_16x16x32_bf16 v[90:93], v[148:151], v[190:193], v[90:93]
	v_mfma_f32_16x16x32_bf16 v[74:77], v[148:151], v[202:205], v[74:77]
	v_mfma_f32_16x16x32_bf16 v[74:77], v[154:157], v[206:209], v[74:77]
	v_mfma_f32_16x16x32_bf16 v[78:81], v[144:147], v[206:209], v[78:81]
	v_mfma_f32_16x16x32_bf16 v[78:81], v[140:143], v[202:205], v[78:81]
	s_setprio 0
	s_setprio 1
	v_mfma_f32_16x16x32_bf16 v[118:121], v[158:161], v[174:177], v[118:121]
	v_mfma_f32_16x16x32_bf16 v[118:121], v[162:165], v[178:181], v[118:121]
	v_mfma_f32_16x16x32_bf16 v[114:117], v[170:173], v[178:181], v[114:117]
	v_mfma_f32_16x16x32_bf16 v[114:117], v[166:169], v[174:177], v[114:117]
	v_mfma_f32_16x16x32_bf16 v[98:101], v[166:169], v[182:185], v[98:101]
	v_mfma_f32_16x16x32_bf16 v[98:101], v[170:173], v[186:189], v[98:101]
	v_mfma_f32_16x16x32_bf16 v[102:105], v[162:165], v[186:189], v[102:105]
	v_mfma_f32_16x16x32_bf16 v[102:105], v[158:161], v[182:185], v[102:105]
	v_mfma_f32_16x16x32_bf16 v[86:89], v[158:161], v[190:193], v[86:89]
	v_mfma_f32_16x16x32_bf16 v[86:89], v[162:165], v[198:201], v[86:89]
	v_mfma_f32_16x16x32_bf16 v[82:85], v[170:173], v[198:201], v[82:85]
	v_mfma_f32_16x16x32_bf16 v[82:85], v[166:169], v[190:193], v[82:85]
	v_mfma_f32_16x16x32_bf16 v[66:69], v[166:169], v[202:205], v[66:69]
	v_mfma_f32_16x16x32_bf16 v[66:69], v[170:173], v[206:209], v[66:69]
	v_mfma_f32_16x16x32_bf16 v[70:73], v[162:165], v[206:209], v[70:73]
	v_mfma_f32_16x16x32_bf16 v[70:73], v[158:161], v[202:205], v[70:73]
	s_setprio 0
	s_barrier
	s_add_i32 s44, s44, s9
	v_lshl_add_u64 v[194:195], s[4:5], 0, v[132:133]
	s_mov_b32 m0, s44
	ds_read_b128 v[174:177], v153 offset:16384
	ds_read_b128 v[178:181], v153 offset:17408
	ds_read_b128 v[182:185], v153 offset:18432
	ds_read_b128 v[186:189], v153 offset:19456
	ds_read_b128 v[190:193], v153 offset:20480
	ds_read_b128 v[198:201], v153 offset:21504
	ds_read_b128 v[202:205], v153 offset:22528
	ds_read_b128 v[206:209], v153 offset:23552
	global_load_lds_dwordx4 v[194:195], off
	s_add_i32 m0, s44, 0x2000
	s_add_u32 s60, s4, 0x80000
	v_lshl_add_u64 v[210:211], s[4:5], 0, v[136:137]
	s_addc_u32 s61, s5, 0
	s_add_i32 s44, s49, s9
	global_load_lds_dwordx4 v[210:211], off
	v_lshl_add_u64 v[212:213], s[60:61], 0, v[132:133]
	s_mov_b32 m0, s44
	v_lshl_add_u64 v[214:215], s[18:19], 0, v[134:135]
	global_load_lds_dwordx4 v[212:213], off
	v_lshl_add_u64 v[212:213], s[60:61], 0, v[136:137]
	s_add_i32 m0, s44, 0x2000
	s_nop 0
	global_load_lds_dwordx4 v[212:213], off
	v_lshl_add_u64 v[212:213], s[18:19], 0, v[130:131]
	s_mov_b32 m0, s27
	s_nop 0
	global_load_lds_dwordx4 v[212:213], off
	s_mov_b32 m0, s28
	s_nop 0
	global_load_lds_dwordx4 v[214:215], off
	s_waitcnt vmcnt(8)
	s_waitcnt lgkmcnt(0)
	s_barrier
	s_setprio 1
	v_mfma_f32_16x16x32_bf16 v[62:65], v[140:143], v[174:177], v[62:65]
	v_mfma_f32_16x16x32_bf16 v[62:65], v[144:147], v[178:181], v[62:65]
	v_mfma_f32_16x16x32_bf16 v[58:61], v[154:157], v[178:181], v[58:61]
	v_mfma_f32_16x16x32_bf16 v[58:61], v[148:151], v[174:177], v[58:61]
	v_mfma_f32_16x16x32_bf16 v[42:45], v[148:151], v[182:185], v[42:45]
	v_mfma_f32_16x16x32_bf16 v[42:45], v[154:157], v[186:189], v[42:45]
	v_mfma_f32_16x16x32_bf16 v[46:49], v[144:147], v[186:189], v[46:49]
	v_mfma_f32_16x16x32_bf16 v[46:49], v[140:143], v[182:185], v[46:49]
	v_mfma_f32_16x16x32_bf16 v[30:33], v[140:143], v[190:193], v[30:33]
	v_mfma_f32_16x16x32_bf16 v[30:33], v[144:147], v[198:201], v[30:33]
	v_mfma_f32_16x16x32_bf16 v[26:29], v[154:157], v[198:201], v[26:29]
	v_mfma_f32_16x16x32_bf16 v[26:29], v[148:151], v[190:193], v[26:29]
	v_mfma_f32_16x16x32_bf16 v[10:13], v[148:151], v[202:205], v[10:13]
	v_mfma_f32_16x16x32_bf16 v[10:13], v[154:157], v[206:209], v[10:13]
	v_mfma_f32_16x16x32_bf16 v[14:17], v[144:147], v[206:209], v[14:17]
	v_mfma_f32_16x16x32_bf16 v[14:17], v[140:143], v[202:205], v[14:17]
	s_setprio 0
	s_setprio 1
	v_mfma_f32_16x16x32_bf16 v[54:57], v[158:161], v[174:177], v[54:57]
	v_mfma_f32_16x16x32_bf16 v[54:57], v[162:165], v[178:181], v[54:57]
	v_mfma_f32_16x16x32_bf16 v[50:53], v[170:173], v[178:181], v[50:53]
	v_mfma_f32_16x16x32_bf16 v[50:53], v[166:169], v[174:177], v[50:53]
	v_mfma_f32_16x16x32_bf16 v[34:37], v[166:169], v[182:185], v[34:37]
	v_mfma_f32_16x16x32_bf16 v[34:37], v[170:173], v[186:189], v[34:37]
	v_mfma_f32_16x16x32_bf16 v[38:41], v[162:165], v[186:189], v[38:41]
	v_mfma_f32_16x16x32_bf16 v[38:41], v[158:161], v[182:185], v[38:41]
	v_mfma_f32_16x16x32_bf16 v[22:25], v[158:161], v[190:193], v[22:25]
	v_mfma_f32_16x16x32_bf16 v[22:25], v[162:165], v[198:201], v[22:25]
	v_mfma_f32_16x16x32_bf16 v[18:21], v[170:173], v[198:201], v[18:21]
	v_mfma_f32_16x16x32_bf16 v[18:21], v[166:169], v[190:193], v[18:21]
	v_mfma_f32_16x16x32_bf16 v[2:5], v[166:169], v[202:205], v[2:5]
	v_mfma_f32_16x16x32_bf16 v[2:5], v[170:173], v[206:209], v[2:5]
	v_mfma_f32_16x16x32_bf16 v[6:9], v[162:165], v[206:209], v[6:9]
	v_mfma_f32_16x16x32_bf16 v[6:9], v[158:161], v[202:205], v[6:9]
	s_setprio 0
	s_barrier
	s_add_i32 s44, 0, 0x18000
	s_add_i32 s47, 0, 0x1c000
	v_add_u32_e32 v154, s44, v152
	v_add_u32_e32 v170, s47, v152
	ds_read_b128 v[140:143], v154
	ds_read_b128 v[144:147], v154 offset:1024
	ds_read_b128 v[148:151], v154 offset:2048
	ds_read_b128 v[154:157], v154 offset:3072
	ds_read_b128 v[158:161], v170
	ds_read_b128 v[162:165], v170 offset:1024
	ds_read_b128 v[166:169], v170 offset:2048
	ds_read_b128 v[170:173], v170 offset:3072
	s_add_u32 s18, s18, 0x80000
	s_addc_u32 s19, s19, 0
	s_mov_b32 m0, s29
	v_lshl_add_u64 v[216:217], s[18:19], 0, v[130:131]
	ds_read_b128 v[174:177], v153 offset:32768
	ds_read_b128 v[178:181], v153 offset:33792
	ds_read_b128 v[182:185], v153 offset:34816
	ds_read_b128 v[186:189], v153 offset:35840
	ds_read_b128 v[190:193], v153 offset:36864
	ds_read_b128 v[198:201], v153 offset:37888
	ds_read_b128 v[202:205], v153 offset:38912
	ds_read_b128 v[206:209], v153 offset:39936
	global_load_lds_dwordx4 v[216:217], off
	v_lshl_add_u64 v[216:217], s[18:19], 0, v[134:135]
	s_mov_b32 m0, s30
	s_nop 0
	global_load_lds_dwordx4 v[216:217], off
	s_waitcnt vmcnt(8)
	s_waitcnt lgkmcnt(0)
	s_barrier
	s_setprio 1
	v_mfma_f32_16x16x32_bf16 v[126:129], v[140:143], v[174:177], v[126:129]
	v_mfma_f32_16x16x32_bf16 v[126:129], v[144:147], v[178:181], v[126:129]
	v_mfma_f32_16x16x32_bf16 v[122:125], v[154:157], v[178:181], v[122:125]
	v_mfma_f32_16x16x32_bf16 v[122:125], v[148:151], v[174:177], v[122:125]
	v_mfma_f32_16x16x32_bf16 v[106:109], v[148:151], v[182:185], v[106:109]
	v_mfma_f32_16x16x32_bf16 v[106:109], v[154:157], v[186:189], v[106:109]
	v_mfma_f32_16x16x32_bf16 v[110:113], v[144:147], v[186:189], v[110:113]
	v_mfma_f32_16x16x32_bf16 v[110:113], v[140:143], v[182:185], v[110:113]
	v_mfma_f32_16x16x32_bf16 v[94:97], v[140:143], v[190:193], v[94:97]
	v_mfma_f32_16x16x32_bf16 v[94:97], v[144:147], v[198:201], v[94:97]
	v_mfma_f32_16x16x32_bf16 v[90:93], v[154:157], v[198:201], v[90:93]
	v_mfma_f32_16x16x32_bf16 v[90:93], v[148:151], v[190:193], v[90:93]
	v_mfma_f32_16x16x32_bf16 v[74:77], v[148:151], v[202:205], v[74:77]
	v_mfma_f32_16x16x32_bf16 v[74:77], v[154:157], v[206:209], v[74:77]
	v_mfma_f32_16x16x32_bf16 v[78:81], v[144:147], v[206:209], v[78:81]
	v_mfma_f32_16x16x32_bf16 v[78:81], v[140:143], v[202:205], v[78:81]
	s_setprio 0
	s_setprio 1
	v_mfma_f32_16x16x32_bf16 v[118:121], v[158:161], v[174:177], v[118:121]
	v_mfma_f32_16x16x32_bf16 v[118:121], v[162:165], v[178:181], v[118:121]
	v_mfma_f32_16x16x32_bf16 v[114:117], v[170:173], v[178:181], v[114:117]
	v_mfma_f32_16x16x32_bf16 v[114:117], v[166:169], v[174:177], v[114:117]
	v_mfma_f32_16x16x32_bf16 v[98:101], v[166:169], v[182:185], v[98:101]
	v_mfma_f32_16x16x32_bf16 v[98:101], v[170:173], v[186:189], v[98:101]
	v_mfma_f32_16x16x32_bf16 v[102:105], v[162:165], v[186:189], v[102:105]
	v_mfma_f32_16x16x32_bf16 v[102:105], v[158:161], v[182:185], v[102:105]
	v_mfma_f32_16x16x32_bf16 v[86:89], v[158:161], v[190:193], v[86:89]
	v_mfma_f32_16x16x32_bf16 v[86:89], v[162:165], v[198:201], v[86:89]
	v_mfma_f32_16x16x32_bf16 v[82:85], v[170:173], v[198:201], v[82:85]
	v_mfma_f32_16x16x32_bf16 v[82:85], v[166:169], v[190:193], v[82:85]
	v_mfma_f32_16x16x32_bf16 v[66:69], v[166:169], v[202:205], v[66:69]
	v_mfma_f32_16x16x32_bf16 v[66:69], v[170:173], v[206:209], v[66:69]
	v_mfma_f32_16x16x32_bf16 v[70:73], v[162:165], v[206:209], v[70:73]
	v_mfma_f32_16x16x32_bf16 v[70:73], v[158:161], v[202:205], v[70:73]
	s_setprio 0
	s_barrier
	s_add_i32 s18, s44, s9
	v_lshl_add_u64 v[194:195], v[194:195], 0, s[2:3]
	s_mov_b32 m0, s18
	ds_read_b128 v[174:177], v153 offset:49152
	ds_read_b128 v[178:181], v153 offset:50176
	ds_read_b128 v[182:185], v153 offset:51200
	ds_read_b128 v[186:189], v153 offset:52224
	ds_read_b128 v[190:193], v153 offset:53248
	ds_read_b128 v[198:201], v153 offset:54272
	ds_read_b128 v[202:205], v153 offset:55296
	ds_read_b128 v[206:209], v153 offset:56320
	global_load_lds_dwordx4 v[194:195], off
	s_add_i32 m0, s18, 0x2000
	s_add_u32 s4, s4, 0x80080
	v_lshl_add_u64 v[194:195], v[210:211], 0, s[2:3]
	s_addc_u32 s5, s5, 0
	s_add_i32 s18, s47, s9
	global_load_lds_dwordx4 v[194:195], off
	v_lshl_add_u64 v[194:195], s[4:5], 0, v[132:133]
	s_mov_b32 m0, s18
	s_nop 0
	global_load_lds_dwordx4 v[194:195], off
	v_lshl_add_u64 v[194:195], s[4:5], 0, v[136:137]
	s_add_i32 m0, s18, 0x2000
	s_nop 0
	global_load_lds_dwordx4 v[194:195], off
	v_lshl_add_u64 v[194:195], v[212:213], 0, s[2:3]
	s_mov_b32 m0, s51
	s_nop 0
	global_load_lds_dwordx4 v[194:195], off
	v_lshl_add_u64 v[194:195], v[214:215], 0, s[2:3]
	s_mov_b32 m0, s52
	s_nop 0
	global_load_lds_dwordx4 v[194:195], off
	s_waitcnt vmcnt(8)
	s_waitcnt lgkmcnt(0)
	s_barrier
	s_setprio 1
	s_waitcnt lgkmcnt(0)
	v_mfma_f32_16x16x32_bf16 v[62:65], v[140:143], v[174:177], v[62:65]
	v_mfma_f32_16x16x32_bf16 v[62:65], v[144:147], v[178:181], v[62:65]
	v_mfma_f32_16x16x32_bf16 v[58:61], v[154:157], v[178:181], v[58:61]
	v_mfma_f32_16x16x32_bf16 v[58:61], v[148:151], v[174:177], v[58:61]
	v_mfma_f32_16x16x32_bf16 v[42:45], v[148:151], v[182:185], v[42:45]
	v_mfma_f32_16x16x32_bf16 v[42:45], v[154:157], v[186:189], v[42:45]
	v_mfma_f32_16x16x32_bf16 v[46:49], v[144:147], v[186:189], v[46:49]
	v_mfma_f32_16x16x32_bf16 v[46:49], v[140:143], v[182:185], v[46:49]
	v_mfma_f32_16x16x32_bf16 v[30:33], v[140:143], v[190:193], v[30:33]
	v_mfma_f32_16x16x32_bf16 v[30:33], v[144:147], v[198:201], v[30:33]
	v_mfma_f32_16x16x32_bf16 v[26:29], v[154:157], v[198:201], v[26:29]
	v_mfma_f32_16x16x32_bf16 v[26:29], v[148:151], v[190:193], v[26:29]
	v_mfma_f32_16x16x32_bf16 v[10:13], v[148:151], v[202:205], v[10:13]
	v_mfma_f32_16x16x32_bf16 v[10:13], v[154:157], v[206:209], v[10:13]
	v_mfma_f32_16x16x32_bf16 v[14:17], v[144:147], v[206:209], v[14:17]
	v_mfma_f32_16x16x32_bf16 v[14:17], v[140:143], v[202:205], v[14:17]
	s_setprio 0
	s_setprio 1
	v_mfma_f32_16x16x32_bf16 v[54:57], v[158:161], v[174:177], v[54:57]
	v_mfma_f32_16x16x32_bf16 v[54:57], v[162:165], v[178:181], v[54:57]
	v_mfma_f32_16x16x32_bf16 v[50:53], v[170:173], v[178:181], v[50:53]
	v_mfma_f32_16x16x32_bf16 v[50:53], v[166:169], v[174:177], v[50:53]
	v_mfma_f32_16x16x32_bf16 v[34:37], v[166:169], v[182:185], v[34:37]
	v_mfma_f32_16x16x32_bf16 v[34:37], v[170:173], v[186:189], v[34:37]
	v_mfma_f32_16x16x32_bf16 v[38:41], v[162:165], v[186:189], v[38:41]
	v_mfma_f32_16x16x32_bf16 v[38:41], v[158:161], v[182:185], v[38:41]
	v_mfma_f32_16x16x32_bf16 v[22:25], v[158:161], v[190:193], v[22:25]
	v_mfma_f32_16x16x32_bf16 v[22:25], v[162:165], v[198:201], v[22:25]
	v_mfma_f32_16x16x32_bf16 v[18:21], v[170:173], v[198:201], v[18:21]
	v_mfma_f32_16x16x32_bf16 v[18:21], v[166:169], v[190:193], v[18:21]
	v_mfma_f32_16x16x32_bf16 v[2:5], v[166:169], v[202:205], v[2:5]
	v_mfma_f32_16x16x32_bf16 v[2:5], v[170:173], v[206:209], v[2:5]
	v_mfma_f32_16x16x32_bf16 v[6:9], v[162:165], v[206:209], v[6:9]
	v_mfma_f32_16x16x32_bf16 v[6:9], v[158:161], v[202:205], v[6:9]
	s_setprio 0
	s_barrier
	s_cmp_gt_u32 s43, 29
	s_mov_b64 s[4:5], s[16:17]
	s_mov_b32 s18, s43
	s_cbranch_scc0 .LBB0_225

.LBB0_398:
	s_add_i32 s52, s24, 2
	s_lshr_b32 s44, s52, 2
	s_lshl_b64 s[22:23], s[44:45], 9
	s_add_u32 s22, s14, s22
	s_addc_u32 s23, s15, s23
	s_and_b32 s25, s20, 0x100
	s_add_u32 s53, s22, s25
	s_addc_u32 s55, s23, 0
	s_add_i32 s22, s24, 4
	s_lshr_b32 s44, s22, 2
	s_lshl_b64 s[22:23], s[44:45], 9
	s_add_u32 s25, s14, s22
	s_addc_u32 s44, s15, s23
	s_add_u32 s22, s20, 0x100
	s_addc_u32 s23, s21, 0
	s_and_b32 s54, s22, 0x100
	s_add_u32 s54, s25, s54
	s_addc_u32 s25, s44, 0
	s_add_u32 s20, s50, s20
	s_addc_u32 s21, s51, s21
	s_add_i32 s44, 0, 0x10000
	s_cmp_eq_u32 s24, 28
	s_cselect_b32 s25, s17, s25
	s_cselect_b32 s24, s16, s54
	v_add_u32_e32 v136, s44, v139
	s_cselect_b32 s21, s19, s21
	s_cselect_b32 s20, s18, s20
	s_add_i32 s56, 0, 0x14000
	ds_read_b128 v[142:145], v136
	ds_read_b128 v[146:149], v136 offset:1024
	ds_read_b128 v[150:153], v136 offset:2048
	ds_read_b128 v[154:157], v136 offset:3072
	v_add_u32_e32 v136, s56, v139
	ds_read_b128 v[158:161], v136
	ds_read_b128 v[162:165], v136 offset:1024
	ds_read_b128 v[166:169], v136 offset:2048
	ds_read_b128 v[170:173], v136 offset:3072
	s_add_u32 s54, s53, 0x80080
	s_addc_u32 s55, s55, 0
	v_lshl_add_u64 v[136:137], s[54:55], 0, v[134:135]
	s_add_i32 m0, s34, 0xc000
	ds_read_b128 v[174:177], v141
	ds_read_b128 v[178:181], v141 offset:1024
	ds_read_b128 v[182:185], v141 offset:2048
	ds_read_b128 v[186:189], v141 offset:3072
	ds_read_b128 v[190:193], v141 offset:4096
	ds_read_b128 v[198:201], v141 offset:5120
	ds_read_b128 v[202:205], v141 offset:6144
	ds_read_b128 v[206:209], v141 offset:7168
	global_load_lds_dwordx4 v[136:137], off
	v_lshl_add_u64 v[136:137], s[54:55], 0, v[132:133]
	s_add_i32 m0, s34, 0xe000
	s_nop 0
	global_load_lds_dwordx4 v[136:137], off
	s_waitcnt vmcnt(8)
	s_waitcnt lgkmcnt(0)
	s_barrier
	s_setprio 1
	s_waitcnt lgkmcnt(0)
	v_mfma_f32_16x16x32_bf16 v[126:129], v[142:145], v[174:177], v[126:129]
	v_mfma_f32_16x16x32_bf16 v[126:129], v[146:149], v[178:181], v[126:129]
	v_mfma_f32_16x16x32_bf16 v[122:125], v[154:157], v[178:181], v[122:125]
	v_mfma_f32_16x16x32_bf16 v[122:125], v[150:153], v[174:177], v[122:125]
	v_mfma_f32_16x16x32_bf16 v[106:109], v[150:153], v[182:185], v[106:109]
	v_mfma_f32_16x16x32_bf16 v[106:109], v[154:157], v[186:189], v[106:109]
	v_mfma_f32_16x16x32_bf16 v[114:117], v[146:149], v[186:189], v[114:117]
	v_mfma_f32_16x16x32_bf16 v[114:117], v[142:145], v[182:185], v[114:117]
	v_mfma_f32_16x16x32_bf16 v[98:101], v[142:145], v[190:193], v[98:101]
	v_mfma_f32_16x16x32_bf16 v[98:101], v[146:149], v[198:201], v[98:101]
	v_mfma_f32_16x16x32_bf16 v[90:93], v[154:157], v[198:201], v[90:93]
	v_mfma_f32_16x16x32_bf16 v[90:93], v[150:153], v[190:193], v[90:93]
	v_mfma_f32_16x16x32_bf16 v[74:77], v[150:153], v[202:205], v[74:77]
	v_mfma_f32_16x16x32_bf16 v[74:77], v[154:157], v[206:209], v[74:77]
	v_mfma_f32_16x16x32_bf16 v[82:85], v[146:149], v[206:209], v[82:85]
	v_mfma_f32_16x16x32_bf16 v[82:85], v[142:145], v[202:205], v[82:85]
	s_setprio 0
	s_setprio 1
	v_mfma_f32_16x16x32_bf16 v[118:121], v[158:161], v[174:177], v[118:121]
	v_mfma_f32_16x16x32_bf16 v[118:121], v[162:165], v[178:181], v[118:121]
	v_mfma_f32_16x16x32_bf16 v[110:113], v[170:173], v[178:181], v[110:113]
	v_mfma_f32_16x16x32_bf16 v[110:113], v[166:169], v[174:177], v[110:113]
	v_mfma_f32_16x16x32_bf16 v[94:97], v[166:169], v[182:185], v[94:97]
	v_mfma_f32_16x16x32_bf16 v[94:97], v[170:173], v[186:189], v[94:97]
	v_mfma_f32_16x16x32_bf16 v[102:105], v[162:165], v[186:189], v[102:105]
	v_mfma_f32_16x16x32_bf16 v[102:105], v[158:161], v[182:185], v[102:105]
	v_mfma_f32_16x16x32_bf16 v[86:89], v[158:161], v[190:193], v[86:89]
	v_mfma_f32_16x16x32_bf16 v[86:89], v[162:165], v[198:201], v[86:89]
	v_mfma_f32_16x16x32_bf16 v[78:81], v[170:173], v[198:201], v[78:81]
	v_mfma_f32_16x16x32_bf16 v[78:81], v[166:169], v[190:193], v[78:81]
	v_mfma_f32_16x16x32_bf16 v[66:69], v[166:169], v[202:205], v[66:69]
	v_mfma_f32_16x16x32_bf16 v[66:69], v[170:173], v[206:209], v[66:69]
	v_mfma_f32_16x16x32_bf16 v[70:73], v[162:165], v[206:209], v[70:73]
	v_mfma_f32_16x16x32_bf16 v[70:73], v[158:161], v[202:205], v[70:73]
	s_setprio 0
	s_barrier
	s_add_i32 s44, s44, s33
	v_lshl_add_u64 v[136:137], s[20:21], 0, v[196:197]
	s_mov_b32 m0, s44
	ds_read_b128 v[174:177], v141 offset:16384
	ds_read_b128 v[178:181], v141 offset:17408
	ds_read_b128 v[182:185], v141 offset:18432
	ds_read_b128 v[186:189], v141 offset:19456
	ds_read_b128 v[190:193], v141 offset:20480
	ds_read_b128 v[198:201], v141 offset:21504
	ds_read_b128 v[202:205], v141 offset:22528
	ds_read_b128 v[206:209], v141 offset:23552
	global_load_lds_dwordx4 v[136:137], off
	s_add_i32 m0, s44, 0x2000
	s_add_u32 s54, s20, 0x80000
	v_lshl_add_u64 v[194:195], s[20:21], 0, v[130:131]
	s_addc_u32 s55, s21, 0
	s_add_i32 s44, s56, s33
	global_load_lds_dwordx4 v[194:195], off
	v_lshl_add_u64 v[210:211], s[54:55], 0, v[196:197]
	s_mov_b32 m0, s44
	v_lshl_add_u64 v[212:213], s[24:25], 0, v[132:133]
	global_load_lds_dwordx4 v[210:211], off
	v_lshl_add_u64 v[210:211], s[54:55], 0, v[130:131]
	s_add_i32 m0, s44, 0x2000
	s_nop 0
	global_load_lds_dwordx4 v[210:211], off
	v_lshl_add_u64 v[210:211], s[24:25], 0, v[134:135]
	s_mov_b32 m0, s34
	s_nop 0
	global_load_lds_dwordx4 v[210:211], off
	s_mov_b32 m0, s35
	s_nop 0
	global_load_lds_dwordx4 v[212:213], off
	s_waitcnt vmcnt(8)
	s_waitcnt lgkmcnt(0)
	s_barrier
	s_setprio 1
	v_mfma_f32_16x16x32_bf16 v[62:65], v[142:145], v[174:177], v[62:65]
	v_mfma_f32_16x16x32_bf16 v[62:65], v[146:149], v[178:181], v[62:65]
	v_mfma_f32_16x16x32_bf16 v[58:61], v[154:157], v[178:181], v[58:61]
	v_mfma_f32_16x16x32_bf16 v[58:61], v[150:153], v[174:177], v[58:61]
	v_mfma_f32_16x16x32_bf16 v[42:45], v[150:153], v[182:185], v[42:45]
	v_mfma_f32_16x16x32_bf16 v[42:45], v[154:157], v[186:189], v[42:45]
	v_mfma_f32_16x16x32_bf16 v[50:53], v[146:149], v[186:189], v[50:53]
	v_mfma_f32_16x16x32_bf16 v[50:53], v[142:145], v[182:185], v[50:53]
	v_mfma_f32_16x16x32_bf16 v[34:37], v[142:145], v[190:193], v[34:37]
	v_mfma_f32_16x16x32_bf16 v[34:37], v[146:149], v[198:201], v[34:37]
	v_mfma_f32_16x16x32_bf16 v[26:29], v[154:157], v[198:201], v[26:29]
	v_mfma_f32_16x16x32_bf16 v[26:29], v[150:153], v[190:193], v[26:29]
	v_mfma_f32_16x16x32_bf16 v[10:13], v[150:153], v[202:205], v[10:13]
	v_mfma_f32_16x16x32_bf16 v[10:13], v[154:157], v[206:209], v[10:13]
	v_mfma_f32_16x16x32_bf16 v[18:21], v[146:149], v[206:209], v[18:21]
	v_mfma_f32_16x16x32_bf16 v[18:21], v[142:145], v[202:205], v[18:21]
	s_setprio 0
	s_setprio 1
	v_mfma_f32_16x16x32_bf16 v[54:57], v[158:161], v[174:177], v[54:57]
	v_mfma_f32_16x16x32_bf16 v[54:57], v[162:165], v[178:181], v[54:57]
	v_mfma_f32_16x16x32_bf16 v[46:49], v[170:173], v[178:181], v[46:49]
	v_mfma_f32_16x16x32_bf16 v[46:49], v[166:169], v[174:177], v[46:49]
	v_mfma_f32_16x16x32_bf16 v[30:33], v[166:169], v[182:185], v[30:33]
	v_mfma_f32_16x16x32_bf16 v[30:33], v[170:173], v[186:189], v[30:33]
	v_mfma_f32_16x16x32_bf16 v[38:41], v[162:165], v[186:189], v[38:41]
	v_mfma_f32_16x16x32_bf16 v[38:41], v[158:161], v[182:185], v[38:41]
	v_mfma_f32_16x16x32_bf16 v[22:25], v[158:161], v[190:193], v[22:25]
	v_mfma_f32_16x16x32_bf16 v[22:25], v[162:165], v[198:201], v[22:25]
	v_mfma_f32_16x16x32_bf16 v[14:17], v[170:173], v[198:201], v[14:17]
	v_mfma_f32_16x16x32_bf16 v[14:17], v[166:169], v[190:193], v[14:17]
	v_mfma_f32_16x16x32_bf16 v[2:5], v[166:169], v[202:205], v[2:5]
	v_mfma_f32_16x16x32_bf16 v[2:5], v[170:173], v[206:209], v[2:5]
	v_mfma_f32_16x16x32_bf16 v[6:9], v[162:165], v[206:209], v[6:9]
	v_mfma_f32_16x16x32_bf16 v[6:9], v[158:161], v[202:205], v[6:9]
	s_setprio 0
	s_barrier
	s_add_i32 s44, 0, 0x18000
	s_add_i32 s53, 0, 0x1c000
	v_add_u32_e32 v154, s44, v139
	v_add_u32_e32 v170, s53, v139
	ds_read_b128 v[142:145], v154
	ds_read_b128 v[146:149], v154 offset:1024
	ds_read_b128 v[150:153], v154 offset:2048
	ds_read_b128 v[154:157], v154 offset:3072
	ds_read_b128 v[158:161], v170
	ds_read_b128 v[162:165], v170 offset:1024
	ds_read_b128 v[166:169], v170 offset:2048
	ds_read_b128 v[170:173], v170 offset:3072
	s_add_u32 s24, s24, 0x80000
	s_addc_u32 s25, s25, 0
	s_mov_b32 m0, s36
	v_lshl_add_u64 v[214:215], s[24:25], 0, v[134:135]
	ds_read_b128 v[174:177], v141 offset:32768
	ds_read_b128 v[178:181], v141 offset:33792
	ds_read_b128 v[182:185], v141 offset:34816
	ds_read_b128 v[186:189], v141 offset:35840
	ds_read_b128 v[190:193], v141 offset:36864
	ds_read_b128 v[198:201], v141 offset:37888
	ds_read_b128 v[202:205], v141 offset:38912
	ds_read_b128 v[206:209], v141 offset:39936
	global_load_lds_dwordx4 v[214:215], off
	v_lshl_add_u64 v[214:215], s[24:25], 0, v[132:133]
	s_mov_b32 m0, s37
	s_nop 0
	global_load_lds_dwordx4 v[214:215], off
	s_waitcnt vmcnt(8)
	s_waitcnt lgkmcnt(0)
	s_barrier
	s_setprio 1
	v_mfma_f32_16x16x32_bf16 v[126:129], v[142:145], v[174:177], v[126:129]
	v_mfma_f32_16x16x32_bf16 v[126:129], v[146:149], v[178:181], v[126:129]
	v_mfma_f32_16x16x32_bf16 v[122:125], v[154:157], v[178:181], v[122:125]
	v_mfma_f32_16x16x32_bf16 v[122:125], v[150:153], v[174:177], v[122:125]
	v_mfma_f32_16x16x32_bf16 v[106:109], v[150:153], v[182:185], v[106:109]
	v_mfma_f32_16x16x32_bf16 v[106:109], v[154:157], v[186:189], v[106:109]
	v_mfma_f32_16x16x32_bf16 v[114:117], v[146:149], v[186:189], v[114:117]
	v_mfma_f32_16x16x32_bf16 v[114:117], v[142:145], v[182:185], v[114:117]
	v_mfma_f32_16x16x32_bf16 v[98:101], v[142:145], v[190:193], v[98:101]
	v_mfma_f32_16x16x32_bf16 v[98:101], v[146:149], v[198:201], v[98:101]
	v_mfma_f32_16x16x32_bf16 v[90:93], v[154:157], v[198:201], v[90:93]
	v_mfma_f32_16x16x32_bf16 v[90:93], v[150:153], v[190:193], v[90:93]
	v_mfma_f32_16x16x32_bf16 v[74:77], v[150:153], v[202:205], v[74:77]
	v_mfma_f32_16x16x32_bf16 v[74:77], v[154:157], v[206:209], v[74:77]
	v_mfma_f32_16x16x32_bf16 v[82:85], v[146:149], v[206:209], v[82:85]
	v_mfma_f32_16x16x32_bf16 v[82:85], v[142:145], v[202:205], v[82:85]
	s_setprio 0
	s_setprio 1
	v_mfma_f32_16x16x32_bf16 v[118:121], v[158:161], v[174:177], v[118:121]
	v_mfma_f32_16x16x32_bf16 v[118:121], v[162:165], v[178:181], v[118:121]
	v_mfma_f32_16x16x32_bf16 v[110:113], v[170:173], v[178:181], v[110:113]
	v_mfma_f32_16x16x32_bf16 v[110:113], v[166:169], v[174:177], v[110:113]
	v_mfma_f32_16x16x32_bf16 v[94:97], v[166:169], v[182:185], v[94:97]
	v_mfma_f32_16x16x32_bf16 v[94:97], v[170:173], v[186:189], v[94:97]
	v_mfma_f32_16x16x32_bf16 v[102:105], v[162:165], v[186:189], v[102:105]
	v_mfma_f32_16x16x32_bf16 v[102:105], v[158:161], v[182:185], v[102:105]
	v_mfma_f32_16x16x32_bf16 v[86:89], v[158:161], v[190:193], v[86:89]
	v_mfma_f32_16x16x32_bf16 v[86:89], v[162:165], v[198:201], v[86:89]
	v_mfma_f32_16x16x32_bf16 v[78:81], v[170:173], v[198:201], v[78:81]
	v_mfma_f32_16x16x32_bf16 v[78:81], v[166:169], v[190:193], v[78:81]
	v_mfma_f32_16x16x32_bf16 v[66:69], v[166:169], v[202:205], v[66:69]
	v_mfma_f32_16x16x32_bf16 v[66:69], v[170:173], v[206:209], v[66:69]
	v_mfma_f32_16x16x32_bf16 v[70:73], v[162:165], v[206:209], v[70:73]
	v_mfma_f32_16x16x32_bf16 v[70:73], v[158:161], v[202:205], v[70:73]
	s_setprio 0
	s_barrier
	s_add_i32 s24, s44, s33
	v_lshl_add_u64 v[136:137], v[136:137], 0, s[2:3]
	s_mov_b32 m0, s24
	ds_read_b128 v[174:177], v141 offset:49152
	ds_read_b128 v[178:181], v141 offset:50176
	ds_read_b128 v[182:185], v141 offset:51200
	ds_read_b128 v[186:189], v141 offset:52224
	ds_read_b128 v[190:193], v141 offset:53248
	ds_read_b128 v[198:201], v141 offset:54272
	ds_read_b128 v[202:205], v141 offset:55296
	ds_read_b128 v[206:209], v141 offset:56320
	global_load_lds_dwordx4 v[136:137], off
	s_add_i32 m0, s24, 0x2000
	s_add_u32 s20, s20, 0x80080
	v_lshl_add_u64 v[136:137], v[194:195], 0, s[2:3]
	s_addc_u32 s21, s21, 0
	s_add_i32 s24, s53, s33
	global_load_lds_dwordx4 v[136:137], off
	v_lshl_add_u64 v[136:137], s[20:21], 0, v[196:197]
	s_mov_b32 m0, s24
	s_nop 0
	global_load_lds_dwordx4 v[136:137], off
	v_lshl_add_u64 v[136:137], s[20:21], 0, v[130:131]
	s_add_i32 m0, s24, 0x2000
	s_nop 0
	global_load_lds_dwordx4 v[136:137], off
	v_lshl_add_u64 v[136:137], v[210:211], 0, s[2:3]
	s_mov_b32 m0, s38
	s_nop 0
	global_load_lds_dwordx4 v[136:137], off
	v_lshl_add_u64 v[136:137], v[212:213], 0, s[2:3]
	s_mov_b32 m0, s39
	s_nop 0
	global_load_lds_dwordx4 v[136:137], off
	s_waitcnt vmcnt(8)
	s_waitcnt lgkmcnt(0)
	s_barrier
	s_setprio 1
	s_waitcnt lgkmcnt(0)
	v_mfma_f32_16x16x32_bf16 v[62:65], v[142:145], v[174:177], v[62:65]
	v_mfma_f32_16x16x32_bf16 v[62:65], v[146:149], v[178:181], v[62:65]
	v_mfma_f32_16x16x32_bf16 v[58:61], v[154:157], v[178:181], v[58:61]
	v_mfma_f32_16x16x32_bf16 v[58:61], v[150:153], v[174:177], v[58:61]
	v_mfma_f32_16x16x32_bf16 v[42:45], v[150:153], v[182:185], v[42:45]
	v_mfma_f32_16x16x32_bf16 v[42:45], v[154:157], v[186:189], v[42:45]
	v_mfma_f32_16x16x32_bf16 v[50:53], v[146:149], v[186:189], v[50:53]
	v_mfma_f32_16x16x32_bf16 v[50:53], v[142:145], v[182:185], v[50:53]
	v_mfma_f32_16x16x32_bf16 v[34:37], v[142:145], v[190:193], v[34:37]
	v_mfma_f32_16x16x32_bf16 v[34:37], v[146:149], v[198:201], v[34:37]
	v_mfma_f32_16x16x32_bf16 v[26:29], v[154:157], v[198:201], v[26:29]
	v_mfma_f32_16x16x32_bf16 v[26:29], v[150:153], v[190:193], v[26:29]
	v_mfma_f32_16x16x32_bf16 v[10:13], v[150:153], v[202:205], v[10:13]
	v_mfma_f32_16x16x32_bf16 v[10:13], v[154:157], v[206:209], v[10:13]
	v_mfma_f32_16x16x32_bf16 v[18:21], v[146:149], v[206:209], v[18:21]
	v_mfma_f32_16x16x32_bf16 v[18:21], v[142:145], v[202:205], v[18:21]
	s_setprio 0
	s_setprio 1
	v_mfma_f32_16x16x32_bf16 v[54:57], v[158:161], v[174:177], v[54:57]
	v_mfma_f32_16x16x32_bf16 v[54:57], v[162:165], v[178:181], v[54:57]
	v_mfma_f32_16x16x32_bf16 v[46:49], v[170:173], v[178:181], v[46:49]
	v_mfma_f32_16x16x32_bf16 v[46:49], v[166:169], v[174:177], v[46:49]
	v_mfma_f32_16x16x32_bf16 v[30:33], v[166:169], v[182:185], v[30:33]
	v_mfma_f32_16x16x32_bf16 v[30:33], v[170:173], v[186:189], v[30:33]
	v_mfma_f32_16x16x32_bf16 v[38:41], v[162:165], v[186:189], v[38:41]
	v_mfma_f32_16x16x32_bf16 v[38:41], v[158:161], v[182:185], v[38:41]
	v_mfma_f32_16x16x32_bf16 v[22:25], v[158:161], v[190:193], v[22:25]
	v_mfma_f32_16x16x32_bf16 v[22:25], v[162:165], v[198:201], v[22:25]
	v_mfma_f32_16x16x32_bf16 v[14:17], v[170:173], v[198:201], v[14:17]
	v_mfma_f32_16x16x32_bf16 v[14:17], v[166:169], v[190:193], v[14:17]
	v_mfma_f32_16x16x32_bf16 v[2:5], v[166:169], v[202:205], v[2:5]
	v_mfma_f32_16x16x32_bf16 v[2:5], v[170:173], v[206:209], v[2:5]
	v_mfma_f32_16x16x32_bf16 v[6:9], v[162:165], v[206:209], v[6:9]
	v_mfma_f32_16x16x32_bf16 v[6:9], v[158:161], v[202:205], v[6:9]
	s_setprio 0
	s_barrier
	s_cmp_gt_u32 s52, 29
	s_mov_b64 s[20:21], s[22:23]
	s_mov_b32 s24, s52
	s_cbranch_scc0 .LBB0_398
	s_and_b64 vcc, exec, s[6:7]
	s_cbranch_vccz .LBB0_401
	s_barrier

.LBB0_414:
	s_add_i32 s42, s24, 2
	s_lshr_b32 s44, s42, 2
	s_lshl_b64 s[22:23], s[44:45], 9
	s_add_u32 s22, s0, s22
	s_addc_u32 s23, s1, s23
	s_and_b32 s25, s20, 0x100
	s_add_u32 s43, s22, s25
	s_addc_u32 s47, s23, 0
	s_add_i32 s22, s24, 4
	s_lshr_b32 s44, s22, 2
	s_lshl_b64 s[22:23], s[44:45], 9
	s_add_u32 s25, s0, s22
	s_addc_u32 s44, s1, s23
	s_add_u32 s22, s20, 0x100
	s_addc_u32 s23, s21, 0
	s_and_b32 s49, s22, 0x100
	s_add_u32 s49, s25, s49
	s_addc_u32 s25, s44, 0
	s_add_u32 s20, s11, s20
	s_addc_u32 s21, s13, s21
	s_add_i32 s44, 0, 0x10000
	s_cmp_eq_u32 s24, 4
	s_cselect_b32 s25, s1, s25
	s_cselect_b32 s24, s0, s49
	v_add_u32_e32 v136, s44, v139
	s_cselect_b32 s21, s19, s21
	s_cselect_b32 s20, s18, s20
	s_add_i32 s49, 0, 0x14000
	ds_read_b128 v[142:145], v136
	ds_read_b128 v[146:149], v136 offset:1024
	ds_read_b128 v[150:153], v136 offset:2048
	ds_read_b128 v[154:157], v136 offset:3072
	v_add_u32_e32 v136, s49, v139
	ds_read_b128 v[158:161], v136
	ds_read_b128 v[162:165], v136 offset:1024
	ds_read_b128 v[166:169], v136 offset:2048
	ds_read_b128 v[170:173], v136 offset:3072
	s_add_u32 s50, s43, 0x20080
	s_addc_u32 s51, s47, 0
	v_lshl_add_u64 v[136:137], s[50:51], 0, v[134:135]
	s_add_i32 m0, s31, 0xc000
	ds_read_b128 v[174:177], v141
	ds_read_b128 v[178:181], v141 offset:1024
	ds_read_b128 v[182:185], v141 offset:2048
	ds_read_b128 v[186:189], v141 offset:3072
	ds_read_b128 v[190:193], v141 offset:4096
	ds_read_b128 v[198:201], v141 offset:5120
	ds_read_b128 v[202:205], v141 offset:6144
	ds_read_b128 v[206:209], v141 offset:7168
	global_load_lds_dwordx4 v[136:137], off
	v_lshl_add_u64 v[136:137], s[50:51], 0, v[132:133]
	s_add_i32 m0, s31, 0xe000
	s_nop 0
	global_load_lds_dwordx4 v[136:137], off
	s_waitcnt vmcnt(8)
	s_waitcnt lgkmcnt(0)
	s_barrier
	s_setprio 1
	v_mfma_f32_16x16x32_bf16 v[126:129], v[142:145], v[174:177], v[126:129]
	v_mfma_f32_16x16x32_bf16 v[126:129], v[146:149], v[178:181], v[126:129]
	v_mfma_f32_16x16x32_bf16 v[122:125], v[154:157], v[178:181], v[122:125]
	v_mfma_f32_16x16x32_bf16 v[122:125], v[150:153], v[174:177], v[122:125]
	v_mfma_f32_16x16x32_bf16 v[106:109], v[150:153], v[182:185], v[106:109]
	v_mfma_f32_16x16x32_bf16 v[106:109], v[154:157], v[186:189], v[106:109]
	v_mfma_f32_16x16x32_bf16 v[114:117], v[146:149], v[186:189], v[114:117]
	v_mfma_f32_16x16x32_bf16 v[114:117], v[142:145], v[182:185], v[114:117]
	v_mfma_f32_16x16x32_bf16 v[98:101], v[142:145], v[190:193], v[98:101]
	v_mfma_f32_16x16x32_bf16 v[98:101], v[146:149], v[198:201], v[98:101]
	v_mfma_f32_16x16x32_bf16 v[90:93], v[154:157], v[198:201], v[90:93]
	v_mfma_f32_16x16x32_bf16 v[90:93], v[150:153], v[190:193], v[90:93]
	v_mfma_f32_16x16x32_bf16 v[74:77], v[150:153], v[202:205], v[74:77]
	v_mfma_f32_16x16x32_bf16 v[74:77], v[154:157], v[206:209], v[74:77]
	v_mfma_f32_16x16x32_bf16 v[82:85], v[146:149], v[206:209], v[82:85]
	v_mfma_f32_16x16x32_bf16 v[82:85], v[142:145], v[202:205], v[82:85]
	s_setprio 0
	s_setprio 1
	v_mfma_f32_16x16x32_bf16 v[118:121], v[158:161], v[174:177], v[118:121]
	v_mfma_f32_16x16x32_bf16 v[118:121], v[162:165], v[178:181], v[118:121]
	v_mfma_f32_16x16x32_bf16 v[110:113], v[170:173], v[178:181], v[110:113]
	v_mfma_f32_16x16x32_bf16 v[110:113], v[166:169], v[174:177], v[110:113]
	v_mfma_f32_16x16x32_bf16 v[94:97], v[166:169], v[182:185], v[94:97]
	v_mfma_f32_16x16x32_bf16 v[94:97], v[170:173], v[186:189], v[94:97]
	v_mfma_f32_16x16x32_bf16 v[102:105], v[162:165], v[186:189], v[102:105]
	v_mfma_f32_16x16x32_bf16 v[102:105], v[158:161], v[182:185], v[102:105]
	v_mfma_f32_16x16x32_bf16 v[86:89], v[158:161], v[190:193], v[86:89]
	v_mfma_f32_16x16x32_bf16 v[86:89], v[162:165], v[198:201], v[86:89]
	v_mfma_f32_16x16x32_bf16 v[78:81], v[170:173], v[198:201], v[78:81]
	v_mfma_f32_16x16x32_bf16 v[78:81], v[166:169], v[190:193], v[78:81]
	v_mfma_f32_16x16x32_bf16 v[66:69], v[166:169], v[202:205], v[66:69]
	v_mfma_f32_16x16x32_bf16 v[66:69], v[170:173], v[206:209], v[66:69]
	v_mfma_f32_16x16x32_bf16 v[70:73], v[162:165], v[206:209], v[70:73]
	v_mfma_f32_16x16x32_bf16 v[70:73], v[158:161], v[202:205], v[70:73]
	s_setprio 0
	s_barrier
	s_add_i32 s43, s44, s30
	v_lshl_add_u64 v[136:137], s[20:21], 0, v[196:197]
	s_mov_b32 m0, s43
	ds_read_b128 v[174:177], v141 offset:16384
	ds_read_b128 v[178:181], v141 offset:17408
	ds_read_b128 v[182:185], v141 offset:18432
	ds_read_b128 v[186:189], v141 offset:19456
	ds_read_b128 v[190:193], v141 offset:20480
	ds_read_b128 v[198:201], v141 offset:21504
	ds_read_b128 v[202:205], v141 offset:22528
	ds_read_b128 v[206:209], v141 offset:23552
	global_load_lds_dwordx4 v[136:137], off
	s_add_i32 m0, s43, 0x2000
	s_add_u32 s50, s20, 0x20000
	v_lshl_add_u64 v[194:195], s[20:21], 0, v[130:131]
	s_addc_u32 s51, s21, 0
	s_add_i32 s43, s49, s30
	global_load_lds_dwordx4 v[194:195], off
	v_lshl_add_u64 v[210:211], s[50:51], 0, v[196:197]
	s_mov_b32 m0, s43
	v_lshl_add_u64 v[212:213], s[24:25], 0, v[132:133]
	global_load_lds_dwordx4 v[210:211], off
	v_lshl_add_u64 v[210:211], s[50:51], 0, v[130:131]
	s_add_i32 m0, s43, 0x2000
	s_nop 0
	global_load_lds_dwordx4 v[210:211], off
	v_lshl_add_u64 v[210:211], s[24:25], 0, v[134:135]
	s_mov_b32 m0, s31
	s_nop 0
	global_load_lds_dwordx4 v[210:211], off
	s_mov_b32 m0, s33
	s_nop 0
	global_load_lds_dwordx4 v[212:213], off
	s_waitcnt vmcnt(8)
	s_waitcnt lgkmcnt(0)
	s_barrier
	s_setprio 1
	v_mfma_f32_16x16x32_bf16 v[62:65], v[142:145], v[174:177], v[62:65]
	v_mfma_f32_16x16x32_bf16 v[62:65], v[146:149], v[178:181], v[62:65]
	v_mfma_f32_16x16x32_bf16 v[58:61], v[154:157], v[178:181], v[58:61]
	v_mfma_f32_16x16x32_bf16 v[58:61], v[150:153], v[174:177], v[58:61]
	v_mfma_f32_16x16x32_bf16 v[42:45], v[150:153], v[182:185], v[42:45]
	v_mfma_f32_16x16x32_bf16 v[42:45], v[154:157], v[186:189], v[42:45]
	v_mfma_f32_16x16x32_bf16 v[50:53], v[146:149], v[186:189], v[50:53]
	v_mfma_f32_16x16x32_bf16 v[50:53], v[142:145], v[182:185], v[50:53]
	v_mfma_f32_16x16x32_bf16 v[34:37], v[142:145], v[190:193], v[34:37]
	v_mfma_f32_16x16x32_bf16 v[34:37], v[146:149], v[198:201], v[34:37]
	v_mfma_f32_16x16x32_bf16 v[26:29], v[154:157], v[198:201], v[26:29]
	v_mfma_f32_16x16x32_bf16 v[26:29], v[150:153], v[190:193], v[26:29]
	v_mfma_f32_16x16x32_bf16 v[10:13], v[150:153], v[202:205], v[10:13]
	v_mfma_f32_16x16x32_bf16 v[10:13], v[154:157], v[206:209], v[10:13]
	v_mfma_f32_16x16x32_bf16 v[18:21], v[146:149], v[206:209], v[18:21]
	v_mfma_f32_16x16x32_bf16 v[18:21], v[142:145], v[202:205], v[18:21]
	s_setprio 0
	s_setprio 1
	v_mfma_f32_16x16x32_bf16 v[54:57], v[158:161], v[174:177], v[54:57]
	v_mfma_f32_16x16x32_bf16 v[54:57], v[162:165], v[178:181], v[54:57]
	v_mfma_f32_16x16x32_bf16 v[46:49], v[170:173], v[178:181], v[46:49]
	v_mfma_f32_16x16x32_bf16 v[46:49], v[166:169], v[174:177], v[46:49]
	v_mfma_f32_16x16x32_bf16 v[30:33], v[166:169], v[182:185], v[30:33]
	v_mfma_f32_16x16x32_bf16 v[30:33], v[170:173], v[186:189], v[30:33]
	v_mfma_f32_16x16x32_bf16 v[38:41], v[162:165], v[186:189], v[38:41]
	v_mfma_f32_16x16x32_bf16 v[38:41], v[158:161], v[182:185], v[38:41]
	v_mfma_f32_16x16x32_bf16 v[22:25], v[158:161], v[190:193], v[22:25]
	v_mfma_f32_16x16x32_bf16 v[22:25], v[162:165], v[198:201], v[22:25]
	v_mfma_f32_16x16x32_bf16 v[14:17], v[170:173], v[198:201], v[14:17]
	v_mfma_f32_16x16x32_bf16 v[14:17], v[166:169], v[190:193], v[14:17]
	v_mfma_f32_16x16x32_bf16 v[2:5], v[166:169], v[202:205], v[2:5]
	v_mfma_f32_16x16x32_bf16 v[2:5], v[170:173], v[206:209], v[2:5]
	v_mfma_f32_16x16x32_bf16 v[6:9], v[162:165], v[206:209], v[6:9]
	v_mfma_f32_16x16x32_bf16 v[6:9], v[158:161], v[202:205], v[6:9]
	s_setprio 0
	s_barrier
	s_add_i32 s43, 0, 0x18000
	s_add_i32 s44, 0, 0x1c000
	v_add_u32_e32 v154, s43, v139
	v_add_u32_e32 v170, s44, v139
	ds_read_b128 v[142:145], v154
	ds_read_b128 v[146:149], v154 offset:1024
	ds_read_b128 v[150:153], v154 offset:2048
	ds_read_b128 v[154:157], v154 offset:3072
	ds_read_b128 v[158:161], v170
	ds_read_b128 v[162:165], v170 offset:1024
	ds_read_b128 v[166:169], v170 offset:2048
	ds_read_b128 v[170:173], v170 offset:3072
	s_add_u32 s24, s24, 0x20000
	s_addc_u32 s25, s25, 0
	s_mov_b32 m0, s34
	v_lshl_add_u64 v[214:215], s[24:25], 0, v[134:135]
	ds_read_b128 v[174:177], v141 offset:32768
	ds_read_b128 v[178:181], v141 offset:33792
	ds_read_b128 v[182:185], v141 offset:34816
	ds_read_b128 v[186:189], v141 offset:35840
	ds_read_b128 v[190:193], v141 offset:36864
	ds_read_b128 v[198:201], v141 offset:37888
	ds_read_b128 v[202:205], v141 offset:38912
	ds_read_b128 v[206:209], v141 offset:39936
	global_load_lds_dwordx4 v[214:215], off
	v_lshl_add_u64 v[214:215], s[24:25], 0, v[132:133]
	s_mov_b32 m0, s35
	s_nop 0
	global_load_lds_dwordx4 v[214:215], off
	s_waitcnt vmcnt(8)
	s_waitcnt lgkmcnt(0)
	s_barrier
	s_setprio 1
	v_mfma_f32_16x16x32_bf16 v[126:129], v[142:145], v[174:177], v[126:129]
	v_mfma_f32_16x16x32_bf16 v[126:129], v[146:149], v[178:181], v[126:129]
	v_mfma_f32_16x16x32_bf16 v[122:125], v[154:157], v[178:181], v[122:125]
	v_mfma_f32_16x16x32_bf16 v[122:125], v[150:153], v[174:177], v[122:125]
	v_mfma_f32_16x16x32_bf16 v[106:109], v[150:153], v[182:185], v[106:109]
	v_mfma_f32_16x16x32_bf16 v[106:109], v[154:157], v[186:189], v[106:109]
	v_mfma_f32_16x16x32_bf16 v[114:117], v[146:149], v[186:189], v[114:117]
	v_mfma_f32_16x16x32_bf16 v[114:117], v[142:145], v[182:185], v[114:117]
	v_mfma_f32_16x16x32_bf16 v[98:101], v[142:145], v[190:193], v[98:101]
	v_mfma_f32_16x16x32_bf16 v[98:101], v[146:149], v[198:201], v[98:101]
	v_mfma_f32_16x16x32_bf16 v[90:93], v[154:157], v[198:201], v[90:93]
	v_mfma_f32_16x16x32_bf16 v[90:93], v[150:153], v[190:193], v[90:93]
	v_mfma_f32_16x16x32_bf16 v[74:77], v[150:153], v[202:205], v[74:77]
	v_mfma_f32_16x16x32_bf16 v[74:77], v[154:157], v[206:209], v[74:77]
	v_mfma_f32_16x16x32_bf16 v[82:85], v[146:149], v[206:209], v[82:85]
	v_mfma_f32_16x16x32_bf16 v[82:85], v[142:145], v[202:205], v[82:85]
	s_setprio 0
	s_setprio 1
	v_mfma_f32_16x16x32_bf16 v[118:121], v[158:161], v[174:177], v[118:121]
	v_mfma_f32_16x16x32_bf16 v[118:121], v[162:165], v[178:181], v[118:121]
	v_mfma_f32_16x16x32_bf16 v[110:113], v[170:173], v[178:181], v[110:113]
	v_mfma_f32_16x16x32_bf16 v[110:113], v[166:169], v[174:177], v[110:113]
	v_mfma_f32_16x16x32_bf16 v[94:97], v[166:169], v[182:185], v[94:97]
	v_mfma_f32_16x16x32_bf16 v[94:97], v[170:173], v[186:189], v[94:97]
	v_mfma_f32_16x16x32_bf16 v[102:105], v[162:165], v[186:189], v[102:105]
	v_mfma_f32_16x16x32_bf16 v[102:105], v[158:161], v[182:185], v[102:105]
	v_mfma_f32_16x16x32_bf16 v[86:89], v[158:161], v[190:193], v[86:89]
	v_mfma_f32_16x16x32_bf16 v[86:89], v[162:165], v[198:201], v[86:89]
	v_mfma_f32_16x16x32_bf16 v[78:81], v[170:173], v[198:201], v[78:81]
	v_mfma_f32_16x16x32_bf16 v[78:81], v[166:169], v[190:193], v[78:81]
	v_mfma_f32_16x16x32_bf16 v[66:69], v[166:169], v[202:205], v[66:69]
	v_mfma_f32_16x16x32_bf16 v[66:69], v[170:173], v[206:209], v[66:69]
	v_mfma_f32_16x16x32_bf16 v[70:73], v[162:165], v[206:209], v[70:73]
	v_mfma_f32_16x16x32_bf16 v[70:73], v[158:161], v[202:205], v[70:73]
	s_setprio 0
	s_barrier
	s_add_i32 s24, s43, s30
	v_lshl_add_u64 v[136:137], v[136:137], 0, s[2:3]
	s_mov_b32 m0, s24
	ds_read_b128 v[174:177], v141 offset:49152
	ds_read_b128 v[178:181], v141 offset:50176
	ds_read_b128 v[182:185], v141 offset:51200
	ds_read_b128 v[186:189], v141 offset:52224
	ds_read_b128 v[190:193], v141 offset:53248
	ds_read_b128 v[198:201], v141 offset:54272
	ds_read_b128 v[202:205], v141 offset:55296
	ds_read_b128 v[206:209], v141 offset:56320
	global_load_lds_dwordx4 v[136:137], off
	s_add_i32 m0, s24, 0x2000
	s_add_u32 s20, s20, 0x20080
	v_lshl_add_u64 v[136:137], v[194:195], 0, s[2:3]
	s_addc_u32 s21, s21, 0
	s_add_i32 s24, s44, s30
	global_load_lds_dwordx4 v[136:137], off
	v_lshl_add_u64 v[136:137], s[20:21], 0, v[196:197]
	s_mov_b32 m0, s24
	s_nop 0
	global_load_lds_dwordx4 v[136:137], off
	v_lshl_add_u64 v[136:137], s[20:21], 0, v[130:131]
	s_add_i32 m0, s24, 0x2000
	s_nop 0
	global_load_lds_dwordx4 v[136:137], off
	v_lshl_add_u64 v[136:137], v[210:211], 0, s[2:3]
	s_mov_b32 m0, s36
	s_nop 0
	global_load_lds_dwordx4 v[136:137], off
	v_lshl_add_u64 v[136:137], v[212:213], 0, s[2:3]
	s_mov_b32 m0, s37
	s_nop 0
	global_load_lds_dwordx4 v[136:137], off
	s_waitcnt vmcnt(8)
	s_waitcnt lgkmcnt(0)
	s_barrier
	s_setprio 1
	s_waitcnt lgkmcnt(0)
	v_mfma_f32_16x16x32_bf16 v[62:65], v[142:145], v[174:177], v[62:65]
	v_mfma_f32_16x16x32_bf16 v[62:65], v[146:149], v[178:181], v[62:65]
	v_mfma_f32_16x16x32_bf16 v[58:61], v[154:157], v[178:181], v[58:61]
	v_mfma_f32_16x16x32_bf16 v[58:61], v[150:153], v[174:177], v[58:61]
	v_mfma_f32_16x16x32_bf16 v[42:45], v[150:153], v[182:185], v[42:45]
	v_mfma_f32_16x16x32_bf16 v[42:45], v[154:157], v[186:189], v[42:45]
	v_mfma_f32_16x16x32_bf16 v[50:53], v[146:149], v[186:189], v[50:53]
	v_mfma_f32_16x16x32_bf16 v[50:53], v[142:145], v[182:185], v[50:53]
	v_mfma_f32_16x16x32_bf16 v[34:37], v[142:145], v[190:193], v[34:37]
	v_mfma_f32_16x16x32_bf16 v[34:37], v[146:149], v[198:201], v[34:37]
	v_mfma_f32_16x16x32_bf16 v[26:29], v[154:157], v[198:201], v[26:29]
	v_mfma_f32_16x16x32_bf16 v[26:29], v[150:153], v[190:193], v[26:29]
	v_mfma_f32_16x16x32_bf16 v[10:13], v[150:153], v[202:205], v[10:13]
	v_mfma_f32_16x16x32_bf16 v[10:13], v[154:157], v[206:209], v[10:13]
	v_mfma_f32_16x16x32_bf16 v[18:21], v[146:149], v[206:209], v[18:21]
	v_mfma_f32_16x16x32_bf16 v[18:21], v[142:145], v[202:205], v[18:21]
	s_setprio 0
	s_setprio 1
	v_mfma_f32_16x16x32_bf16 v[54:57], v[158:161], v[174:177], v[54:57]
	v_mfma_f32_16x16x32_bf16 v[54:57], v[162:165], v[178:181], v[54:57]
	v_mfma_f32_16x16x32_bf16 v[46:49], v[170:173], v[178:181], v[46:49]
	v_mfma_f32_16x16x32_bf16 v[46:49], v[166:169], v[174:177], v[46:49]
	v_mfma_f32_16x16x32_bf16 v[30:33], v[166:169], v[182:185], v[30:33]
	v_mfma_f32_16x16x32_bf16 v[30:33], v[170:173], v[186:189], v[30:33]
	v_mfma_f32_16x16x32_bf16 v[38:41], v[162:165], v[186:189], v[38:41]
	v_mfma_f32_16x16x32_bf16 v[38:41], v[158:161], v[182:185], v[38:41]
	v_mfma_f32_16x16x32_bf16 v[22:25], v[158:161], v[190:193], v[22:25]
	v_mfma_f32_16x16x32_bf16 v[22:25], v[162:165], v[198:201], v[22:25]
	v_mfma_f32_16x16x32_bf16 v[14:17], v[170:173], v[198:201], v[14:17]
	v_mfma_f32_16x16x32_bf16 v[14:17], v[166:169], v[190:193], v[14:17]
	v_mfma_f32_16x16x32_bf16 v[2:5], v[166:169], v[202:205], v[2:5]
	v_mfma_f32_16x16x32_bf16 v[2:5], v[170:173], v[206:209], v[2:5]
	v_mfma_f32_16x16x32_bf16 v[6:9], v[162:165], v[206:209], v[6:9]
	v_mfma_f32_16x16x32_bf16 v[6:9], v[158:161], v[202:205], v[6:9]
	s_setprio 0
	s_barrier
	s_cmp_gt_u32 s42, 5
	s_mov_b64 s[20:21], s[22:23]
	s_mov_b32 s24, s42
	s_cbranch_scc0 .LBB0_414
	s_and_b64 vcc, exec, s[8:9]
	s_cbranch_vccz .LBB0_417
	s_barrier

.LBB0_630:
	s_cmp_lt_i32 s5, 1
	s_cbranch_scc1 .LBB0_670
	s_add_u32 s7, s30, 0x100
	s_addc_u32 s47, s31, 0
	s_mov_b32 s49, 2
	s_mov_b64 s[30:31], 0
	s_add_i32 s34, s49, -2
	s_lshr_b32 s44, s34, 2
	s_lshl_b64 s[36:37], s[44:45], 9
	s_lshr_b32 s44, s49, 2
	s_and_b32 s64, s30, 0x100
	s_lshl_b64 s[34:35], s[44:45], 9
	s_add_u32 s44, s28, s34
	s_addc_u32 s65, s29, s35
	s_add_u32 s34, s30, 0x100
	s_addc_u32 s35, s31, 0
	s_and_b32 s66, s34, 0x100
	s_add_u32 s44, s44, s66
	s_addc_u32 s65, s65, 0
	s_add_u32 s30, s7, s30
	s_addc_u32 s31, s47, s31
	s_add_i32 s66, 0, 0x10000
	s_add_u32 s67, s28, s36
	s_addc_u32 s68, s29, s37
	s_cmp_eq_u32 s5, s49
	s_cselect_b32 s37, s25, s65
	s_cselect_b32 s36, s24, s44
	s_cselect_b32 s31, s27, s31
	s_cselect_b32 s30, s26, s30
	s_add_i32 s44, 0, 0x14000
	v_add_u32_e32 v142, s66, v227
	v_add_u32_e32 v158, s44, v227
	ds_read_b128 v[130:133], v142
	ds_read_b128 v[134:137], v142 offset:1024
	ds_read_b128 v[138:141], v142 offset:2048
	ds_read_b128 v[142:145], v142 offset:3072
	ds_read_b128 v[146:149], v158
	ds_read_b128 v[150:153], v158 offset:1024
	ds_read_b128 v[154:157], v158 offset:2048
	ds_read_b128 v[158:161], v158 offset:3072
	s_add_u32 s64, s67, s64
	s_addc_u32 s65, s68, 0
	s_add_u32 s64, s64, 0x80080
	s_addc_u32 s65, s65, 0
	v_lshl_add_u64 v[194:195], s[64:65], 0, v[198:199]
	s_add_i32 m0, s40, 0xc000
	ds_read_b128 v[162:165], v229
	ds_read_b128 v[166:169], v229 offset:1024
	ds_read_b128 v[170:173], v229 offset:2048
	ds_read_b128 v[174:177], v229 offset:3072
	ds_read_b128 v[178:181], v229 offset:4096
	ds_read_b128 v[182:185], v229 offset:5120
	ds_read_b128 v[186:189], v229 offset:6144
	ds_read_b128 v[190:193], v229 offset:7168
	global_load_lds_dwordx4 v[194:195], off
	v_lshl_add_u64 v[194:195], s[64:65], 0, v[202:203]
	s_add_i32 m0, s40, 0xe000
	s_nop 0
	global_load_lds_dwordx4 v[194:195], off
	s_waitcnt vmcnt(8)
	s_waitcnt lgkmcnt(0)
	s_barrier
	s_setprio 1
	v_mfma_f32_16x16x32_bf16 v[126:129], v[130:133], v[162:165], 0
	v_mfma_f32_16x16x32_bf16 v[126:129], v[134:137], v[166:169], v[126:129]
	v_mfma_f32_16x16x32_bf16 v[122:125], v[142:145], v[166:169], 0
	v_mfma_f32_16x16x32_bf16 v[122:125], v[138:141], v[162:165], v[122:125]
	v_mfma_f32_16x16x32_bf16 v[106:109], v[138:141], v[170:173], 0
	v_mfma_f32_16x16x32_bf16 v[106:109], v[142:145], v[174:177], v[106:109]
	v_mfma_f32_16x16x32_bf16 v[110:113], v[134:137], v[174:177], 0
	v_mfma_f32_16x16x32_bf16 v[110:113], v[130:133], v[170:173], v[110:113]
	v_mfma_f32_16x16x32_bf16 v[94:97], v[130:133], v[178:181], 0
	v_mfma_f32_16x16x32_bf16 v[94:97], v[134:137], v[182:185], v[94:97]
	v_mfma_f32_16x16x32_bf16 v[90:93], v[142:145], v[182:185], 0
	v_mfma_f32_16x16x32_bf16 v[90:93], v[138:141], v[178:181], v[90:93]
	v_mfma_f32_16x16x32_bf16 v[74:77], v[138:141], v[186:189], 0
	v_mfma_f32_16x16x32_bf16 v[74:77], v[142:145], v[190:193], v[74:77]
	v_mfma_f32_16x16x32_bf16 v[78:81], v[134:137], v[190:193], 0
	v_mfma_f32_16x16x32_bf16 v[78:81], v[130:133], v[186:189], v[78:81]
	s_setprio 0
	s_setprio 1
	v_mfma_f32_16x16x32_bf16 v[118:121], v[146:149], v[162:165], 0
	v_mfma_f32_16x16x32_bf16 v[118:121], v[150:153], v[166:169], v[118:121]
	v_mfma_f32_16x16x32_bf16 v[114:117], v[158:161], v[166:169], 0
	v_mfma_f32_16x16x32_bf16 v[114:117], v[154:157], v[162:165], v[114:117]
	v_mfma_f32_16x16x32_bf16 v[98:101], v[154:157], v[170:173], 0
	v_mfma_f32_16x16x32_bf16 v[98:101], v[158:161], v[174:177], v[98:101]
	v_mfma_f32_16x16x32_bf16 v[102:105], v[150:153], v[174:177], 0
	v_mfma_f32_16x16x32_bf16 v[102:105], v[146:149], v[170:173], v[102:105]
	v_mfma_f32_16x16x32_bf16 v[86:89], v[146:149], v[178:181], 0
	v_mfma_f32_16x16x32_bf16 v[86:89], v[150:153], v[182:185], v[86:89]
	v_mfma_f32_16x16x32_bf16 v[82:85], v[158:161], v[182:185], 0
	v_mfma_f32_16x16x32_bf16 v[82:85], v[154:157], v[178:181], v[82:85]
	v_mfma_f32_16x16x32_bf16 v[66:69], v[154:157], v[186:189], 0
	v_mfma_f32_16x16x32_bf16 v[66:69], v[158:161], v[190:193], v[66:69]
	v_mfma_f32_16x16x32_bf16 v[70:73], v[150:153], v[190:193], 0
	v_mfma_f32_16x16x32_bf16 v[70:73], v[146:149], v[186:189], v[70:73]
	s_setprio 0
	s_barrier
	s_add_i32 s64, s66, s39
	v_lshl_add_u64 v[194:195], s[30:31], 0, v[200:201]
	s_mov_b32 m0, s64
	ds_read_b128 v[162:165], v229 offset:16384
	ds_read_b128 v[166:169], v229 offset:17408
	ds_read_b128 v[170:173], v229 offset:18432
	ds_read_b128 v[174:177], v229 offset:19456
	ds_read_b128 v[178:181], v229 offset:20480
	ds_read_b128 v[182:185], v229 offset:21504
	ds_read_b128 v[186:189], v229 offset:22528
	ds_read_b128 v[190:193], v229 offset:23552
	global_load_lds_dwordx4 v[194:195], off
	s_add_i32 m0, s64, 0x2000
	s_add_u32 s64, s30, 0x80000
	v_lshl_add_u64 v[206:207], s[30:31], 0, v[204:205]
	s_addc_u32 s65, s31, 0
	s_add_i32 s44, s44, s39
	global_load_lds_dwordx4 v[206:207], off
	v_lshl_add_u64 v[208:209], s[64:65], 0, v[200:201]
	s_mov_b32 m0, s44
	v_lshl_add_u64 v[210:211], s[36:37], 0, v[202:203]
	global_load_lds_dwordx4 v[208:209], off
	v_lshl_add_u64 v[208:209], s[64:65], 0, v[204:205]
	s_add_i32 m0, s44, 0x2000
	s_nop 0
	global_load_lds_dwordx4 v[208:209], off
	v_lshl_add_u64 v[208:209], s[36:37], 0, v[198:199]
	s_mov_b32 m0, s40
	s_nop 0
	global_load_lds_dwordx4 v[208:209], off
	s_mov_b32 m0, s41
	s_nop 0
	global_load_lds_dwordx4 v[210:211], off
	s_waitcnt vmcnt(8)
	s_waitcnt lgkmcnt(0)
	s_barrier
	s_setprio 1
	v_mfma_f32_16x16x32_bf16 v[62:65], v[130:133], v[162:165], 0
	v_mfma_f32_16x16x32_bf16 v[62:65], v[134:137], v[166:169], v[62:65]
	v_mfma_f32_16x16x32_bf16 v[58:61], v[142:145], v[166:169], 0
	v_mfma_f32_16x16x32_bf16 v[58:61], v[138:141], v[162:165], v[58:61]
	v_mfma_f32_16x16x32_bf16 v[42:45], v[138:141], v[170:173], 0
	v_mfma_f32_16x16x32_bf16 v[42:45], v[142:145], v[174:177], v[42:45]
	v_mfma_f32_16x16x32_bf16 v[46:49], v[134:137], v[174:177], 0
	v_mfma_f32_16x16x32_bf16 v[46:49], v[130:133], v[170:173], v[46:49]
	v_mfma_f32_16x16x32_bf16 v[30:33], v[130:133], v[178:181], 0
	v_mfma_f32_16x16x32_bf16 v[30:33], v[134:137], v[182:185], v[30:33]
	v_mfma_f32_16x16x32_bf16 v[26:29], v[142:145], v[182:185], 0
	v_mfma_f32_16x16x32_bf16 v[26:29], v[138:141], v[178:181], v[26:29]
	v_mfma_f32_16x16x32_bf16 v[10:13], v[138:141], v[186:189], 0
	v_mfma_f32_16x16x32_bf16 v[10:13], v[142:145], v[190:193], v[10:13]
	v_mfma_f32_16x16x32_bf16 v[14:17], v[134:137], v[190:193], 0
	v_mfma_f32_16x16x32_bf16 v[14:17], v[130:133], v[186:189], v[14:17]
	s_setprio 0
	s_setprio 1
	v_mfma_f32_16x16x32_bf16 v[54:57], v[146:149], v[162:165], 0
	v_mfma_f32_16x16x32_bf16 v[54:57], v[150:153], v[166:169], v[54:57]
	v_mfma_f32_16x16x32_bf16 v[50:53], v[158:161], v[166:169], 0
	v_mfma_f32_16x16x32_bf16 v[50:53], v[154:157], v[162:165], v[50:53]
	v_mfma_f32_16x16x32_bf16 v[34:37], v[154:157], v[170:173], 0
	v_mfma_f32_16x16x32_bf16 v[34:37], v[158:161], v[174:177], v[34:37]
	v_mfma_f32_16x16x32_bf16 v[38:41], v[150:153], v[174:177], 0
	v_mfma_f32_16x16x32_bf16 v[38:41], v[146:149], v[170:173], v[38:41]
	v_mfma_f32_16x16x32_bf16 v[22:25], v[146:149], v[178:181], 0
	v_mfma_f32_16x16x32_bf16 v[22:25], v[150:153], v[182:185], v[22:25]
	v_mfma_f32_16x16x32_bf16 v[18:21], v[158:161], v[182:185], 0
	v_mfma_f32_16x16x32_bf16 v[18:21], v[154:157], v[178:181], v[18:21]
	v_mfma_f32_16x16x32_bf16 v[2:5], v[154:157], v[186:189], 0
	v_mfma_f32_16x16x32_bf16 v[2:5], v[158:161], v[190:193], v[2:5]
	v_mfma_f32_16x16x32_bf16 v[6:9], v[150:153], v[190:193], 0
	v_mfma_f32_16x16x32_bf16 v[6:9], v[146:149], v[186:189], v[6:9]
	s_setprio 0
	s_barrier
	s_add_i32 s44, 0, 0x18000
	s_add_i32 s64, 0, 0x1c000
	v_add_u32_e32 v142, s44, v227
	v_add_u32_e32 v158, s64, v227
	ds_read_b128 v[130:133], v142
	ds_read_b128 v[134:137], v142 offset:1024
	ds_read_b128 v[138:141], v142 offset:2048
	ds_read_b128 v[142:145], v142 offset:3072
	ds_read_b128 v[146:149], v158
	ds_read_b128 v[150:153], v158 offset:1024
	ds_read_b128 v[154:157], v158 offset:2048
	ds_read_b128 v[158:161], v158 offset:3072
	s_add_u32 s36, s36, 0x80000
	s_addc_u32 s37, s37, 0
	s_mov_b32 m0, s42
	v_lshl_add_u64 v[212:213], s[36:37], 0, v[198:199]
	ds_read_b128 v[162:165], v229 offset:32768
	ds_read_b128 v[166:169], v229 offset:33792
	ds_read_b128 v[170:173], v229 offset:34816
	ds_read_b128 v[174:177], v229 offset:35840
	ds_read_b128 v[178:181], v229 offset:36864
	ds_read_b128 v[182:185], v229 offset:37888
	ds_read_b128 v[186:189], v229 offset:38912
	ds_read_b128 v[190:193], v229 offset:39936
	global_load_lds_dwordx4 v[212:213], off
	v_lshl_add_u64 v[212:213], s[36:37], 0, v[202:203]
	s_mov_b32 m0, s43
	s_nop 0
	global_load_lds_dwordx4 v[212:213], off
	s_waitcnt vmcnt(8)
	s_waitcnt lgkmcnt(0)
	s_barrier
	s_setprio 1
	v_mfma_f32_16x16x32_bf16 v[126:129], v[130:133], v[162:165], v[126:129]
	v_mfma_f32_16x16x32_bf16 v[126:129], v[134:137], v[166:169], v[126:129]
	v_mfma_f32_16x16x32_bf16 v[122:125], v[142:145], v[166:169], v[122:125]
	v_mfma_f32_16x16x32_bf16 v[122:125], v[138:141], v[162:165], v[122:125]
	v_mfma_f32_16x16x32_bf16 v[106:109], v[138:141], v[170:173], v[106:109]
	v_mfma_f32_16x16x32_bf16 v[106:109], v[142:145], v[174:177], v[106:109]
	v_mfma_f32_16x16x32_bf16 v[110:113], v[134:137], v[174:177], v[110:113]
	v_mfma_f32_16x16x32_bf16 v[110:113], v[130:133], v[170:173], v[110:113]
	v_mfma_f32_16x16x32_bf16 v[94:97], v[130:133], v[178:181], v[94:97]
	v_mfma_f32_16x16x32_bf16 v[94:97], v[134:137], v[182:185], v[94:97]
	v_mfma_f32_16x16x32_bf16 v[90:93], v[142:145], v[182:185], v[90:93]
	v_mfma_f32_16x16x32_bf16 v[90:93], v[138:141], v[178:181], v[90:93]
	v_mfma_f32_16x16x32_bf16 v[74:77], v[138:141], v[186:189], v[74:77]
	v_mfma_f32_16x16x32_bf16 v[74:77], v[142:145], v[190:193], v[74:77]
	v_mfma_f32_16x16x32_bf16 v[78:81], v[134:137], v[190:193], v[78:81]
	v_mfma_f32_16x16x32_bf16 v[78:81], v[130:133], v[186:189], v[78:81]
	s_setprio 0
	s_setprio 1
	v_mfma_f32_16x16x32_bf16 v[118:121], v[146:149], v[162:165], v[118:121]
	v_mfma_f32_16x16x32_bf16 v[118:121], v[150:153], v[166:169], v[118:121]
	v_mfma_f32_16x16x32_bf16 v[114:117], v[158:161], v[166:169], v[114:117]
	v_mfma_f32_16x16x32_bf16 v[114:117], v[154:157], v[162:165], v[114:117]
	v_mfma_f32_16x16x32_bf16 v[98:101], v[154:157], v[170:173], v[98:101]
	v_mfma_f32_16x16x32_bf16 v[98:101], v[158:161], v[174:177], v[98:101]
	v_mfma_f32_16x16x32_bf16 v[102:105], v[150:153], v[174:177], v[102:105]
	v_mfma_f32_16x16x32_bf16 v[102:105], v[146:149], v[170:173], v[102:105]
	v_mfma_f32_16x16x32_bf16 v[86:89], v[146:149], v[178:181], v[86:89]
	v_mfma_f32_16x16x32_bf16 v[86:89], v[150:153], v[182:185], v[86:89]
	v_mfma_f32_16x16x32_bf16 v[82:85], v[158:161], v[182:185], v[82:85]
	v_mfma_f32_16x16x32_bf16 v[82:85], v[154:157], v[178:181], v[82:85]
	v_mfma_f32_16x16x32_bf16 v[66:69], v[154:157], v[186:189], v[66:69]
	v_mfma_f32_16x16x32_bf16 v[66:69], v[158:161], v[190:193], v[66:69]
	v_mfma_f32_16x16x32_bf16 v[70:73], v[150:153], v[190:193], v[70:73]
	v_mfma_f32_16x16x32_bf16 v[70:73], v[146:149], v[186:189], v[70:73]
	s_setprio 0
	s_barrier
	s_add_i32 s36, s44, s39
	v_lshl_add_u64 v[194:195], v[194:195], 0, s[2:3]
	s_mov_b32 m0, s36
	ds_read_b128 v[162:165], v229 offset:49152
	ds_read_b128 v[166:169], v229 offset:50176
	ds_read_b128 v[170:173], v229 offset:51200
	ds_read_b128 v[174:177], v229 offset:52224
	ds_read_b128 v[178:181], v229 offset:53248
	ds_read_b128 v[182:185], v229 offset:54272
	ds_read_b128 v[186:189], v229 offset:55296
	ds_read_b128 v[190:193], v229 offset:56320
	global_load_lds_dwordx4 v[194:195], off
	s_add_i32 m0, s36, 0x2000
	s_add_u32 s30, s30, 0x80080
	v_lshl_add_u64 v[194:195], v[206:207], 0, s[2:3]
	s_addc_u32 s31, s31, 0
	s_add_i32 s36, s64, s39
	global_load_lds_dwordx4 v[194:195], off
	v_lshl_add_u64 v[194:195], s[30:31], 0, v[200:201]
	s_mov_b32 m0, s36
	s_nop 0
	global_load_lds_dwordx4 v[194:195], off
	v_lshl_add_u64 v[194:195], s[30:31], 0, v[204:205]
	s_add_i32 m0, s36, 0x2000
	s_nop 0
	global_load_lds_dwordx4 v[194:195], off
	v_lshl_add_u64 v[194:195], v[208:209], 0, s[2:3]
	s_mov_b32 m0, s50
	s_nop 0
	global_load_lds_dwordx4 v[194:195], off
	v_lshl_add_u64 v[194:195], v[210:211], 0, s[2:3]
	s_mov_b32 m0, s51
	s_nop 0
	global_load_lds_dwordx4 v[194:195], off
	s_waitcnt vmcnt(8)
	s_waitcnt lgkmcnt(0)
	s_barrier
	s_setprio 1
	s_waitcnt lgkmcnt(0)
	v_mfma_f32_16x16x32_bf16 v[62:65], v[130:133], v[162:165], v[62:65]
	v_mfma_f32_16x16x32_bf16 v[62:65], v[134:137], v[166:169], v[62:65]
	v_mfma_f32_16x16x32_bf16 v[58:61], v[142:145], v[166:169], v[58:61]
	v_mfma_f32_16x16x32_bf16 v[58:61], v[138:141], v[162:165], v[58:61]
	v_mfma_f32_16x16x32_bf16 v[42:45], v[138:141], v[170:173], v[42:45]
	v_mfma_f32_16x16x32_bf16 v[42:45], v[142:145], v[174:177], v[42:45]
	v_mfma_f32_16x16x32_bf16 v[46:49], v[134:137], v[174:177], v[46:49]
	v_mfma_f32_16x16x32_bf16 v[46:49], v[130:133], v[170:173], v[46:49]
	v_mfma_f32_16x16x32_bf16 v[30:33], v[130:133], v[178:181], v[30:33]
	v_mfma_f32_16x16x32_bf16 v[30:33], v[134:137], v[182:185], v[30:33]
	v_mfma_f32_16x16x32_bf16 v[26:29], v[142:145], v[182:185], v[26:29]
	v_mfma_f32_16x16x32_bf16 v[26:29], v[138:141], v[178:181], v[26:29]
	v_mfma_f32_16x16x32_bf16 v[10:13], v[138:141], v[186:189], v[10:13]
	v_mfma_f32_16x16x32_bf16 v[10:13], v[142:145], v[190:193], v[10:13]
	v_mfma_f32_16x16x32_bf16 v[14:17], v[134:137], v[190:193], v[14:17]
	v_mfma_f32_16x16x32_bf16 v[14:17], v[130:133], v[186:189], v[14:17]
	s_setprio 0
	s_setprio 1
	v_mfma_f32_16x16x32_bf16 v[54:57], v[146:149], v[162:165], v[54:57]
	v_mfma_f32_16x16x32_bf16 v[54:57], v[150:153], v[166:169], v[54:57]
	v_mfma_f32_16x16x32_bf16 v[50:53], v[158:161], v[166:169], v[50:53]
	v_mfma_f32_16x16x32_bf16 v[50:53], v[154:157], v[162:165], v[50:53]
	v_mfma_f32_16x16x32_bf16 v[34:37], v[154:157], v[170:173], v[34:37]
	v_mfma_f32_16x16x32_bf16 v[34:37], v[158:161], v[174:177], v[34:37]
	v_mfma_f32_16x16x32_bf16 v[38:41], v[150:153], v[174:177], v[38:41]
	v_mfma_f32_16x16x32_bf16 v[38:41], v[146:149], v[170:173], v[38:41]
	v_mfma_f32_16x16x32_bf16 v[22:25], v[146:149], v[178:181], v[22:25]
	v_mfma_f32_16x16x32_bf16 v[22:25], v[150:153], v[182:185], v[22:25]
	v_mfma_f32_16x16x32_bf16 v[18:21], v[158:161], v[182:185], v[18:21]
	v_mfma_f32_16x16x32_bf16 v[18:21], v[154:157], v[178:181], v[18:21]
	v_mfma_f32_16x16x32_bf16 v[2:5], v[154:157], v[186:189], v[2:5]
	v_mfma_f32_16x16x32_bf16 v[2:5], v[158:161], v[190:193], v[2:5]
	v_mfma_f32_16x16x32_bf16 v[6:9], v[150:153], v[190:193], v[6:9]
	v_mfma_f32_16x16x32_bf16 v[6:9], v[146:149], v[186:189], v[6:9]
	s_setprio 0
	s_barrier
	s_add_i32 s36, s49, 2
	s_cmp_ge_i32 s49, s5
	s_mov_b64 s[30:31], s[34:35]
	s_mov_b32 s49, s36
	s_cbranch_scc1 .Lpeel_exit_branch
.LBB0_632:
	s_add_i32 s34, s49, -2
	s_lshr_b32 s44, s34, 2
	s_lshl_b64 s[36:37], s[44:45], 9
	s_lshr_b32 s44, s49, 2
	s_and_b32 s64, s30, 0x100
	s_lshl_b64 s[34:35], s[44:45], 9
	s_add_u32 s44, s28, s34
	s_addc_u32 s65, s29, s35
	s_add_u32 s34, s30, 0x100
	s_addc_u32 s35, s31, 0
	s_and_b32 s66, s34, 0x100
	s_add_u32 s44, s44, s66
	s_addc_u32 s65, s65, 0
	s_add_u32 s30, s7, s30
	s_addc_u32 s31, s47, s31
	s_add_i32 s66, 0, 0x10000
	s_add_u32 s67, s28, s36
	s_addc_u32 s68, s29, s37
	s_cmp_eq_u32 s5, s49
	s_cselect_b32 s37, s25, s65
	s_cselect_b32 s36, s24, s44
	s_cselect_b32 s31, s27, s31
	s_cselect_b32 s30, s26, s30
	s_add_i32 s44, 0, 0x14000
	v_add_u32_e32 v142, s66, v227
	v_add_u32_e32 v158, s44, v227
	ds_read_b128 v[130:133], v142
	ds_read_b128 v[134:137], v142 offset:1024
	ds_read_b128 v[138:141], v142 offset:2048
	ds_read_b128 v[142:145], v142 offset:3072
	ds_read_b128 v[146:149], v158
	ds_read_b128 v[150:153], v158 offset:1024
	ds_read_b128 v[154:157], v158 offset:2048
	ds_read_b128 v[158:161], v158 offset:3072
	s_add_u32 s64, s67, s64
	s_addc_u32 s65, s68, 0
	s_add_u32 s64, s64, 0x80080
	s_addc_u32 s65, s65, 0
	v_lshl_add_u64 v[194:195], s[64:65], 0, v[198:199]
	s_add_i32 m0, s40, 0xc000
	ds_read_b128 v[162:165], v229
	ds_read_b128 v[166:169], v229 offset:1024
	ds_read_b128 v[170:173], v229 offset:2048
	ds_read_b128 v[174:177], v229 offset:3072
	ds_read_b128 v[178:181], v229 offset:4096
	ds_read_b128 v[182:185], v229 offset:5120
	ds_read_b128 v[186:189], v229 offset:6144
	ds_read_b128 v[190:193], v229 offset:7168
	global_load_lds_dwordx4 v[194:195], off
	v_lshl_add_u64 v[194:195], s[64:65], 0, v[202:203]
	s_add_i32 m0, s40, 0xe000
	s_nop 0
	global_load_lds_dwordx4 v[194:195], off
	s_waitcnt vmcnt(8)
	s_waitcnt lgkmcnt(0)
	s_barrier
	s_setprio 1
	v_mfma_f32_16x16x32_bf16 v[126:129], v[130:133], v[162:165], v[126:129]
	v_mfma_f32_16x16x32_bf16 v[126:129], v[134:137], v[166:169], v[126:129]
	v_mfma_f32_16x16x32_bf16 v[122:125], v[142:145], v[166:169], v[122:125]
	v_mfma_f32_16x16x32_bf16 v[122:125], v[138:141], v[162:165], v[122:125]
	v_mfma_f32_16x16x32_bf16 v[106:109], v[138:141], v[170:173], v[106:109]
	v_mfma_f32_16x16x32_bf16 v[106:109], v[142:145], v[174:177], v[106:109]
	v_mfma_f32_16x16x32_bf16 v[110:113], v[134:137], v[174:177], v[110:113]
	v_mfma_f32_16x16x32_bf16 v[110:113], v[130:133], v[170:173], v[110:113]
	v_mfma_f32_16x16x32_bf16 v[94:97], v[130:133], v[178:181], v[94:97]
	v_mfma_f32_16x16x32_bf16 v[94:97], v[134:137], v[182:185], v[94:97]
	v_mfma_f32_16x16x32_bf16 v[90:93], v[142:145], v[182:185], v[90:93]
	v_mfma_f32_16x16x32_bf16 v[90:93], v[138:141], v[178:181], v[90:93]
	v_mfma_f32_16x16x32_bf16 v[74:77], v[138:141], v[186:189], v[74:77]
	v_mfma_f32_16x16x32_bf16 v[74:77], v[142:145], v[190:193], v[74:77]
	v_mfma_f32_16x16x32_bf16 v[78:81], v[134:137], v[190:193], v[78:81]
	v_mfma_f32_16x16x32_bf16 v[78:81], v[130:133], v[186:189], v[78:81]
	s_setprio 0
	s_setprio 1
	v_mfma_f32_16x16x32_bf16 v[118:121], v[146:149], v[162:165], v[118:121]
	v_mfma_f32_16x16x32_bf16 v[118:121], v[150:153], v[166:169], v[118:121]
	v_mfma_f32_16x16x32_bf16 v[114:117], v[158:161], v[166:169], v[114:117]
	v_mfma_f32_16x16x32_bf16 v[114:117], v[154:157], v[162:165], v[114:117]
	v_mfma_f32_16x16x32_bf16 v[98:101], v[154:157], v[170:173], v[98:101]
	v_mfma_f32_16x16x32_bf16 v[98:101], v[158:161], v[174:177], v[98:101]
	v_mfma_f32_16x16x32_bf16 v[102:105], v[150:153], v[174:177], v[102:105]
	v_mfma_f32_16x16x32_bf16 v[102:105], v[146:149], v[170:173], v[102:105]
	v_mfma_f32_16x16x32_bf16 v[86:89], v[146:149], v[178:181], v[86:89]
	v_mfma_f32_16x16x32_bf16 v[86:89], v[150:153], v[182:185], v[86:89]
	v_mfma_f32_16x16x32_bf16 v[82:85], v[158:161], v[182:185], v[82:85]
	v_mfma_f32_16x16x32_bf16 v[82:85], v[154:157], v[178:181], v[82:85]
	v_mfma_f32_16x16x32_bf16 v[66:69], v[154:157], v[186:189], v[66:69]
	v_mfma_f32_16x16x32_bf16 v[66:69], v[158:161], v[190:193], v[66:69]
	v_mfma_f32_16x16x32_bf16 v[70:73], v[150:153], v[190:193], v[70:73]
	v_mfma_f32_16x16x32_bf16 v[70:73], v[146:149], v[186:189], v[70:73]
	s_setprio 0
	s_barrier
	s_add_i32 s64, s66, s39
	v_lshl_add_u64 v[194:195], s[30:31], 0, v[200:201]
	s_mov_b32 m0, s64
	ds_read_b128 v[162:165], v229 offset:16384
	ds_read_b128 v[166:169], v229 offset:17408
	ds_read_b128 v[170:173], v229 offset:18432
	ds_read_b128 v[174:177], v229 offset:19456
	ds_read_b128 v[178:181], v229 offset:20480
	ds_read_b128 v[182:185], v229 offset:21504
	ds_read_b128 v[186:189], v229 offset:22528
	ds_read_b128 v[190:193], v229 offset:23552
	global_load_lds_dwordx4 v[194:195], off
	s_add_i32 m0, s64, 0x2000
	s_add_u32 s64, s30, 0x80000
	v_lshl_add_u64 v[206:207], s[30:31], 0, v[204:205]
	s_addc_u32 s65, s31, 0
	s_add_i32 s44, s44, s39
	global_load_lds_dwordx4 v[206:207], off
	v_lshl_add_u64 v[208:209], s[64:65], 0, v[200:201]
	s_mov_b32 m0, s44
	v_lshl_add_u64 v[210:211], s[36:37], 0, v[202:203]
	global_load_lds_dwordx4 v[208:209], off
	v_lshl_add_u64 v[208:209], s[64:65], 0, v[204:205]
	s_add_i32 m0, s44, 0x2000
	s_nop 0
	global_load_lds_dwordx4 v[208:209], off
	v_lshl_add_u64 v[208:209], s[36:37], 0, v[198:199]
	s_mov_b32 m0, s40
	s_nop 0
	global_load_lds_dwordx4 v[208:209], off
	s_mov_b32 m0, s41
	s_nop 0
	global_load_lds_dwordx4 v[210:211], off
	s_waitcnt vmcnt(8)
	s_waitcnt lgkmcnt(0)
	s_barrier
	s_setprio 1
	v_mfma_f32_16x16x32_bf16 v[62:65], v[130:133], v[162:165], v[62:65]
	v_mfma_f32_16x16x32_bf16 v[62:65], v[134:137], v[166:169], v[62:65]
	v_mfma_f32_16x16x32_bf16 v[58:61], v[142:145], v[166:169], v[58:61]
	v_mfma_f32_16x16x32_bf16 v[58:61], v[138:141], v[162:165], v[58:61]
	v_mfma_f32_16x16x32_bf16 v[42:45], v[138:141], v[170:173], v[42:45]
	v_mfma_f32_16x16x32_bf16 v[42:45], v[142:145], v[174:177], v[42:45]
	v_mfma_f32_16x16x32_bf16 v[46:49], v[134:137], v[174:177], v[46:49]
	v_mfma_f32_16x16x32_bf16 v[46:49], v[130:133], v[170:173], v[46:49]
	v_mfma_f32_16x16x32_bf16 v[30:33], v[130:133], v[178:181], v[30:33]
	v_mfma_f32_16x16x32_bf16 v[30:33], v[134:137], v[182:185], v[30:33]
	v_mfma_f32_16x16x32_bf16 v[26:29], v[142:145], v[182:185], v[26:29]
	v_mfma_f32_16x16x32_bf16 v[26:29], v[138:141], v[178:181], v[26:29]
	v_mfma_f32_16x16x32_bf16 v[10:13], v[138:141], v[186:189], v[10:13]
	v_mfma_f32_16x16x32_bf16 v[10:13], v[142:145], v[190:193], v[10:13]
	v_mfma_f32_16x16x32_bf16 v[14:17], v[134:137], v[190:193], v[14:17]
	v_mfma_f32_16x16x32_bf16 v[14:17], v[130:133], v[186:189], v[14:17]
	s_setprio 0
	s_setprio 1
	v_mfma_f32_16x16x32_bf16 v[54:57], v[146:149], v[162:165], v[54:57]
	v_mfma_f32_16x16x32_bf16 v[54:57], v[150:153], v[166:169], v[54:57]
	v_mfma_f32_16x16x32_bf16 v[50:53], v[158:161], v[166:169], v[50:53]
	v_mfma_f32_16x16x32_bf16 v[50:53], v[154:157], v[162:165], v[50:53]
	v_mfma_f32_16x16x32_bf16 v[34:37], v[154:157], v[170:173], v[34:37]
	v_mfma_f32_16x16x32_bf16 v[34:37], v[158:161], v[174:177], v[34:37]
	v_mfma_f32_16x16x32_bf16 v[38:41], v[150:153], v[174:177], v[38:41]
	v_mfma_f32_16x16x32_bf16 v[38:41], v[146:149], v[170:173], v[38:41]
	v_mfma_f32_16x16x32_bf16 v[22:25], v[146:149], v[178:181], v[22:25]
	v_mfma_f32_16x16x32_bf16 v[22:25], v[150:153], v[182:185], v[22:25]
	v_mfma_f32_16x16x32_bf16 v[18:21], v[158:161], v[182:185], v[18:21]
	v_mfma_f32_16x16x32_bf16 v[18:21], v[154:157], v[178:181], v[18:21]
	v_mfma_f32_16x16x32_bf16 v[2:5], v[154:157], v[186:189], v[2:5]
	v_mfma_f32_16x16x32_bf16 v[2:5], v[158:161], v[190:193], v[2:5]
	v_mfma_f32_16x16x32_bf16 v[6:9], v[150:153], v[190:193], v[6:9]
	v_mfma_f32_16x16x32_bf16 v[6:9], v[146:149], v[186:189], v[6:9]
	s_setprio 0
	s_barrier
	s_add_i32 s44, 0, 0x18000
	s_add_i32 s64, 0, 0x1c000
	v_add_u32_e32 v142, s44, v227
	v_add_u32_e32 v158, s64, v227
	ds_read_b128 v[130:133], v142
	ds_read_b128 v[134:137], v142 offset:1024
	ds_read_b128 v[138:141], v142 offset:2048
	ds_read_b128 v[142:145], v142 offset:3072
	ds_read_b128 v[146:149], v158
	ds_read_b128 v[150:153], v158 offset:1024
	ds_read_b128 v[154:157], v158 offset:2048
	ds_read_b128 v[158:161], v158 offset:3072
	s_add_u32 s36, s36, 0x80000
	s_addc_u32 s37, s37, 0
	s_mov_b32 m0, s42
	v_lshl_add_u64 v[212:213], s[36:37], 0, v[198:199]
	ds_read_b128 v[162:165], v229 offset:32768
	ds_read_b128 v[166:169], v229 offset:33792
	ds_read_b128 v[170:173], v229 offset:34816
	ds_read_b128 v[174:177], v229 offset:35840
	ds_read_b128 v[178:181], v229 offset:36864
	ds_read_b128 v[182:185], v229 offset:37888
	ds_read_b128 v[186:189], v229 offset:38912
	ds_read_b128 v[190:193], v229 offset:39936
	global_load_lds_dwordx4 v[212:213], off
	v_lshl_add_u64 v[212:213], s[36:37], 0, v[202:203]
	s_mov_b32 m0, s43
	s_nop 0
	global_load_lds_dwordx4 v[212:213], off
	s_waitcnt vmcnt(8)
	s_waitcnt lgkmcnt(0)
	s_barrier
	s_setprio 1
	v_mfma_f32_16x16x32_bf16 v[126:129], v[130:133], v[162:165], v[126:129]
	v_mfma_f32_16x16x32_bf16 v[126:129], v[134:137], v[166:169], v[126:129]
	v_mfma_f32_16x16x32_bf16 v[122:125], v[142:145], v[166:169], v[122:125]
	v_mfma_f32_16x16x32_bf16 v[122:125], v[138:141], v[162:165], v[122:125]
	v_mfma_f32_16x16x32_bf16 v[106:109], v[138:141], v[170:173], v[106:109]
	v_mfma_f32_16x16x32_bf16 v[106:109], v[142:145], v[174:177], v[106:109]
	v_mfma_f32_16x16x32_bf16 v[110:113], v[134:137], v[174:177], v[110:113]
	v_mfma_f32_16x16x32_bf16 v[110:113], v[130:133], v[170:173], v[110:113]
	v_mfma_f32_16x16x32_bf16 v[94:97], v[130:133], v[178:181], v[94:97]
	v_mfma_f32_16x16x32_bf16 v[94:97], v[134:137], v[182:185], v[94:97]
	v_mfma_f32_16x16x32_bf16 v[90:93], v[142:145], v[182:185], v[90:93]
	v_mfma_f32_16x16x32_bf16 v[90:93], v[138:141], v[178:181], v[90:93]
	v_mfma_f32_16x16x32_bf16 v[74:77], v[138:141], v[186:189], v[74:77]
	v_mfma_f32_16x16x32_bf16 v[74:77], v[142:145], v[190:193], v[74:77]
	v_mfma_f32_16x16x32_bf16 v[78:81], v[134:137], v[190:193], v[78:81]
	v_mfma_f32_16x16x32_bf16 v[78:81], v[130:133], v[186:189], v[78:81]
	s_setprio 0
	s_setprio 1
	v_mfma_f32_16x16x32_bf16 v[118:121], v[146:149], v[162:165], v[118:121]
	v_mfma_f32_16x16x32_bf16 v[118:121], v[150:153], v[166:169], v[118:121]
	v_mfma_f32_16x16x32_bf16 v[114:117], v[158:161], v[166:169], v[114:117]
	v_mfma_f32_16x16x32_bf16 v[114:117], v[154:157], v[162:165], v[114:117]
	v_mfma_f32_16x16x32_bf16 v[98:101], v[154:157], v[170:173], v[98:101]
	v_mfma_f32_16x16x32_bf16 v[98:101], v[158:161], v[174:177], v[98:101]
	v_mfma_f32_16x16x32_bf16 v[102:105], v[150:153], v[174:177], v[102:105]
	v_mfma_f32_16x16x32_bf16 v[102:105], v[146:149], v[170:173], v[102:105]
	v_mfma_f32_16x16x32_bf16 v[86:89], v[146:149], v[178:181], v[86:89]
	v_mfma_f32_16x16x32_bf16 v[86:89], v[150:153], v[182:185], v[86:89]
	v_mfma_f32_16x16x32_bf16 v[82:85], v[158:161], v[182:185], v[82:85]
	v_mfma_f32_16x16x32_bf16 v[82:85], v[154:157], v[178:181], v[82:85]
	v_mfma_f32_16x16x32_bf16 v[66:69], v[154:157], v[186:189], v[66:69]
	v_mfma_f32_16x16x32_bf16 v[66:69], v[158:161], v[190:193], v[66:69]
	v_mfma_f32_16x16x32_bf16 v[70:73], v[150:153], v[190:193], v[70:73]
	v_mfma_f32_16x16x32_bf16 v[70:73], v[146:149], v[186:189], v[70:73]
	s_setprio 0
	s_barrier
	s_add_i32 s36, s44, s39
	v_lshl_add_u64 v[194:195], v[194:195], 0, s[2:3]
	s_mov_b32 m0, s36
	ds_read_b128 v[162:165], v229 offset:49152
	ds_read_b128 v[166:169], v229 offset:50176
	ds_read_b128 v[170:173], v229 offset:51200
	ds_read_b128 v[174:177], v229 offset:52224
	ds_read_b128 v[178:181], v229 offset:53248
	ds_read_b128 v[182:185], v229 offset:54272
	ds_read_b128 v[186:189], v229 offset:55296
	ds_read_b128 v[190:193], v229 offset:56320
	global_load_lds_dwordx4 v[194:195], off
	s_add_i32 m0, s36, 0x2000
	s_add_u32 s30, s30, 0x80080
	v_lshl_add_u64 v[194:195], v[206:207], 0, s[2:3]
	s_addc_u32 s31, s31, 0
	s_add_i32 s36, s64, s39
	global_load_lds_dwordx4 v[194:195], off
	v_lshl_add_u64 v[194:195], s[30:31], 0, v[200:201]
	s_mov_b32 m0, s36
	s_nop 0
	global_load_lds_dwordx4 v[194:195], off
	v_lshl_add_u64 v[194:195], s[30:31], 0, v[204:205]
	s_add_i32 m0, s36, 0x2000
	s_nop 0
	global_load_lds_dwordx4 v[194:195], off
	v_lshl_add_u64 v[194:195], v[208:209], 0, s[2:3]
	s_mov_b32 m0, s50
	s_nop 0
	global_load_lds_dwordx4 v[194:195], off
	v_lshl_add_u64 v[194:195], v[210:211], 0, s[2:3]
	s_mov_b32 m0, s51
	s_nop 0
	global_load_lds_dwordx4 v[194:195], off
	s_waitcnt vmcnt(8)
	s_waitcnt lgkmcnt(0)
	s_barrier
	s_setprio 1
	s_waitcnt lgkmcnt(0)
	v_mfma_f32_16x16x32_bf16 v[62:65], v[130:133], v[162:165], v[62:65]
	v_mfma_f32_16x16x32_bf16 v[62:65], v[134:137], v[166:169], v[62:65]
	v_mfma_f32_16x16x32_bf16 v[58:61], v[142:145], v[166:169], v[58:61]
	v_mfma_f32_16x16x32_bf16 v[58:61], v[138:141], v[162:165], v[58:61]
	v_mfma_f32_16x16x32_bf16 v[42:45], v[138:141], v[170:173], v[42:45]
	v_mfma_f32_16x16x32_bf16 v[42:45], v[142:145], v[174:177], v[42:45]
	v_mfma_f32_16x16x32_bf16 v[46:49], v[134:137], v[174:177], v[46:49]
	v_mfma_f32_16x16x32_bf16 v[46:49], v[130:133], v[170:173], v[46:49]
	v_mfma_f32_16x16x32_bf16 v[30:33], v[130:133], v[178:181], v[30:33]
	v_mfma_f32_16x16x32_bf16 v[30:33], v[134:137], v[182:185], v[30:33]
	v_mfma_f32_16x16x32_bf16 v[26:29], v[142:145], v[182:185], v[26:29]
	v_mfma_f32_16x16x32_bf16 v[26:29], v[138:141], v[178:181], v[26:29]
	v_mfma_f32_16x16x32_bf16 v[10:13], v[138:141], v[186:189], v[10:13]
	v_mfma_f32_16x16x32_bf16 v[10:13], v[142:145], v[190:193], v[10:13]
	v_mfma_f32_16x16x32_bf16 v[14:17], v[134:137], v[190:193], v[14:17]
	v_mfma_f32_16x16x32_bf16 v[14:17], v[130:133], v[186:189], v[14:17]
	s_setprio 0
	s_setprio 1
	v_mfma_f32_16x16x32_bf16 v[54:57], v[146:149], v[162:165], v[54:57]
	v_mfma_f32_16x16x32_bf16 v[54:57], v[150:153], v[166:169], v[54:57]
	v_mfma_f32_16x16x32_bf16 v[50:53], v[158:161], v[166:169], v[50:53]
	v_mfma_f32_16x16x32_bf16 v[50:53], v[154:157], v[162:165], v[50:53]
	v_mfma_f32_16x16x32_bf16 v[34:37], v[154:157], v[170:173], v[34:37]
	v_mfma_f32_16x16x32_bf16 v[34:37], v[158:161], v[174:177], v[34:37]
	v_mfma_f32_16x16x32_bf16 v[38:41], v[150:153], v[174:177], v[38:41]
	v_mfma_f32_16x16x32_bf16 v[38:41], v[146:149], v[170:173], v[38:41]
	v_mfma_f32_16x16x32_bf16 v[22:25], v[146:149], v[178:181], v[22:25]
	v_mfma_f32_16x16x32_bf16 v[22:25], v[150:153], v[182:185], v[22:25]
	v_mfma_f32_16x16x32_bf16 v[18:21], v[158:161], v[182:185], v[18:21]
	v_mfma_f32_16x16x32_bf16 v[18:21], v[154:157], v[178:181], v[18:21]
	v_mfma_f32_16x16x32_bf16 v[2:5], v[154:157], v[186:189], v[2:5]
	v_mfma_f32_16x16x32_bf16 v[2:5], v[158:161], v[190:193], v[2:5]
	v_mfma_f32_16x16x32_bf16 v[6:9], v[150:153], v[190:193], v[6:9]
	v_mfma_f32_16x16x32_bf16 v[6:9], v[146:149], v[186:189], v[6:9]
	s_setprio 0
	s_barrier
	s_add_i32 s36, s49, 2
	s_cmp_ge_i32 s49, s5
	s_mov_b64 s[30:31], s[34:35]
	s_mov_b32 s49, s36
	s_cbranch_scc0 .LBB0_632

.LBB0_782:
	s_add_u32 s58, s34, 0x100
	s_addc_u32 s59, s35, 0
	s_mov_b32 s60, 2
	s_mov_b64 s[34:35], 0
	s_add_i32 s36, s60, -2
	s_lshr_b32 s44, s36, 2
	s_lshl_b64 s[38:39], s[44:45], 9
	s_lshr_b32 s44, s60, 2
	s_and_b32 s61, s34, 0x100
	s_lshl_b64 s[36:37], s[44:45], 9
	s_add_u32 s44, s30, s36
	s_addc_u32 s62, s31, s37
	s_add_u32 s36, s34, 0x100
	s_addc_u32 s37, s35, 0
	s_and_b32 s63, s36, 0x100
	s_add_u32 s44, s44, s63
	s_addc_u32 s62, s62, 0
	s_add_u32 s34, s58, s34
	s_addc_u32 s35, s59, s35
	s_add_i32 s64, 0, 0x10000
	s_add_u32 s63, s30, s38
	s_addc_u32 s65, s31, s39
	s_cmp_eq_u32 s57, s60
	s_cselect_b32 s39, s27, s62
	s_cselect_b32 s38, s26, s44
	s_cselect_b32 s35, s29, s35
	s_cselect_b32 s34, s28, s34
	s_add_i32 s44, 0, 0x14000
	v_add_u32_e32 v152, s64, v137
	v_add_u32_e32 v168, s44, v137
	ds_read_b128 v[140:143], v152
	ds_read_b128 v[144:147], v152 offset:1024
	ds_read_b128 v[148:151], v152 offset:2048
	ds_read_b128 v[152:155], v152 offset:3072
	ds_read_b128 v[156:159], v168
	ds_read_b128 v[160:163], v168 offset:1024
	ds_read_b128 v[164:167], v168 offset:2048
	ds_read_b128 v[168:171], v168 offset:3072
	s_add_u32 s61, s63, s61
	s_addc_u32 s63, s65, 0
	s_add_u32 s62, s61, 0x80080
	s_addc_u32 s63, s63, 0
	v_lshl_add_u64 v[206:207], s[62:63], 0, v[130:131]
	s_add_i32 m0, s11, 0xc000
	ds_read_b128 v[172:175], v139
	ds_read_b128 v[176:179], v139 offset:1024
	ds_read_b128 v[180:183], v139 offset:2048
	ds_read_b128 v[184:187], v139 offset:3072
	ds_read_b128 v[188:191], v139 offset:4096
	ds_read_b128 v[192:195], v139 offset:5120
	ds_read_b128 v[198:201], v139 offset:6144
	ds_read_b128 v[202:205], v139 offset:7168
	global_load_lds_dwordx4 v[206:207], off
	v_lshl_add_u64 v[206:207], s[62:63], 0, v[132:133]
	s_add_i32 m0, s11, 0xe000
	s_nop 0
	global_load_lds_dwordx4 v[206:207], off
	s_waitcnt vmcnt(8)
	s_waitcnt lgkmcnt(0)
	s_barrier
	s_setprio 1
	v_mfma_f32_16x16x32_bf16 v[126:129], v[140:143], v[172:175], 0
	v_mfma_f32_16x16x32_bf16 v[126:129], v[144:147], v[176:179], v[126:129]
	v_mfma_f32_16x16x32_bf16 v[122:125], v[152:155], v[176:179], 0
	v_mfma_f32_16x16x32_bf16 v[122:125], v[148:151], v[172:175], v[122:125]
	v_mfma_f32_16x16x32_bf16 v[106:109], v[148:151], v[180:183], 0
	v_mfma_f32_16x16x32_bf16 v[106:109], v[152:155], v[184:187], v[106:109]
	v_mfma_f32_16x16x32_bf16 v[110:113], v[144:147], v[184:187], 0
	v_mfma_f32_16x16x32_bf16 v[110:113], v[140:143], v[180:183], v[110:113]
	v_mfma_f32_16x16x32_bf16 v[94:97], v[140:143], v[188:191], 0
	v_mfma_f32_16x16x32_bf16 v[94:97], v[144:147], v[192:195], v[94:97]
	v_mfma_f32_16x16x32_bf16 v[90:93], v[152:155], v[192:195], 0
	v_mfma_f32_16x16x32_bf16 v[90:93], v[148:151], v[188:191], v[90:93]
	v_mfma_f32_16x16x32_bf16 v[74:77], v[148:151], v[198:201], 0
	v_mfma_f32_16x16x32_bf16 v[74:77], v[152:155], v[202:205], v[74:77]
	v_mfma_f32_16x16x32_bf16 v[78:81], v[144:147], v[202:205], 0
	v_mfma_f32_16x16x32_bf16 v[78:81], v[140:143], v[198:201], v[78:81]
	s_setprio 0
	s_setprio 1
	v_mfma_f32_16x16x32_bf16 v[118:121], v[156:159], v[172:175], 0
	v_mfma_f32_16x16x32_bf16 v[118:121], v[160:163], v[176:179], v[118:121]
	v_mfma_f32_16x16x32_bf16 v[114:117], v[168:171], v[176:179], 0
	v_mfma_f32_16x16x32_bf16 v[114:117], v[164:167], v[172:175], v[114:117]
	v_mfma_f32_16x16x32_bf16 v[98:101], v[164:167], v[180:183], 0
	v_mfma_f32_16x16x32_bf16 v[98:101], v[168:171], v[184:187], v[98:101]
	v_mfma_f32_16x16x32_bf16 v[102:105], v[160:163], v[184:187], 0
	v_mfma_f32_16x16x32_bf16 v[102:105], v[156:159], v[180:183], v[102:105]
	v_mfma_f32_16x16x32_bf16 v[86:89], v[156:159], v[188:191], 0
	v_mfma_f32_16x16x32_bf16 v[86:89], v[160:163], v[192:195], v[86:89]
	v_mfma_f32_16x16x32_bf16 v[82:85], v[168:171], v[192:195], 0
	v_mfma_f32_16x16x32_bf16 v[82:85], v[164:167], v[188:191], v[82:85]
	v_mfma_f32_16x16x32_bf16 v[66:69], v[164:167], v[198:201], 0
	v_mfma_f32_16x16x32_bf16 v[66:69], v[168:171], v[202:205], v[66:69]
	v_mfma_f32_16x16x32_bf16 v[70:73], v[160:163], v[202:205], 0
	v_mfma_f32_16x16x32_bf16 v[70:73], v[156:159], v[198:201], v[70:73]
	s_setprio 0
	s_barrier
	s_add_i32 s61, s64, s9
	v_lshl_add_u64 v[206:207], s[34:35], 0, v[196:197]
	s_mov_b32 m0, s61
	ds_read_b128 v[172:175], v139 offset:16384
	ds_read_b128 v[176:179], v139 offset:17408
	ds_read_b128 v[180:183], v139 offset:18432
	ds_read_b128 v[184:187], v139 offset:19456
	ds_read_b128 v[188:191], v139 offset:20480
	ds_read_b128 v[192:195], v139 offset:21504
	ds_read_b128 v[198:201], v139 offset:22528
	ds_read_b128 v[202:205], v139 offset:23552
	global_load_lds_dwordx4 v[206:207], off
	s_add_i32 m0, s61, 0x2000
	s_add_u32 s62, s34, 0x80000
	v_lshl_add_u64 v[208:209], s[34:35], 0, v[134:135]
	s_addc_u32 s63, s35, 0
	s_add_i32 s44, s44, s9
	global_load_lds_dwordx4 v[208:209], off
	v_lshl_add_u64 v[210:211], s[62:63], 0, v[196:197]
	s_mov_b32 m0, s44
	v_lshl_add_u64 v[212:213], s[38:39], 0, v[132:133]
	global_load_lds_dwordx4 v[210:211], off
	v_lshl_add_u64 v[210:211], s[62:63], 0, v[134:135]
	s_add_i32 m0, s44, 0x2000
	s_nop 0
	global_load_lds_dwordx4 v[210:211], off
	v_lshl_add_u64 v[210:211], s[38:39], 0, v[130:131]
	s_mov_b32 m0, s11
	s_nop 0
	global_load_lds_dwordx4 v[210:211], off
	s_mov_b32 m0, s33
	s_nop 0
	global_load_lds_dwordx4 v[212:213], off
	s_waitcnt vmcnt(8)
	s_waitcnt lgkmcnt(0)
	s_barrier
	s_setprio 1
	v_mfma_f32_16x16x32_bf16 v[62:65], v[140:143], v[172:175], 0
	v_mfma_f32_16x16x32_bf16 v[62:65], v[144:147], v[176:179], v[62:65]
	v_mfma_f32_16x16x32_bf16 v[58:61], v[152:155], v[176:179], 0
	v_mfma_f32_16x16x32_bf16 v[58:61], v[148:151], v[172:175], v[58:61]
	v_mfma_f32_16x16x32_bf16 v[42:45], v[148:151], v[180:183], 0
	v_mfma_f32_16x16x32_bf16 v[42:45], v[152:155], v[184:187], v[42:45]
	v_mfma_f32_16x16x32_bf16 v[46:49], v[144:147], v[184:187], 0
	v_mfma_f32_16x16x32_bf16 v[46:49], v[140:143], v[180:183], v[46:49]
	v_mfma_f32_16x16x32_bf16 v[30:33], v[140:143], v[188:191], 0
	v_mfma_f32_16x16x32_bf16 v[30:33], v[144:147], v[192:195], v[30:33]
	v_mfma_f32_16x16x32_bf16 v[26:29], v[152:155], v[192:195], 0
	v_mfma_f32_16x16x32_bf16 v[26:29], v[148:151], v[188:191], v[26:29]
	v_mfma_f32_16x16x32_bf16 v[10:13], v[148:151], v[198:201], 0
	v_mfma_f32_16x16x32_bf16 v[10:13], v[152:155], v[202:205], v[10:13]
	v_mfma_f32_16x16x32_bf16 v[14:17], v[144:147], v[202:205], 0
	v_mfma_f32_16x16x32_bf16 v[14:17], v[140:143], v[198:201], v[14:17]
	s_setprio 0
	s_setprio 1
	v_mfma_f32_16x16x32_bf16 v[54:57], v[156:159], v[172:175], 0
	v_mfma_f32_16x16x32_bf16 v[54:57], v[160:163], v[176:179], v[54:57]
	v_mfma_f32_16x16x32_bf16 v[50:53], v[168:171], v[176:179], 0
	v_mfma_f32_16x16x32_bf16 v[50:53], v[164:167], v[172:175], v[50:53]
	v_mfma_f32_16x16x32_bf16 v[34:37], v[164:167], v[180:183], 0
	v_mfma_f32_16x16x32_bf16 v[34:37], v[168:171], v[184:187], v[34:37]
	v_mfma_f32_16x16x32_bf16 v[38:41], v[160:163], v[184:187], 0
	v_mfma_f32_16x16x32_bf16 v[38:41], v[156:159], v[180:183], v[38:41]
	v_mfma_f32_16x16x32_bf16 v[22:25], v[156:159], v[188:191], 0
	v_mfma_f32_16x16x32_bf16 v[22:25], v[160:163], v[192:195], v[22:25]
	v_mfma_f32_16x16x32_bf16 v[18:21], v[168:171], v[192:195], 0
	v_mfma_f32_16x16x32_bf16 v[18:21], v[164:167], v[188:191], v[18:21]
	v_mfma_f32_16x16x32_bf16 v[2:5], v[164:167], v[198:201], 0
	v_mfma_f32_16x16x32_bf16 v[2:5], v[168:171], v[202:205], v[2:5]
	v_mfma_f32_16x16x32_bf16 v[6:9], v[160:163], v[202:205], 0
	v_mfma_f32_16x16x32_bf16 v[6:9], v[156:159], v[198:201], v[6:9]
	s_setprio 0
	s_barrier
	s_add_i32 s44, 0, 0x18000
	s_add_i32 s61, 0, 0x1c000
	v_add_u32_e32 v152, s44, v137
	v_add_u32_e32 v168, s61, v137
	ds_read_b128 v[140:143], v152
	ds_read_b128 v[144:147], v152 offset:1024
	ds_read_b128 v[148:151], v152 offset:2048
	ds_read_b128 v[152:155], v152 offset:3072
	ds_read_b128 v[156:159], v168
	ds_read_b128 v[160:163], v168 offset:1024
	ds_read_b128 v[164:167], v168 offset:2048
	ds_read_b128 v[168:171], v168 offset:3072
	s_add_u32 s38, s38, 0x80000
	s_addc_u32 s39, s39, 0
	s_mov_b32 m0, s40
	v_lshl_add_u64 v[214:215], s[38:39], 0, v[130:131]
	ds_read_b128 v[172:175], v139 offset:32768
	ds_read_b128 v[176:179], v139 offset:33792
	ds_read_b128 v[180:183], v139 offset:34816
	ds_read_b128 v[184:187], v139 offset:35840
	ds_read_b128 v[188:191], v139 offset:36864
	ds_read_b128 v[192:195], v139 offset:37888
	ds_read_b128 v[198:201], v139 offset:38912
	ds_read_b128 v[202:205], v139 offset:39936
	global_load_lds_dwordx4 v[214:215], off
	v_lshl_add_u64 v[214:215], s[38:39], 0, v[132:133]
	s_mov_b32 m0, s41
	s_nop 0
	global_load_lds_dwordx4 v[214:215], off
	s_waitcnt vmcnt(8)
	s_waitcnt lgkmcnt(0)
	s_barrier
	s_setprio 1
	v_mfma_f32_16x16x32_bf16 v[126:129], v[140:143], v[172:175], v[126:129]
	v_mfma_f32_16x16x32_bf16 v[126:129], v[144:147], v[176:179], v[126:129]
	v_mfma_f32_16x16x32_bf16 v[122:125], v[152:155], v[176:179], v[122:125]
	v_mfma_f32_16x16x32_bf16 v[122:125], v[148:151], v[172:175], v[122:125]
	v_mfma_f32_16x16x32_bf16 v[106:109], v[148:151], v[180:183], v[106:109]
	v_mfma_f32_16x16x32_bf16 v[106:109], v[152:155], v[184:187], v[106:109]
	v_mfma_f32_16x16x32_bf16 v[110:113], v[144:147], v[184:187], v[110:113]
	v_mfma_f32_16x16x32_bf16 v[110:113], v[140:143], v[180:183], v[110:113]
	v_mfma_f32_16x16x32_bf16 v[94:97], v[140:143], v[188:191], v[94:97]
	v_mfma_f32_16x16x32_bf16 v[94:97], v[144:147], v[192:195], v[94:97]
	v_mfma_f32_16x16x32_bf16 v[90:93], v[152:155], v[192:195], v[90:93]
	v_mfma_f32_16x16x32_bf16 v[90:93], v[148:151], v[188:191], v[90:93]
	v_mfma_f32_16x16x32_bf16 v[74:77], v[148:151], v[198:201], v[74:77]
	v_mfma_f32_16x16x32_bf16 v[74:77], v[152:155], v[202:205], v[74:77]
	v_mfma_f32_16x16x32_bf16 v[78:81], v[144:147], v[202:205], v[78:81]
	v_mfma_f32_16x16x32_bf16 v[78:81], v[140:143], v[198:201], v[78:81]
	s_setprio 0
	s_setprio 1
	v_mfma_f32_16x16x32_bf16 v[118:121], v[156:159], v[172:175], v[118:121]
	v_mfma_f32_16x16x32_bf16 v[118:121], v[160:163], v[176:179], v[118:121]
	v_mfma_f32_16x16x32_bf16 v[114:117], v[168:171], v[176:179], v[114:117]
	v_mfma_f32_16x16x32_bf16 v[114:117], v[164:167], v[172:175], v[114:117]
	v_mfma_f32_16x16x32_bf16 v[98:101], v[164:167], v[180:183], v[98:101]
	v_mfma_f32_16x16x32_bf16 v[98:101], v[168:171], v[184:187], v[98:101]
	v_mfma_f32_16x16x32_bf16 v[102:105], v[160:163], v[184:187], v[102:105]
	v_mfma_f32_16x16x32_bf16 v[102:105], v[156:159], v[180:183], v[102:105]
	v_mfma_f32_16x16x32_bf16 v[86:89], v[156:159], v[188:191], v[86:89]
	v_mfma_f32_16x16x32_bf16 v[86:89], v[160:163], v[192:195], v[86:89]
	v_mfma_f32_16x16x32_bf16 v[82:85], v[168:171], v[192:195], v[82:85]
	v_mfma_f32_16x16x32_bf16 v[82:85], v[164:167], v[188:191], v[82:85]
	v_mfma_f32_16x16x32_bf16 v[66:69], v[164:167], v[198:201], v[66:69]
	v_mfma_f32_16x16x32_bf16 v[66:69], v[168:171], v[202:205], v[66:69]
	v_mfma_f32_16x16x32_bf16 v[70:73], v[160:163], v[202:205], v[70:73]
	v_mfma_f32_16x16x32_bf16 v[70:73], v[156:159], v[198:201], v[70:73]
	s_setprio 0
	s_barrier
	s_add_i32 s38, s44, s9
	v_lshl_add_u64 v[206:207], v[206:207], 0, s[2:3]
	s_mov_b32 m0, s38
	ds_read_b128 v[172:175], v139 offset:49152
	ds_read_b128 v[176:179], v139 offset:50176
	ds_read_b128 v[180:183], v139 offset:51200
	ds_read_b128 v[184:187], v139 offset:52224
	ds_read_b128 v[188:191], v139 offset:53248
	ds_read_b128 v[192:195], v139 offset:54272
	ds_read_b128 v[198:201], v139 offset:55296
	ds_read_b128 v[202:205], v139 offset:56320
	global_load_lds_dwordx4 v[206:207], off
	s_add_i32 m0, s38, 0x2000
	s_add_u32 s34, s34, 0x80080
	v_lshl_add_u64 v[206:207], v[208:209], 0, s[2:3]
	s_addc_u32 s35, s35, 0
	s_add_i32 s38, s61, s9
	global_load_lds_dwordx4 v[206:207], off
	v_lshl_add_u64 v[206:207], s[34:35], 0, v[196:197]
	s_mov_b32 m0, s38
	s_nop 0
	global_load_lds_dwordx4 v[206:207], off
	v_lshl_add_u64 v[206:207], s[34:35], 0, v[134:135]
	s_add_i32 m0, s38, 0x2000
	s_nop 0
	global_load_lds_dwordx4 v[206:207], off
	v_lshl_add_u64 v[206:207], v[210:211], 0, s[2:3]
	s_mov_b32 m0, s50
	s_nop 0
	global_load_lds_dwordx4 v[206:207], off
	v_lshl_add_u64 v[206:207], v[212:213], 0, s[2:3]
	s_mov_b32 m0, s51
	s_nop 0
	global_load_lds_dwordx4 v[206:207], off
	s_waitcnt vmcnt(8)
	s_waitcnt lgkmcnt(0)
	s_barrier
	s_setprio 1
	s_waitcnt lgkmcnt(0)
	v_mfma_f32_16x16x32_bf16 v[62:65], v[140:143], v[172:175], v[62:65]
	v_mfma_f32_16x16x32_bf16 v[62:65], v[144:147], v[176:179], v[62:65]
	v_mfma_f32_16x16x32_bf16 v[58:61], v[152:155], v[176:179], v[58:61]
	v_mfma_f32_16x16x32_bf16 v[58:61], v[148:151], v[172:175], v[58:61]
	v_mfma_f32_16x16x32_bf16 v[42:45], v[148:151], v[180:183], v[42:45]
	v_mfma_f32_16x16x32_bf16 v[42:45], v[152:155], v[184:187], v[42:45]
	v_mfma_f32_16x16x32_bf16 v[46:49], v[144:147], v[184:187], v[46:49]
	v_mfma_f32_16x16x32_bf16 v[46:49], v[140:143], v[180:183], v[46:49]
	v_mfma_f32_16x16x32_bf16 v[30:33], v[140:143], v[188:191], v[30:33]
	v_mfma_f32_16x16x32_bf16 v[30:33], v[144:147], v[192:195], v[30:33]
	v_mfma_f32_16x16x32_bf16 v[26:29], v[152:155], v[192:195], v[26:29]
	v_mfma_f32_16x16x32_bf16 v[26:29], v[148:151], v[188:191], v[26:29]
	v_mfma_f32_16x16x32_bf16 v[10:13], v[148:151], v[198:201], v[10:13]
	v_mfma_f32_16x16x32_bf16 v[10:13], v[152:155], v[202:205], v[10:13]
	v_mfma_f32_16x16x32_bf16 v[14:17], v[144:147], v[202:205], v[14:17]
	v_mfma_f32_16x16x32_bf16 v[14:17], v[140:143], v[198:201], v[14:17]
	s_setprio 0
	s_setprio 1
	v_mfma_f32_16x16x32_bf16 v[54:57], v[156:159], v[172:175], v[54:57]
	v_mfma_f32_16x16x32_bf16 v[54:57], v[160:163], v[176:179], v[54:57]
	v_mfma_f32_16x16x32_bf16 v[50:53], v[168:171], v[176:179], v[50:53]
	v_mfma_f32_16x16x32_bf16 v[50:53], v[164:167], v[172:175], v[50:53]
	v_mfma_f32_16x16x32_bf16 v[34:37], v[164:167], v[180:183], v[34:37]
	v_mfma_f32_16x16x32_bf16 v[34:37], v[168:171], v[184:187], v[34:37]
	v_mfma_f32_16x16x32_bf16 v[38:41], v[160:163], v[184:187], v[38:41]
	v_mfma_f32_16x16x32_bf16 v[38:41], v[156:159], v[180:183], v[38:41]
	v_mfma_f32_16x16x32_bf16 v[22:25], v[156:159], v[188:191], v[22:25]
	v_mfma_f32_16x16x32_bf16 v[22:25], v[160:163], v[192:195], v[22:25]
	v_mfma_f32_16x16x32_bf16 v[18:21], v[168:171], v[192:195], v[18:21]
	v_mfma_f32_16x16x32_bf16 v[18:21], v[164:167], v[188:191], v[18:21]
	v_mfma_f32_16x16x32_bf16 v[2:5], v[164:167], v[198:201], v[2:5]
	v_mfma_f32_16x16x32_bf16 v[2:5], v[168:171], v[202:205], v[2:5]
	v_mfma_f32_16x16x32_bf16 v[6:9], v[160:163], v[202:205], v[6:9]
	v_mfma_f32_16x16x32_bf16 v[6:9], v[156:159], v[198:201], v[6:9]
	s_setprio 0
	s_barrier
	s_add_i32 s38, s60, 2
	s_cmp_ge_i32 s60, s57
	s_mov_b64 s[34:35], s[36:37]
	s_mov_b32 s60, s38
	s_cbranch_scc1 .Lpeel_exit_wout
.LBB0_783:
	s_add_i32 s36, s60, -2
	s_lshr_b32 s44, s36, 2
	s_lshl_b64 s[38:39], s[44:45], 9
	s_lshr_b32 s44, s60, 2
	s_and_b32 s61, s34, 0x100
	s_lshl_b64 s[36:37], s[44:45], 9
	s_add_u32 s44, s30, s36
	s_addc_u32 s62, s31, s37
	s_add_u32 s36, s34, 0x100
	s_addc_u32 s37, s35, 0
	s_and_b32 s63, s36, 0x100
	s_add_u32 s44, s44, s63
	s_addc_u32 s62, s62, 0
	s_add_u32 s34, s58, s34
	s_addc_u32 s35, s59, s35
	s_add_i32 s64, 0, 0x10000
	s_add_u32 s63, s30, s38
	s_addc_u32 s65, s31, s39
	s_cmp_eq_u32 s57, s60
	s_cselect_b32 s39, s27, s62
	s_cselect_b32 s38, s26, s44
	s_cselect_b32 s35, s29, s35
	s_cselect_b32 s34, s28, s34
	s_add_i32 s44, 0, 0x14000
	v_add_u32_e32 v152, s64, v137
	v_add_u32_e32 v168, s44, v137
	ds_read_b128 v[140:143], v152
	ds_read_b128 v[144:147], v152 offset:1024
	ds_read_b128 v[148:151], v152 offset:2048
	ds_read_b128 v[152:155], v152 offset:3072
	ds_read_b128 v[156:159], v168
	ds_read_b128 v[160:163], v168 offset:1024
	ds_read_b128 v[164:167], v168 offset:2048
	ds_read_b128 v[168:171], v168 offset:3072
	s_add_u32 s61, s63, s61
	s_addc_u32 s63, s65, 0
	s_add_u32 s62, s61, 0x80080
	s_addc_u32 s63, s63, 0
	v_lshl_add_u64 v[206:207], s[62:63], 0, v[130:131]
	s_add_i32 m0, s11, 0xc000
	ds_read_b128 v[172:175], v139
	ds_read_b128 v[176:179], v139 offset:1024
	ds_read_b128 v[180:183], v139 offset:2048
	ds_read_b128 v[184:187], v139 offset:3072
	ds_read_b128 v[188:191], v139 offset:4096
	ds_read_b128 v[192:195], v139 offset:5120
	ds_read_b128 v[198:201], v139 offset:6144
	ds_read_b128 v[202:205], v139 offset:7168
	global_load_lds_dwordx4 v[206:207], off
	v_lshl_add_u64 v[206:207], s[62:63], 0, v[132:133]
	s_add_i32 m0, s11, 0xe000
	s_nop 0
	global_load_lds_dwordx4 v[206:207], off
	s_waitcnt vmcnt(8)
	s_waitcnt lgkmcnt(0)
	s_barrier
	s_setprio 1
	v_mfma_f32_16x16x32_bf16 v[126:129], v[140:143], v[172:175], v[126:129]
	v_mfma_f32_16x16x32_bf16 v[126:129], v[144:147], v[176:179], v[126:129]
	v_mfma_f32_16x16x32_bf16 v[122:125], v[152:155], v[176:179], v[122:125]
	v_mfma_f32_16x16x32_bf16 v[122:125], v[148:151], v[172:175], v[122:125]
	v_mfma_f32_16x16x32_bf16 v[106:109], v[148:151], v[180:183], v[106:109]
	v_mfma_f32_16x16x32_bf16 v[106:109], v[152:155], v[184:187], v[106:109]
	v_mfma_f32_16x16x32_bf16 v[110:113], v[144:147], v[184:187], v[110:113]
	v_mfma_f32_16x16x32_bf16 v[110:113], v[140:143], v[180:183], v[110:113]
	v_mfma_f32_16x16x32_bf16 v[94:97], v[140:143], v[188:191], v[94:97]
	v_mfma_f32_16x16x32_bf16 v[94:97], v[144:147], v[192:195], v[94:97]
	v_mfma_f32_16x16x32_bf16 v[90:93], v[152:155], v[192:195], v[90:93]
	v_mfma_f32_16x16x32_bf16 v[90:93], v[148:151], v[188:191], v[90:93]
	v_mfma_f32_16x16x32_bf16 v[74:77], v[148:151], v[198:201], v[74:77]
	v_mfma_f32_16x16x32_bf16 v[74:77], v[152:155], v[202:205], v[74:77]
	v_mfma_f32_16x16x32_bf16 v[78:81], v[144:147], v[202:205], v[78:81]
	v_mfma_f32_16x16x32_bf16 v[78:81], v[140:143], v[198:201], v[78:81]
	s_setprio 0
	s_setprio 1
	v_mfma_f32_16x16x32_bf16 v[118:121], v[156:159], v[172:175], v[118:121]
	v_mfma_f32_16x16x32_bf16 v[118:121], v[160:163], v[176:179], v[118:121]
	v_mfma_f32_16x16x32_bf16 v[114:117], v[168:171], v[176:179], v[114:117]
	v_mfma_f32_16x16x32_bf16 v[114:117], v[164:167], v[172:175], v[114:117]
	v_mfma_f32_16x16x32_bf16 v[98:101], v[164:167], v[180:183], v[98:101]
	v_mfma_f32_16x16x32_bf16 v[98:101], v[168:171], v[184:187], v[98:101]
	v_mfma_f32_16x16x32_bf16 v[102:105], v[160:163], v[184:187], v[102:105]
	v_mfma_f32_16x16x32_bf16 v[102:105], v[156:159], v[180:183], v[102:105]
	v_mfma_f32_16x16x32_bf16 v[86:89], v[156:159], v[188:191], v[86:89]
	v_mfma_f32_16x16x32_bf16 v[86:89], v[160:163], v[192:195], v[86:89]
	v_mfma_f32_16x16x32_bf16 v[82:85], v[168:171], v[192:195], v[82:85]
	v_mfma_f32_16x16x32_bf16 v[82:85], v[164:167], v[188:191], v[82:85]
	v_mfma_f32_16x16x32_bf16 v[66:69], v[164:167], v[198:201], v[66:69]
	v_mfma_f32_16x16x32_bf16 v[66:69], v[168:171], v[202:205], v[66:69]
	v_mfma_f32_16x16x32_bf16 v[70:73], v[160:163], v[202:205], v[70:73]
	v_mfma_f32_16x16x32_bf16 v[70:73], v[156:159], v[198:201], v[70:73]
	s_setprio 0
	s_barrier
	s_add_i32 s61, s64, s9
	v_lshl_add_u64 v[206:207], s[34:35], 0, v[196:197]
	s_mov_b32 m0, s61
	ds_read_b128 v[172:175], v139 offset:16384
	ds_read_b128 v[176:179], v139 offset:17408
	ds_read_b128 v[180:183], v139 offset:18432
	ds_read_b128 v[184:187], v139 offset:19456
	ds_read_b128 v[188:191], v139 offset:20480
	ds_read_b128 v[192:195], v139 offset:21504
	ds_read_b128 v[198:201], v139 offset:22528
	ds_read_b128 v[202:205], v139 offset:23552
	global_load_lds_dwordx4 v[206:207], off
	s_add_i32 m0, s61, 0x2000
	s_add_u32 s62, s34, 0x80000
	v_lshl_add_u64 v[208:209], s[34:35], 0, v[134:135]
	s_addc_u32 s63, s35, 0
	s_add_i32 s44, s44, s9
	global_load_lds_dwordx4 v[208:209], off
	v_lshl_add_u64 v[210:211], s[62:63], 0, v[196:197]
	s_mov_b32 m0, s44
	v_lshl_add_u64 v[212:213], s[38:39], 0, v[132:133]
	global_load_lds_dwordx4 v[210:211], off
	v_lshl_add_u64 v[210:211], s[62:63], 0, v[134:135]
	s_add_i32 m0, s44, 0x2000
	s_nop 0
	global_load_lds_dwordx4 v[210:211], off
	v_lshl_add_u64 v[210:211], s[38:39], 0, v[130:131]
	s_mov_b32 m0, s11
	s_nop 0
	global_load_lds_dwordx4 v[210:211], off
	s_mov_b32 m0, s33
	s_nop 0
	global_load_lds_dwordx4 v[212:213], off
	s_waitcnt vmcnt(8)
	s_waitcnt lgkmcnt(0)
	s_barrier
	s_setprio 1
	v_mfma_f32_16x16x32_bf16 v[62:65], v[140:143], v[172:175], v[62:65]
	v_mfma_f32_16x16x32_bf16 v[62:65], v[144:147], v[176:179], v[62:65]
	v_mfma_f32_16x16x32_bf16 v[58:61], v[152:155], v[176:179], v[58:61]
	v_mfma_f32_16x16x32_bf16 v[58:61], v[148:151], v[172:175], v[58:61]
	v_mfma_f32_16x16x32_bf16 v[42:45], v[148:151], v[180:183], v[42:45]
	v_mfma_f32_16x16x32_bf16 v[42:45], v[152:155], v[184:187], v[42:45]
	v_mfma_f32_16x16x32_bf16 v[46:49], v[144:147], v[184:187], v[46:49]
	v_mfma_f32_16x16x32_bf16 v[46:49], v[140:143], v[180:183], v[46:49]
	v_mfma_f32_16x16x32_bf16 v[30:33], v[140:143], v[188:191], v[30:33]
	v_mfma_f32_16x16x32_bf16 v[30:33], v[144:147], v[192:195], v[30:33]
	v_mfma_f32_16x16x32_bf16 v[26:29], v[152:155], v[192:195], v[26:29]
	v_mfma_f32_16x16x32_bf16 v[26:29], v[148:151], v[188:191], v[26:29]
	v_mfma_f32_16x16x32_bf16 v[10:13], v[148:151], v[198:201], v[10:13]
	v_mfma_f32_16x16x32_bf16 v[10:13], v[152:155], v[202:205], v[10:13]
	v_mfma_f32_16x16x32_bf16 v[14:17], v[144:147], v[202:205], v[14:17]
	v_mfma_f32_16x16x32_bf16 v[14:17], v[140:143], v[198:201], v[14:17]
	s_setprio 0
	s_setprio 1
	v_mfma_f32_16x16x32_bf16 v[54:57], v[156:159], v[172:175], v[54:57]
	v_mfma_f32_16x16x32_bf16 v[54:57], v[160:163], v[176:179], v[54:57]
	v_mfma_f32_16x16x32_bf16 v[50:53], v[168:171], v[176:179], v[50:53]
	v_mfma_f32_16x16x32_bf16 v[50:53], v[164:167], v[172:175], v[50:53]
	v_mfma_f32_16x16x32_bf16 v[34:37], v[164:167], v[180:183], v[34:37]
	v_mfma_f32_16x16x32_bf16 v[34:37], v[168:171], v[184:187], v[34:37]
	v_mfma_f32_16x16x32_bf16 v[38:41], v[160:163], v[184:187], v[38:41]
	v_mfma_f32_16x16x32_bf16 v[38:41], v[156:159], v[180:183], v[38:41]
	v_mfma_f32_16x16x32_bf16 v[22:25], v[156:159], v[188:191], v[22:25]
	v_mfma_f32_16x16x32_bf16 v[22:25], v[160:163], v[192:195], v[22:25]
	v_mfma_f32_16x16x32_bf16 v[18:21], v[168:171], v[192:195], v[18:21]
	v_mfma_f32_16x16x32_bf16 v[18:21], v[164:167], v[188:191], v[18:21]
	v_mfma_f32_16x16x32_bf16 v[2:5], v[164:167], v[198:201], v[2:5]
	v_mfma_f32_16x16x32_bf16 v[2:5], v[168:171], v[202:205], v[2:5]
	v_mfma_f32_16x16x32_bf16 v[6:9], v[160:163], v[202:205], v[6:9]
	v_mfma_f32_16x16x32_bf16 v[6:9], v[156:159], v[198:201], v[6:9]
	s_setprio 0
	s_barrier
	s_add_i32 s44, 0, 0x18000
	s_add_i32 s61, 0, 0x1c000
	v_add_u32_e32 v152, s44, v137
	v_add_u32_e32 v168, s61, v137
	ds_read_b128 v[140:143], v152
	ds_read_b128 v[144:147], v152 offset:1024
	ds_read_b128 v[148:151], v152 offset:2048
	ds_read_b128 v[152:155], v152 offset:3072
	ds_read_b128 v[156:159], v168
	ds_read_b128 v[160:163], v168 offset:1024
	ds_read_b128 v[164:167], v168 offset:2048
	ds_read_b128 v[168:171], v168 offset:3072
	s_add_u32 s38, s38, 0x80000
	s_addc_u32 s39, s39, 0
	s_mov_b32 m0, s40
	v_lshl_add_u64 v[214:215], s[38:39], 0, v[130:131]
	ds_read_b128 v[172:175], v139 offset:32768
	ds_read_b128 v[176:179], v139 offset:33792
	ds_read_b128 v[180:183], v139 offset:34816
	ds_read_b128 v[184:187], v139 offset:35840
	ds_read_b128 v[188:191], v139 offset:36864
	ds_read_b128 v[192:195], v139 offset:37888
	ds_read_b128 v[198:201], v139 offset:38912
	ds_read_b128 v[202:205], v139 offset:39936
	global_load_lds_dwordx4 v[214:215], off
	v_lshl_add_u64 v[214:215], s[38:39], 0, v[132:133]
	s_mov_b32 m0, s41
	s_nop 0
	global_load_lds_dwordx4 v[214:215], off
	s_waitcnt vmcnt(8)
	s_waitcnt lgkmcnt(0)
	s_barrier
	s_setprio 1
	v_mfma_f32_16x16x32_bf16 v[126:129], v[140:143], v[172:175], v[126:129]
	v_mfma_f32_16x16x32_bf16 v[126:129], v[144:147], v[176:179], v[126:129]
	v_mfma_f32_16x16x32_bf16 v[122:125], v[152:155], v[176:179], v[122:125]
	v_mfma_f32_16x16x32_bf16 v[122:125], v[148:151], v[172:175], v[122:125]
	v_mfma_f32_16x16x32_bf16 v[106:109], v[148:151], v[180:183], v[106:109]
	v_mfma_f32_16x16x32_bf16 v[106:109], v[152:155], v[184:187], v[106:109]
	v_mfma_f32_16x16x32_bf16 v[110:113], v[144:147], v[184:187], v[110:113]
	v_mfma_f32_16x16x32_bf16 v[110:113], v[140:143], v[180:183], v[110:113]
	v_mfma_f32_16x16x32_bf16 v[94:97], v[140:143], v[188:191], v[94:97]
	v_mfma_f32_16x16x32_bf16 v[94:97], v[144:147], v[192:195], v[94:97]
	v_mfma_f32_16x16x32_bf16 v[90:93], v[152:155], v[192:195], v[90:93]
	v_mfma_f32_16x16x32_bf16 v[90:93], v[148:151], v[188:191], v[90:93]
	v_mfma_f32_16x16x32_bf16 v[74:77], v[148:151], v[198:201], v[74:77]
	v_mfma_f32_16x16x32_bf16 v[74:77], v[152:155], v[202:205], v[74:77]
	v_mfma_f32_16x16x32_bf16 v[78:81], v[144:147], v[202:205], v[78:81]
	v_mfma_f32_16x16x32_bf16 v[78:81], v[140:143], v[198:201], v[78:81]
	s_setprio 0
	s_setprio 1
	v_mfma_f32_16x16x32_bf16 v[118:121], v[156:159], v[172:175], v[118:121]
	v_mfma_f32_16x16x32_bf16 v[118:121], v[160:163], v[176:179], v[118:121]
	v_mfma_f32_16x16x32_bf16 v[114:117], v[168:171], v[176:179], v[114:117]
	v_mfma_f32_16x16x32_bf16 v[114:117], v[164:167], v[172:175], v[114:117]
	v_mfma_f32_16x16x32_bf16 v[98:101], v[164:167], v[180:183], v[98:101]
	v_mfma_f32_16x16x32_bf16 v[98:101], v[168:171], v[184:187], v[98:101]
	v_mfma_f32_16x16x32_bf16 v[102:105], v[160:163], v[184:187], v[102:105]
	v_mfma_f32_16x16x32_bf16 v[102:105], v[156:159], v[180:183], v[102:105]
	v_mfma_f32_16x16x32_bf16 v[86:89], v[156:159], v[188:191], v[86:89]
	v_mfma_f32_16x16x32_bf16 v[86:89], v[160:163], v[192:195], v[86:89]
	v_mfma_f32_16x16x32_bf16 v[82:85], v[168:171], v[192:195], v[82:85]
	v_mfma_f32_16x16x32_bf16 v[82:85], v[164:167], v[188:191], v[82:85]
	v_mfma_f32_16x16x32_bf16 v[66:69], v[164:167], v[198:201], v[66:69]
	v_mfma_f32_16x16x32_bf16 v[66:69], v[168:171], v[202:205], v[66:69]
	v_mfma_f32_16x16x32_bf16 v[70:73], v[160:163], v[202:205], v[70:73]
	v_mfma_f32_16x16x32_bf16 v[70:73], v[156:159], v[198:201], v[70:73]
	s_setprio 0
	s_barrier
	s_add_i32 s38, s44, s9
	v_lshl_add_u64 v[206:207], v[206:207], 0, s[2:3]
	s_mov_b32 m0, s38
	ds_read_b128 v[172:175], v139 offset:49152
	ds_read_b128 v[176:179], v139 offset:50176
	ds_read_b128 v[180:183], v139 offset:51200
	ds_read_b128 v[184:187], v139 offset:52224
	ds_read_b128 v[188:191], v139 offset:53248
	ds_read_b128 v[192:195], v139 offset:54272
	ds_read_b128 v[198:201], v139 offset:55296
	ds_read_b128 v[202:205], v139 offset:56320
	global_load_lds_dwordx4 v[206:207], off
	s_add_i32 m0, s38, 0x2000
	s_add_u32 s34, s34, 0x80080
	v_lshl_add_u64 v[206:207], v[208:209], 0, s[2:3]
	s_addc_u32 s35, s35, 0
	s_add_i32 s38, s61, s9
	global_load_lds_dwordx4 v[206:207], off
	v_lshl_add_u64 v[206:207], s[34:35], 0, v[196:197]
	s_mov_b32 m0, s38
	s_nop 0
	global_load_lds_dwordx4 v[206:207], off
	v_lshl_add_u64 v[206:207], s[34:35], 0, v[134:135]
	s_add_i32 m0, s38, 0x2000
	s_nop 0
	global_load_lds_dwordx4 v[206:207], off
	v_lshl_add_u64 v[206:207], v[210:211], 0, s[2:3]
	s_mov_b32 m0, s50
	s_nop 0
	global_load_lds_dwordx4 v[206:207], off
	v_lshl_add_u64 v[206:207], v[212:213], 0, s[2:3]
	s_mov_b32 m0, s51
	s_nop 0
	global_load_lds_dwordx4 v[206:207], off
	s_waitcnt vmcnt(8)
	s_waitcnt lgkmcnt(0)
	s_barrier
	s_setprio 1
	s_waitcnt lgkmcnt(0)
	v_mfma_f32_16x16x32_bf16 v[62:65], v[140:143], v[172:175], v[62:65]
	v_mfma_f32_16x16x32_bf16 v[62:65], v[144:147], v[176:179], v[62:65]
	v_mfma_f32_16x16x32_bf16 v[58:61], v[152:155], v[176:179], v[58:61]
	v_mfma_f32_16x16x32_bf16 v[58:61], v[148:151], v[172:175], v[58:61]
	v_mfma_f32_16x16x32_bf16 v[42:45], v[148:151], v[180:183], v[42:45]
	v_mfma_f32_16x16x32_bf16 v[42:45], v[152:155], v[184:187], v[42:45]
	v_mfma_f32_16x16x32_bf16 v[46:49], v[144:147], v[184:187], v[46:49]
	v_mfma_f32_16x16x32_bf16 v[46:49], v[140:143], v[180:183], v[46:49]
	v_mfma_f32_16x16x32_bf16 v[30:33], v[140:143], v[188:191], v[30:33]
	v_mfma_f32_16x16x32_bf16 v[30:33], v[144:147], v[192:195], v[30:33]
	v_mfma_f32_16x16x32_bf16 v[26:29], v[152:155], v[192:195], v[26:29]
	v_mfma_f32_16x16x32_bf16 v[26:29], v[148:151], v[188:191], v[26:29]
	v_mfma_f32_16x16x32_bf16 v[10:13], v[148:151], v[198:201], v[10:13]
	v_mfma_f32_16x16x32_bf16 v[10:13], v[152:155], v[202:205], v[10:13]
	v_mfma_f32_16x16x32_bf16 v[14:17], v[144:147], v[202:205], v[14:17]
	v_mfma_f32_16x16x32_bf16 v[14:17], v[140:143], v[198:201], v[14:17]
	s_setprio 0
	s_setprio 1
	v_mfma_f32_16x16x32_bf16 v[54:57], v[156:159], v[172:175], v[54:57]
	v_mfma_f32_16x16x32_bf16 v[54:57], v[160:163], v[176:179], v[54:57]
	v_mfma_f32_16x16x32_bf16 v[50:53], v[168:171], v[176:179], v[50:53]
	v_mfma_f32_16x16x32_bf16 v[50:53], v[164:167], v[172:175], v[50:53]
	v_mfma_f32_16x16x32_bf16 v[34:37], v[164:167], v[180:183], v[34:37]
	v_mfma_f32_16x16x32_bf16 v[34:37], v[168:171], v[184:187], v[34:37]
	v_mfma_f32_16x16x32_bf16 v[38:41], v[160:163], v[184:187], v[38:41]
	v_mfma_f32_16x16x32_bf16 v[38:41], v[156:159], v[180:183], v[38:41]
	v_mfma_f32_16x16x32_bf16 v[22:25], v[156:159], v[188:191], v[22:25]
	v_mfma_f32_16x16x32_bf16 v[22:25], v[160:163], v[192:195], v[22:25]
	v_mfma_f32_16x16x32_bf16 v[18:21], v[168:171], v[192:195], v[18:21]
	v_mfma_f32_16x16x32_bf16 v[18:21], v[164:167], v[188:191], v[18:21]
	v_mfma_f32_16x16x32_bf16 v[2:5], v[164:167], v[198:201], v[2:5]
	v_mfma_f32_16x16x32_bf16 v[2:5], v[168:171], v[202:205], v[2:5]
	v_mfma_f32_16x16x32_bf16 v[6:9], v[160:163], v[202:205], v[6:9]
	v_mfma_f32_16x16x32_bf16 v[6:9], v[156:159], v[198:201], v[6:9]
	s_setprio 0
	s_barrier
	s_add_i32 s38, s60, 2
	s_cmp_ge_i32 s60, s57
	s_mov_b64 s[34:35], s[36:37]
	s_mov_b32 s60, s38
	s_cbranch_scc0 .LBB0_783

.LBB0_962:
	s_add_u32 s1, s18, 0x100
	s_addc_u32 s7, s19, 0
	s_mov_b32 s22, -2
	s_mov_b64 s[18:19], 0
	s_add_i32 s43, s22, 2
	s_lshr_b32 s44, s43, 2
	s_add_i32 s20, s22, 4
	s_lshl_b64 s[50:51], s[44:45], 9
	s_lshr_b32 s44, s20, 2
	s_and_b32 s47, s18, 0x100
	s_lshl_b64 s[20:21], s[44:45], 9
	s_add_u32 s23, s12, s20
	s_addc_u32 s44, s13, s21
	s_add_u32 s20, s18, 0x100
	s_addc_u32 s21, s19, 0
	s_and_b32 s49, s20, 0x100
	s_add_u32 s49, s23, s49
	s_addc_u32 s23, s44, 0
	s_add_u32 s18, s1, s18
	s_addc_u32 s19, s7, s19
	s_add_i32 s44, 0, 0x10000
	s_add_u32 s50, s12, s50
	s_addc_u32 s51, s13, s51
	s_cmp_eq_u32 s22, 28
	s_cselect_b32 s23, s15, s23
	s_cselect_b32 s22, s14, s49
	v_add_u32_e32 v138, s44, v140
	s_cselect_b32 s19, s17, s19
	s_cselect_b32 s18, s16, s18
	s_add_i32 s49, 0, 0x14000
	ds_read_b128 v[142:145], v138
	ds_read_b128 v[146:149], v138 offset:1024
	ds_read_b128 v[150:153], v138 offset:2048
	ds_read_b128 v[154:157], v138 offset:3072
	v_add_u32_e32 v138, s49, v140
	ds_read_b128 v[158:161], v138
	ds_read_b128 v[162:165], v138 offset:1024
	ds_read_b128 v[166:169], v138 offset:2048
	ds_read_b128 v[170:173], v138 offset:3072
	s_add_u32 s47, s50, s47
	s_addc_u32 s51, s51, 0
	s_add_u32 s50, s47, 0x80080
	s_addc_u32 s51, s51, 0
	v_lshl_add_u64 v[138:139], s[50:51], 0, v[134:135]
	s_add_i32 m0, s33, 0xc000
	ds_read_b128 v[174:177], v141
	ds_read_b128 v[178:181], v141 offset:1024
	ds_read_b128 v[182:185], v141 offset:2048
	ds_read_b128 v[186:189], v141 offset:3072
	ds_read_b128 v[190:193], v141 offset:4096
	ds_read_b128 v[198:201], v141 offset:5120
	ds_read_b128 v[202:205], v141 offset:6144
	ds_read_b128 v[206:209], v141 offset:7168
	global_load_lds_dwordx4 v[138:139], off
	v_lshl_add_u64 v[138:139], s[50:51], 0, v[132:133]
	s_add_i32 m0, s33, 0xe000
	s_nop 0
	global_load_lds_dwordx4 v[138:139], off
	s_waitcnt vmcnt(8)
	s_waitcnt lgkmcnt(0)
	s_barrier
	s_setprio 1
	v_mfma_f32_16x16x32_bf16 v[126:129], v[142:145], v[174:177], 0
	v_mfma_f32_16x16x32_bf16 v[126:129], v[146:149], v[178:181], v[126:129]
	v_mfma_f32_16x16x32_bf16 v[122:125], v[154:157], v[178:181], 0
	v_mfma_f32_16x16x32_bf16 v[122:125], v[150:153], v[174:177], v[122:125]
	v_mfma_f32_16x16x32_bf16 v[106:109], v[150:153], v[182:185], 0
	v_mfma_f32_16x16x32_bf16 v[106:109], v[154:157], v[186:189], v[106:109]
	v_mfma_f32_16x16x32_bf16 v[110:113], v[146:149], v[186:189], 0
	v_mfma_f32_16x16x32_bf16 v[110:113], v[142:145], v[182:185], v[110:113]
	v_mfma_f32_16x16x32_bf16 v[94:97], v[142:145], v[190:193], 0
	v_mfma_f32_16x16x32_bf16 v[94:97], v[146:149], v[198:201], v[94:97]
	v_mfma_f32_16x16x32_bf16 v[90:93], v[154:157], v[198:201], 0
	v_mfma_f32_16x16x32_bf16 v[90:93], v[150:153], v[190:193], v[90:93]
	v_mfma_f32_16x16x32_bf16 v[74:77], v[150:153], v[202:205], 0
	v_mfma_f32_16x16x32_bf16 v[74:77], v[154:157], v[206:209], v[74:77]
	v_mfma_f32_16x16x32_bf16 v[78:81], v[146:149], v[206:209], 0
	v_mfma_f32_16x16x32_bf16 v[78:81], v[142:145], v[202:205], v[78:81]
	s_setprio 0
	s_setprio 1
	v_mfma_f32_16x16x32_bf16 v[118:121], v[158:161], v[174:177], 0
	v_mfma_f32_16x16x32_bf16 v[118:121], v[162:165], v[178:181], v[118:121]
	v_mfma_f32_16x16x32_bf16 v[114:117], v[170:173], v[178:181], 0
	v_mfma_f32_16x16x32_bf16 v[114:117], v[166:169], v[174:177], v[114:117]
	v_mfma_f32_16x16x32_bf16 v[98:101], v[166:169], v[182:185], 0
	v_mfma_f32_16x16x32_bf16 v[98:101], v[170:173], v[186:189], v[98:101]
	v_mfma_f32_16x16x32_bf16 v[102:105], v[162:165], v[186:189], 0
	v_mfma_f32_16x16x32_bf16 v[102:105], v[158:161], v[182:185], v[102:105]
	v_mfma_f32_16x16x32_bf16 v[86:89], v[158:161], v[190:193], 0
	v_mfma_f32_16x16x32_bf16 v[86:89], v[162:165], v[198:201], v[86:89]
	v_mfma_f32_16x16x32_bf16 v[82:85], v[170:173], v[198:201], 0
	v_mfma_f32_16x16x32_bf16 v[82:85], v[166:169], v[190:193], v[82:85]
	v_mfma_f32_16x16x32_bf16 v[66:69], v[166:169], v[202:205], 0
	v_mfma_f32_16x16x32_bf16 v[66:69], v[170:173], v[206:209], v[66:69]
	v_mfma_f32_16x16x32_bf16 v[70:73], v[162:165], v[206:209], 0
	v_mfma_f32_16x16x32_bf16 v[70:73], v[158:161], v[202:205], v[70:73]
	s_setprio 0
	s_barrier
	s_add_i32 s44, s44, s31
	v_lshl_add_u64 v[138:139], s[18:19], 0, v[196:197]
	s_mov_b32 m0, s44
	ds_read_b128 v[174:177], v141 offset:16384
	ds_read_b128 v[178:181], v141 offset:17408
	ds_read_b128 v[182:185], v141 offset:18432
	ds_read_b128 v[186:189], v141 offset:19456
	ds_read_b128 v[190:193], v141 offset:20480
	ds_read_b128 v[198:201], v141 offset:21504
	ds_read_b128 v[202:205], v141 offset:22528
	ds_read_b128 v[206:209], v141 offset:23552
	global_load_lds_dwordx4 v[138:139], off
	s_add_i32 m0, s44, 0x2000
	s_add_u32 s50, s18, 0x80000
	v_lshl_add_u64 v[194:195], s[18:19], 0, v[130:131]
	s_addc_u32 s51, s19, 0
	s_add_i32 s44, s49, s31
	global_load_lds_dwordx4 v[194:195], off
	v_lshl_add_u64 v[210:211], s[50:51], 0, v[196:197]
	s_mov_b32 m0, s44
	v_lshl_add_u64 v[212:213], s[22:23], 0, v[132:133]
	global_load_lds_dwordx4 v[210:211], off
	v_lshl_add_u64 v[210:211], s[50:51], 0, v[130:131]
	s_add_i32 m0, s44, 0x2000
	s_nop 0
	global_load_lds_dwordx4 v[210:211], off
	v_lshl_add_u64 v[210:211], s[22:23], 0, v[134:135]
	s_mov_b32 m0, s33
	s_nop 0
	global_load_lds_dwordx4 v[210:211], off
	s_mov_b32 m0, s34
	s_nop 0
	global_load_lds_dwordx4 v[212:213], off
	s_waitcnt vmcnt(8)
	s_waitcnt lgkmcnt(0)
	s_barrier
	s_setprio 1
	v_mfma_f32_16x16x32_bf16 v[62:65], v[142:145], v[174:177], 0
	v_mfma_f32_16x16x32_bf16 v[62:65], v[146:149], v[178:181], v[62:65]
	v_mfma_f32_16x16x32_bf16 v[58:61], v[154:157], v[178:181], 0
	v_mfma_f32_16x16x32_bf16 v[58:61], v[150:153], v[174:177], v[58:61]
	v_mfma_f32_16x16x32_bf16 v[42:45], v[150:153], v[182:185], 0
	v_mfma_f32_16x16x32_bf16 v[42:45], v[154:157], v[186:189], v[42:45]
	v_mfma_f32_16x16x32_bf16 v[46:49], v[146:149], v[186:189], 0
	v_mfma_f32_16x16x32_bf16 v[46:49], v[142:145], v[182:185], v[46:49]
	v_mfma_f32_16x16x32_bf16 v[30:33], v[142:145], v[190:193], 0
	v_mfma_f32_16x16x32_bf16 v[30:33], v[146:149], v[198:201], v[30:33]
	v_mfma_f32_16x16x32_bf16 v[26:29], v[154:157], v[198:201], 0
	v_mfma_f32_16x16x32_bf16 v[26:29], v[150:153], v[190:193], v[26:29]
	v_mfma_f32_16x16x32_bf16 v[10:13], v[150:153], v[202:205], 0
	v_mfma_f32_16x16x32_bf16 v[10:13], v[154:157], v[206:209], v[10:13]
	v_mfma_f32_16x16x32_bf16 v[14:17], v[146:149], v[206:209], 0
	v_mfma_f32_16x16x32_bf16 v[14:17], v[142:145], v[202:205], v[14:17]
	s_setprio 0
	s_setprio 1
	v_mfma_f32_16x16x32_bf16 v[54:57], v[158:161], v[174:177], 0
	v_mfma_f32_16x16x32_bf16 v[54:57], v[162:165], v[178:181], v[54:57]
	v_mfma_f32_16x16x32_bf16 v[50:53], v[170:173], v[178:181], 0
	v_mfma_f32_16x16x32_bf16 v[50:53], v[166:169], v[174:177], v[50:53]
	v_mfma_f32_16x16x32_bf16 v[34:37], v[166:169], v[182:185], 0
	v_mfma_f32_16x16x32_bf16 v[34:37], v[170:173], v[186:189], v[34:37]
	v_mfma_f32_16x16x32_bf16 v[38:41], v[162:165], v[186:189], 0
	v_mfma_f32_16x16x32_bf16 v[38:41], v[158:161], v[182:185], v[38:41]
	v_mfma_f32_16x16x32_bf16 v[22:25], v[158:161], v[190:193], 0
	v_mfma_f32_16x16x32_bf16 v[22:25], v[162:165], v[198:201], v[22:25]
	v_mfma_f32_16x16x32_bf16 v[18:21], v[170:173], v[198:201], 0
	v_mfma_f32_16x16x32_bf16 v[18:21], v[166:169], v[190:193], v[18:21]
	v_mfma_f32_16x16x32_bf16 v[2:5], v[166:169], v[202:205], 0
	v_mfma_f32_16x16x32_bf16 v[2:5], v[170:173], v[206:209], v[2:5]
	v_mfma_f32_16x16x32_bf16 v[6:9], v[162:165], v[206:209], 0
	v_mfma_f32_16x16x32_bf16 v[6:9], v[158:161], v[202:205], v[6:9]
	s_setprio 0
	s_barrier
	s_add_i32 s44, 0, 0x18000
	s_add_i32 s47, 0, 0x1c000
	v_add_u32_e32 v154, s44, v140
	v_add_u32_e32 v170, s47, v140
	ds_read_b128 v[142:145], v154
	ds_read_b128 v[146:149], v154 offset:1024
	ds_read_b128 v[150:153], v154 offset:2048
	ds_read_b128 v[154:157], v154 offset:3072
	ds_read_b128 v[158:161], v170
	ds_read_b128 v[162:165], v170 offset:1024
	ds_read_b128 v[166:169], v170 offset:2048
	ds_read_b128 v[170:173], v170 offset:3072
	s_add_u32 s22, s22, 0x80000
	s_addc_u32 s23, s23, 0
	s_mov_b32 m0, s35
	v_lshl_add_u64 v[214:215], s[22:23], 0, v[134:135]
	ds_read_b128 v[174:177], v141 offset:32768
	ds_read_b128 v[178:181], v141 offset:33792
	ds_read_b128 v[182:185], v141 offset:34816
	ds_read_b128 v[186:189], v141 offset:35840
	ds_read_b128 v[190:193], v141 offset:36864
	ds_read_b128 v[198:201], v141 offset:37888
	ds_read_b128 v[202:205], v141 offset:38912
	ds_read_b128 v[206:209], v141 offset:39936
	global_load_lds_dwordx4 v[214:215], off
	v_lshl_add_u64 v[214:215], s[22:23], 0, v[132:133]
	s_mov_b32 m0, s36
	s_nop 0
	global_load_lds_dwordx4 v[214:215], off
	s_waitcnt vmcnt(8)
	s_waitcnt lgkmcnt(0)
	s_barrier
	s_setprio 1
	v_mfma_f32_16x16x32_bf16 v[126:129], v[142:145], v[174:177], v[126:129]
	v_mfma_f32_16x16x32_bf16 v[126:129], v[146:149], v[178:181], v[126:129]
	v_mfma_f32_16x16x32_bf16 v[122:125], v[154:157], v[178:181], v[122:125]
	v_mfma_f32_16x16x32_bf16 v[122:125], v[150:153], v[174:177], v[122:125]
	v_mfma_f32_16x16x32_bf16 v[106:109], v[150:153], v[182:185], v[106:109]
	v_mfma_f32_16x16x32_bf16 v[106:109], v[154:157], v[186:189], v[106:109]
	v_mfma_f32_16x16x32_bf16 v[110:113], v[146:149], v[186:189], v[110:113]
	v_mfma_f32_16x16x32_bf16 v[110:113], v[142:145], v[182:185], v[110:113]
	v_mfma_f32_16x16x32_bf16 v[94:97], v[142:145], v[190:193], v[94:97]
	v_mfma_f32_16x16x32_bf16 v[94:97], v[146:149], v[198:201], v[94:97]
	v_mfma_f32_16x16x32_bf16 v[90:93], v[154:157], v[198:201], v[90:93]
	v_mfma_f32_16x16x32_bf16 v[90:93], v[150:153], v[190:193], v[90:93]
	v_mfma_f32_16x16x32_bf16 v[74:77], v[150:153], v[202:205], v[74:77]
	v_mfma_f32_16x16x32_bf16 v[74:77], v[154:157], v[206:209], v[74:77]
	v_mfma_f32_16x16x32_bf16 v[78:81], v[146:149], v[206:209], v[78:81]
	v_mfma_f32_16x16x32_bf16 v[78:81], v[142:145], v[202:205], v[78:81]
	s_setprio 0
	s_setprio 1
	v_mfma_f32_16x16x32_bf16 v[118:121], v[158:161], v[174:177], v[118:121]
	v_mfma_f32_16x16x32_bf16 v[118:121], v[162:165], v[178:181], v[118:121]
	v_mfma_f32_16x16x32_bf16 v[114:117], v[170:173], v[178:181], v[114:117]
	v_mfma_f32_16x16x32_bf16 v[114:117], v[166:169], v[174:177], v[114:117]
	v_mfma_f32_16x16x32_bf16 v[98:101], v[166:169], v[182:185], v[98:101]
	v_mfma_f32_16x16x32_bf16 v[98:101], v[170:173], v[186:189], v[98:101]
	v_mfma_f32_16x16x32_bf16 v[102:105], v[162:165], v[186:189], v[102:105]
	v_mfma_f32_16x16x32_bf16 v[102:105], v[158:161], v[182:185], v[102:105]
	v_mfma_f32_16x16x32_bf16 v[86:89], v[158:161], v[190:193], v[86:89]
	v_mfma_f32_16x16x32_bf16 v[86:89], v[162:165], v[198:201], v[86:89]
	v_mfma_f32_16x16x32_bf16 v[82:85], v[170:173], v[198:201], v[82:85]
	v_mfma_f32_16x16x32_bf16 v[82:85], v[166:169], v[190:193], v[82:85]
	v_mfma_f32_16x16x32_bf16 v[66:69], v[166:169], v[202:205], v[66:69]
	v_mfma_f32_16x16x32_bf16 v[66:69], v[170:173], v[206:209], v[66:69]
	v_mfma_f32_16x16x32_bf16 v[70:73], v[162:165], v[206:209], v[70:73]
	v_mfma_f32_16x16x32_bf16 v[70:73], v[158:161], v[202:205], v[70:73]
	s_setprio 0
	s_barrier
	s_add_i32 s22, s44, s31
	v_lshl_add_u64 v[138:139], v[138:139], 0, s[2:3]
	s_mov_b32 m0, s22
	ds_read_b128 v[174:177], v141 offset:49152
	ds_read_b128 v[178:181], v141 offset:50176
	ds_read_b128 v[182:185], v141 offset:51200
	ds_read_b128 v[186:189], v141 offset:52224
	ds_read_b128 v[190:193], v141 offset:53248
	ds_read_b128 v[198:201], v141 offset:54272
	ds_read_b128 v[202:205], v141 offset:55296
	ds_read_b128 v[206:209], v141 offset:56320
	global_load_lds_dwordx4 v[138:139], off
	s_add_i32 m0, s22, 0x2000
	s_add_u32 s18, s18, 0x80080
	v_lshl_add_u64 v[138:139], v[194:195], 0, s[2:3]
	s_addc_u32 s19, s19, 0
	s_add_i32 s22, s47, s31
	global_load_lds_dwordx4 v[138:139], off
	v_lshl_add_u64 v[138:139], s[18:19], 0, v[196:197]
	s_mov_b32 m0, s22
	s_nop 0
	global_load_lds_dwordx4 v[138:139], off
	v_lshl_add_u64 v[138:139], s[18:19], 0, v[130:131]
	s_add_i32 m0, s22, 0x2000
	s_nop 0
	global_load_lds_dwordx4 v[138:139], off
	v_lshl_add_u64 v[138:139], v[210:211], 0, s[2:3]
	s_mov_b32 m0, s37
	s_nop 0
	global_load_lds_dwordx4 v[138:139], off
	v_lshl_add_u64 v[138:139], v[212:213], 0, s[2:3]
	s_mov_b32 m0, s38
	s_nop 0
	global_load_lds_dwordx4 v[138:139], off
	s_waitcnt vmcnt(8)
	s_waitcnt lgkmcnt(0)
	s_barrier
	s_setprio 1
	s_waitcnt lgkmcnt(0)
	v_mfma_f32_16x16x32_bf16 v[62:65], v[142:145], v[174:177], v[62:65]
	v_mfma_f32_16x16x32_bf16 v[62:65], v[146:149], v[178:181], v[62:65]
	v_mfma_f32_16x16x32_bf16 v[58:61], v[154:157], v[178:181], v[58:61]
	v_mfma_f32_16x16x32_bf16 v[58:61], v[150:153], v[174:177], v[58:61]
	v_mfma_f32_16x16x32_bf16 v[42:45], v[150:153], v[182:185], v[42:45]
	v_mfma_f32_16x16x32_bf16 v[42:45], v[154:157], v[186:189], v[42:45]
	v_mfma_f32_16x16x32_bf16 v[46:49], v[146:149], v[186:189], v[46:49]
	v_mfma_f32_16x16x32_bf16 v[46:49], v[142:145], v[182:185], v[46:49]
	v_mfma_f32_16x16x32_bf16 v[30:33], v[142:145], v[190:193], v[30:33]
	v_mfma_f32_16x16x32_bf16 v[30:33], v[146:149], v[198:201], v[30:33]
	v_mfma_f32_16x16x32_bf16 v[26:29], v[154:157], v[198:201], v[26:29]
	v_mfma_f32_16x16x32_bf16 v[26:29], v[150:153], v[190:193], v[26:29]
	v_mfma_f32_16x16x32_bf16 v[10:13], v[150:153], v[202:205], v[10:13]
	v_mfma_f32_16x16x32_bf16 v[10:13], v[154:157], v[206:209], v[10:13]
	v_mfma_f32_16x16x32_bf16 v[14:17], v[146:149], v[206:209], v[14:17]
	v_mfma_f32_16x16x32_bf16 v[14:17], v[142:145], v[202:205], v[14:17]
	s_setprio 0
	s_setprio 1
	v_mfma_f32_16x16x32_bf16 v[54:57], v[158:161], v[174:177], v[54:57]
	v_mfma_f32_16x16x32_bf16 v[54:57], v[162:165], v[178:181], v[54:57]
	v_mfma_f32_16x16x32_bf16 v[50:53], v[170:173], v[178:181], v[50:53]
	v_mfma_f32_16x16x32_bf16 v[50:53], v[166:169], v[174:177], v[50:53]
	v_mfma_f32_16x16x32_bf16 v[34:37], v[166:169], v[182:185], v[34:37]
	v_mfma_f32_16x16x32_bf16 v[34:37], v[170:173], v[186:189], v[34:37]
	v_mfma_f32_16x16x32_bf16 v[38:41], v[162:165], v[186:189], v[38:41]
	v_mfma_f32_16x16x32_bf16 v[38:41], v[158:161], v[182:185], v[38:41]
	v_mfma_f32_16x16x32_bf16 v[22:25], v[158:161], v[190:193], v[22:25]
	v_mfma_f32_16x16x32_bf16 v[22:25], v[162:165], v[198:201], v[22:25]
	v_mfma_f32_16x16x32_bf16 v[18:21], v[170:173], v[198:201], v[18:21]
	v_mfma_f32_16x16x32_bf16 v[18:21], v[166:169], v[190:193], v[18:21]
	v_mfma_f32_16x16x32_bf16 v[2:5], v[166:169], v[202:205], v[2:5]
	v_mfma_f32_16x16x32_bf16 v[2:5], v[170:173], v[206:209], v[2:5]
	v_mfma_f32_16x16x32_bf16 v[6:9], v[162:165], v[206:209], v[6:9]
	v_mfma_f32_16x16x32_bf16 v[6:9], v[158:161], v[202:205], v[6:9]
	s_setprio 0
	s_barrier
	s_cmp_gt_u32 s43, 29
	s_mov_b64 s[18:19], s[20:21]
	s_mov_b32 s22, s43
	s_cbranch_scc1 .Lpeel_exit_w1
.LBB0_963:
	s_add_i32 s43, s22, 2
	s_lshr_b32 s44, s43, 2
	s_add_i32 s20, s22, 4
	s_lshl_b64 s[50:51], s[44:45], 9
	s_lshr_b32 s44, s20, 2
	s_and_b32 s47, s18, 0x100
	s_lshl_b64 s[20:21], s[44:45], 9
	s_add_u32 s23, s12, s20
	s_addc_u32 s44, s13, s21
	s_add_u32 s20, s18, 0x100
	s_addc_u32 s21, s19, 0
	s_and_b32 s49, s20, 0x100
	s_add_u32 s49, s23, s49
	s_addc_u32 s23, s44, 0
	s_add_u32 s18, s1, s18
	s_addc_u32 s19, s7, s19
	s_add_i32 s44, 0, 0x10000
	s_add_u32 s50, s12, s50
	s_addc_u32 s51, s13, s51
	s_cmp_eq_u32 s22, 28
	s_cselect_b32 s23, s15, s23
	s_cselect_b32 s22, s14, s49
	v_add_u32_e32 v138, s44, v140
	s_cselect_b32 s19, s17, s19
	s_cselect_b32 s18, s16, s18
	s_add_i32 s49, 0, 0x14000
	ds_read_b128 v[142:145], v138
	ds_read_b128 v[146:149], v138 offset:1024
	ds_read_b128 v[150:153], v138 offset:2048
	ds_read_b128 v[154:157], v138 offset:3072
	v_add_u32_e32 v138, s49, v140
	ds_read_b128 v[158:161], v138
	ds_read_b128 v[162:165], v138 offset:1024
	ds_read_b128 v[166:169], v138 offset:2048
	ds_read_b128 v[170:173], v138 offset:3072
	s_add_u32 s47, s50, s47
	s_addc_u32 s51, s51, 0
	s_add_u32 s50, s47, 0x80080
	s_addc_u32 s51, s51, 0
	v_lshl_add_u64 v[138:139], s[50:51], 0, v[134:135]
	s_add_i32 m0, s33, 0xc000
	ds_read_b128 v[174:177], v141
	ds_read_b128 v[178:181], v141 offset:1024
	ds_read_b128 v[182:185], v141 offset:2048
	ds_read_b128 v[186:189], v141 offset:3072
	ds_read_b128 v[190:193], v141 offset:4096
	ds_read_b128 v[198:201], v141 offset:5120
	ds_read_b128 v[202:205], v141 offset:6144
	ds_read_b128 v[206:209], v141 offset:7168
	global_load_lds_dwordx4 v[138:139], off
	v_lshl_add_u64 v[138:139], s[50:51], 0, v[132:133]
	s_add_i32 m0, s33, 0xe000
	s_nop 0
	global_load_lds_dwordx4 v[138:139], off
	s_waitcnt vmcnt(8)
	s_waitcnt lgkmcnt(0)
	s_barrier
	s_setprio 1
	v_mfma_f32_16x16x32_bf16 v[126:129], v[142:145], v[174:177], v[126:129]
	v_mfma_f32_16x16x32_bf16 v[126:129], v[146:149], v[178:181], v[126:129]
	v_mfma_f32_16x16x32_bf16 v[122:125], v[154:157], v[178:181], v[122:125]
	v_mfma_f32_16x16x32_bf16 v[122:125], v[150:153], v[174:177], v[122:125]
	v_mfma_f32_16x16x32_bf16 v[106:109], v[150:153], v[182:185], v[106:109]
	v_mfma_f32_16x16x32_bf16 v[106:109], v[154:157], v[186:189], v[106:109]
	v_mfma_f32_16x16x32_bf16 v[110:113], v[146:149], v[186:189], v[110:113]
	v_mfma_f32_16x16x32_bf16 v[110:113], v[142:145], v[182:185], v[110:113]
	v_mfma_f32_16x16x32_bf16 v[94:97], v[142:145], v[190:193], v[94:97]
	v_mfma_f32_16x16x32_bf16 v[94:97], v[146:149], v[198:201], v[94:97]
	v_mfma_f32_16x16x32_bf16 v[90:93], v[154:157], v[198:201], v[90:93]
	v_mfma_f32_16x16x32_bf16 v[90:93], v[150:153], v[190:193], v[90:93]
	v_mfma_f32_16x16x32_bf16 v[74:77], v[150:153], v[202:205], v[74:77]
	v_mfma_f32_16x16x32_bf16 v[74:77], v[154:157], v[206:209], v[74:77]
	v_mfma_f32_16x16x32_bf16 v[78:81], v[146:149], v[206:209], v[78:81]
	v_mfma_f32_16x16x32_bf16 v[78:81], v[142:145], v[202:205], v[78:81]
	s_setprio 0
	s_setprio 1
	v_mfma_f32_16x16x32_bf16 v[118:121], v[158:161], v[174:177], v[118:121]
	v_mfma_f32_16x16x32_bf16 v[118:121], v[162:165], v[178:181], v[118:121]
	v_mfma_f32_16x16x32_bf16 v[114:117], v[170:173], v[178:181], v[114:117]
	v_mfma_f32_16x16x32_bf16 v[114:117], v[166:169], v[174:177], v[114:117]
	v_mfma_f32_16x16x32_bf16 v[98:101], v[166:169], v[182:185], v[98:101]
	v_mfma_f32_16x16x32_bf16 v[98:101], v[170:173], v[186:189], v[98:101]
	v_mfma_f32_16x16x32_bf16 v[102:105], v[162:165], v[186:189], v[102:105]
	v_mfma_f32_16x16x32_bf16 v[102:105], v[158:161], v[182:185], v[102:105]
	v_mfma_f32_16x16x32_bf16 v[86:89], v[158:161], v[190:193], v[86:89]
	v_mfma_f32_16x16x32_bf16 v[86:89], v[162:165], v[198:201], v[86:89]
	v_mfma_f32_16x16x32_bf16 v[82:85], v[170:173], v[198:201], v[82:85]
	v_mfma_f32_16x16x32_bf16 v[82:85], v[166:169], v[190:193], v[82:85]
	v_mfma_f32_16x16x32_bf16 v[66:69], v[166:169], v[202:205], v[66:69]
	v_mfma_f32_16x16x32_bf16 v[66:69], v[170:173], v[206:209], v[66:69]
	v_mfma_f32_16x16x32_bf16 v[70:73], v[162:165], v[206:209], v[70:73]
	v_mfma_f32_16x16x32_bf16 v[70:73], v[158:161], v[202:205], v[70:73]
	s_setprio 0
	s_barrier
	s_add_i32 s44, s44, s31
	v_lshl_add_u64 v[138:139], s[18:19], 0, v[196:197]
	s_mov_b32 m0, s44
	ds_read_b128 v[174:177], v141 offset:16384
	ds_read_b128 v[178:181], v141 offset:17408
	ds_read_b128 v[182:185], v141 offset:18432
	ds_read_b128 v[186:189], v141 offset:19456
	ds_read_b128 v[190:193], v141 offset:20480
	ds_read_b128 v[198:201], v141 offset:21504
	ds_read_b128 v[202:205], v141 offset:22528
	ds_read_b128 v[206:209], v141 offset:23552
	global_load_lds_dwordx4 v[138:139], off
	s_add_i32 m0, s44, 0x2000
	s_add_u32 s50, s18, 0x80000
	v_lshl_add_u64 v[194:195], s[18:19], 0, v[130:131]
	s_addc_u32 s51, s19, 0
	s_add_i32 s44, s49, s31
	global_load_lds_dwordx4 v[194:195], off
	v_lshl_add_u64 v[210:211], s[50:51], 0, v[196:197]
	s_mov_b32 m0, s44
	v_lshl_add_u64 v[212:213], s[22:23], 0, v[132:133]
	global_load_lds_dwordx4 v[210:211], off
	v_lshl_add_u64 v[210:211], s[50:51], 0, v[130:131]
	s_add_i32 m0, s44, 0x2000
	s_nop 0
	global_load_lds_dwordx4 v[210:211], off
	v_lshl_add_u64 v[210:211], s[22:23], 0, v[134:135]
	s_mov_b32 m0, s33
	s_nop 0
	global_load_lds_dwordx4 v[210:211], off
	s_mov_b32 m0, s34
	s_nop 0
	global_load_lds_dwordx4 v[212:213], off
	s_waitcnt vmcnt(8)
	s_waitcnt lgkmcnt(0)
	s_barrier
	s_setprio 1
	v_mfma_f32_16x16x32_bf16 v[62:65], v[142:145], v[174:177], v[62:65]
	v_mfma_f32_16x16x32_bf16 v[62:65], v[146:149], v[178:181], v[62:65]
	v_mfma_f32_16x16x32_bf16 v[58:61], v[154:157], v[178:181], v[58:61]
	v_mfma_f32_16x16x32_bf16 v[58:61], v[150:153], v[174:177], v[58:61]
	v_mfma_f32_16x16x32_bf16 v[42:45], v[150:153], v[182:185], v[42:45]
	v_mfma_f32_16x16x32_bf16 v[42:45], v[154:157], v[186:189], v[42:45]
	v_mfma_f32_16x16x32_bf16 v[46:49], v[146:149], v[186:189], v[46:49]
	v_mfma_f32_16x16x32_bf16 v[46:49], v[142:145], v[182:185], v[46:49]
	v_mfma_f32_16x16x32_bf16 v[30:33], v[142:145], v[190:193], v[30:33]
	v_mfma_f32_16x16x32_bf16 v[30:33], v[146:149], v[198:201], v[30:33]
	v_mfma_f32_16x16x32_bf16 v[26:29], v[154:157], v[198:201], v[26:29]
	v_mfma_f32_16x16x32_bf16 v[26:29], v[150:153], v[190:193], v[26:29]
	v_mfma_f32_16x16x32_bf16 v[10:13], v[150:153], v[202:205], v[10:13]
	v_mfma_f32_16x16x32_bf16 v[10:13], v[154:157], v[206:209], v[10:13]
	v_mfma_f32_16x16x32_bf16 v[14:17], v[146:149], v[206:209], v[14:17]
	v_mfma_f32_16x16x32_bf16 v[14:17], v[142:145], v[202:205], v[14:17]
	s_setprio 0
	s_setprio 1
	v_mfma_f32_16x16x32_bf16 v[54:57], v[158:161], v[174:177], v[54:57]
	v_mfma_f32_16x16x32_bf16 v[54:57], v[162:165], v[178:181], v[54:57]
	v_mfma_f32_16x16x32_bf16 v[50:53], v[170:173], v[178:181], v[50:53]
	v_mfma_f32_16x16x32_bf16 v[50:53], v[166:169], v[174:177], v[50:53]
	v_mfma_f32_16x16x32_bf16 v[34:37], v[166:169], v[182:185], v[34:37]
	v_mfma_f32_16x16x32_bf16 v[34:37], v[170:173], v[186:189], v[34:37]
	v_mfma_f32_16x16x32_bf16 v[38:41], v[162:165], v[186:189], v[38:41]
	v_mfma_f32_16x16x32_bf16 v[38:41], v[158:161], v[182:185], v[38:41]
	v_mfma_f32_16x16x32_bf16 v[22:25], v[158:161], v[190:193], v[22:25]
	v_mfma_f32_16x16x32_bf16 v[22:25], v[162:165], v[198:201], v[22:25]
	v_mfma_f32_16x16x32_bf16 v[18:21], v[170:173], v[198:201], v[18:21]
	v_mfma_f32_16x16x32_bf16 v[18:21], v[166:169], v[190:193], v[18:21]
	v_mfma_f32_16x16x32_bf16 v[2:5], v[166:169], v[202:205], v[2:5]
	v_mfma_f32_16x16x32_bf16 v[2:5], v[170:173], v[206:209], v[2:5]
	v_mfma_f32_16x16x32_bf16 v[6:9], v[162:165], v[206:209], v[6:9]
	v_mfma_f32_16x16x32_bf16 v[6:9], v[158:161], v[202:205], v[6:9]
	s_setprio 0
	s_barrier
	s_add_i32 s44, 0, 0x18000
	s_add_i32 s47, 0, 0x1c000
	v_add_u32_e32 v154, s44, v140
	v_add_u32_e32 v170, s47, v140
	ds_read_b128 v[142:145], v154
	ds_read_b128 v[146:149], v154 offset:1024
	ds_read_b128 v[150:153], v154 offset:2048
	ds_read_b128 v[154:157], v154 offset:3072
	ds_read_b128 v[158:161], v170
	ds_read_b128 v[162:165], v170 offset:1024
	ds_read_b128 v[166:169], v170 offset:2048
	ds_read_b128 v[170:173], v170 offset:3072
	s_add_u32 s22, s22, 0x80000
	s_addc_u32 s23, s23, 0
	s_mov_b32 m0, s35
	v_lshl_add_u64 v[214:215], s[22:23], 0, v[134:135]
	ds_read_b128 v[174:177], v141 offset:32768
	ds_read_b128 v[178:181], v141 offset:33792
	ds_read_b128 v[182:185], v141 offset:34816
	ds_read_b128 v[186:189], v141 offset:35840
	ds_read_b128 v[190:193], v141 offset:36864
	ds_read_b128 v[198:201], v141 offset:37888
	ds_read_b128 v[202:205], v141 offset:38912
	ds_read_b128 v[206:209], v141 offset:39936
	global_load_lds_dwordx4 v[214:215], off
	v_lshl_add_u64 v[214:215], s[22:23], 0, v[132:133]
	s_mov_b32 m0, s36
	s_nop 0
	global_load_lds_dwordx4 v[214:215], off
	s_waitcnt vmcnt(8)
	s_waitcnt lgkmcnt(0)
	s_barrier
	s_setprio 1
	v_mfma_f32_16x16x32_bf16 v[126:129], v[142:145], v[174:177], v[126:129]
	v_mfma_f32_16x16x32_bf16 v[126:129], v[146:149], v[178:181], v[126:129]
	v_mfma_f32_16x16x32_bf16 v[122:125], v[154:157], v[178:181], v[122:125]
	v_mfma_f32_16x16x32_bf16 v[122:125], v[150:153], v[174:177], v[122:125]
	v_mfma_f32_16x16x32_bf16 v[106:109], v[150:153], v[182:185], v[106:109]
	v_mfma_f32_16x16x32_bf16 v[106:109], v[154:157], v[186:189], v[106:109]
	v_mfma_f32_16x16x32_bf16 v[110:113], v[146:149], v[186:189], v[110:113]
	v_mfma_f32_16x16x32_bf16 v[110:113], v[142:145], v[182:185], v[110:113]
	v_mfma_f32_16x16x32_bf16 v[94:97], v[142:145], v[190:193], v[94:97]
	v_mfma_f32_16x16x32_bf16 v[94:97], v[146:149], v[198:201], v[94:97]
	v_mfma_f32_16x16x32_bf16 v[90:93], v[154:157], v[198:201], v[90:93]
	v_mfma_f32_16x16x32_bf16 v[90:93], v[150:153], v[190:193], v[90:93]
	v_mfma_f32_16x16x32_bf16 v[74:77], v[150:153], v[202:205], v[74:77]
	v_mfma_f32_16x16x32_bf16 v[74:77], v[154:157], v[206:209], v[74:77]
	v_mfma_f32_16x16x32_bf16 v[78:81], v[146:149], v[206:209], v[78:81]
	v_mfma_f32_16x16x32_bf16 v[78:81], v[142:145], v[202:205], v[78:81]
	s_setprio 0
	s_setprio 1
	v_mfma_f32_16x16x32_bf16 v[118:121], v[158:161], v[174:177], v[118:121]
	v_mfma_f32_16x16x32_bf16 v[118:121], v[162:165], v[178:181], v[118:121]
	v_mfma_f32_16x16x32_bf16 v[114:117], v[170:173], v[178:181], v[114:117]
	v_mfma_f32_16x16x32_bf16 v[114:117], v[166:169], v[174:177], v[114:117]
	v_mfma_f32_16x16x32_bf16 v[98:101], v[166:169], v[182:185], v[98:101]
	v_mfma_f32_16x16x32_bf16 v[98:101], v[170:173], v[186:189], v[98:101]
	v_mfma_f32_16x16x32_bf16 v[102:105], v[162:165], v[186:189], v[102:105]
	v_mfma_f32_16x16x32_bf16 v[102:105], v[158:161], v[182:185], v[102:105]
	v_mfma_f32_16x16x32_bf16 v[86:89], v[158:161], v[190:193], v[86:89]
	v_mfma_f32_16x16x32_bf16 v[86:89], v[162:165], v[198:201], v[86:89]
	v_mfma_f32_16x16x32_bf16 v[82:85], v[170:173], v[198:201], v[82:85]
	v_mfma_f32_16x16x32_bf16 v[82:85], v[166:169], v[190:193], v[82:85]
	v_mfma_f32_16x16x32_bf16 v[66:69], v[166:169], v[202:205], v[66:69]
	v_mfma_f32_16x16x32_bf16 v[66:69], v[170:173], v[206:209], v[66:69]
	v_mfma_f32_16x16x32_bf16 v[70:73], v[162:165], v[206:209], v[70:73]
	v_mfma_f32_16x16x32_bf16 v[70:73], v[158:161], v[202:205], v[70:73]
	s_setprio 0
	s_barrier
	s_add_i32 s22, s44, s31
	v_lshl_add_u64 v[138:139], v[138:139], 0, s[2:3]
	s_mov_b32 m0, s22
	ds_read_b128 v[174:177], v141 offset:49152
	ds_read_b128 v[178:181], v141 offset:50176
	ds_read_b128 v[182:185], v141 offset:51200
	ds_read_b128 v[186:189], v141 offset:52224
	ds_read_b128 v[190:193], v141 offset:53248
	ds_read_b128 v[198:201], v141 offset:54272
	ds_read_b128 v[202:205], v141 offset:55296
	ds_read_b128 v[206:209], v141 offset:56320
	global_load_lds_dwordx4 v[138:139], off
	s_add_i32 m0, s22, 0x2000
	s_add_u32 s18, s18, 0x80080
	v_lshl_add_u64 v[138:139], v[194:195], 0, s[2:3]
	s_addc_u32 s19, s19, 0
	s_add_i32 s22, s47, s31
	global_load_lds_dwordx4 v[138:139], off
	v_lshl_add_u64 v[138:139], s[18:19], 0, v[196:197]
	s_mov_b32 m0, s22
	s_nop 0
	global_load_lds_dwordx4 v[138:139], off
	v_lshl_add_u64 v[138:139], s[18:19], 0, v[130:131]
	s_add_i32 m0, s22, 0x2000
	s_nop 0
	global_load_lds_dwordx4 v[138:139], off
	v_lshl_add_u64 v[138:139], v[210:211], 0, s[2:3]
	s_mov_b32 m0, s37
	s_nop 0
	global_load_lds_dwordx4 v[138:139], off
	v_lshl_add_u64 v[138:139], v[212:213], 0, s[2:3]
	s_mov_b32 m0, s38
	s_nop 0
	global_load_lds_dwordx4 v[138:139], off
	s_waitcnt vmcnt(8)
	s_waitcnt lgkmcnt(0)
	s_barrier
	s_setprio 1
	s_waitcnt lgkmcnt(0)
	v_mfma_f32_16x16x32_bf16 v[62:65], v[142:145], v[174:177], v[62:65]
	v_mfma_f32_16x16x32_bf16 v[62:65], v[146:149], v[178:181], v[62:65]
	v_mfma_f32_16x16x32_bf16 v[58:61], v[154:157], v[178:181], v[58:61]
	v_mfma_f32_16x16x32_bf16 v[58:61], v[150:153], v[174:177], v[58:61]
	v_mfma_f32_16x16x32_bf16 v[42:45], v[150:153], v[182:185], v[42:45]
	v_mfma_f32_16x16x32_bf16 v[42:45], v[154:157], v[186:189], v[42:45]
	v_mfma_f32_16x16x32_bf16 v[46:49], v[146:149], v[186:189], v[46:49]
	v_mfma_f32_16x16x32_bf16 v[46:49], v[142:145], v[182:185], v[46:49]
	v_mfma_f32_16x16x32_bf16 v[30:33], v[142:145], v[190:193], v[30:33]
	v_mfma_f32_16x16x32_bf16 v[30:33], v[146:149], v[198:201], v[30:33]
	v_mfma_f32_16x16x32_bf16 v[26:29], v[154:157], v[198:201], v[26:29]
	v_mfma_f32_16x16x32_bf16 v[26:29], v[150:153], v[190:193], v[26:29]
	v_mfma_f32_16x16x32_bf16 v[10:13], v[150:153], v[202:205], v[10:13]
	v_mfma_f32_16x16x32_bf16 v[10:13], v[154:157], v[206:209], v[10:13]
	v_mfma_f32_16x16x32_bf16 v[14:17], v[146:149], v[206:209], v[14:17]
	v_mfma_f32_16x16x32_bf16 v[14:17], v[142:145], v[202:205], v[14:17]
	s_setprio 0
	s_setprio 1
	v_mfma_f32_16x16x32_bf16 v[54:57], v[158:161], v[174:177], v[54:57]
	v_mfma_f32_16x16x32_bf16 v[54:57], v[162:165], v[178:181], v[54:57]
	v_mfma_f32_16x16x32_bf16 v[50:53], v[170:173], v[178:181], v[50:53]
	v_mfma_f32_16x16x32_bf16 v[50:53], v[166:169], v[174:177], v[50:53]
	v_mfma_f32_16x16x32_bf16 v[34:37], v[166:169], v[182:185], v[34:37]
	v_mfma_f32_16x16x32_bf16 v[34:37], v[170:173], v[186:189], v[34:37]
	v_mfma_f32_16x16x32_bf16 v[38:41], v[162:165], v[186:189], v[38:41]
	v_mfma_f32_16x16x32_bf16 v[38:41], v[158:161], v[182:185], v[38:41]
	v_mfma_f32_16x16x32_bf16 v[22:25], v[158:161], v[190:193], v[22:25]
	v_mfma_f32_16x16x32_bf16 v[22:25], v[162:165], v[198:201], v[22:25]
	v_mfma_f32_16x16x32_bf16 v[18:21], v[170:173], v[198:201], v[18:21]
	v_mfma_f32_16x16x32_bf16 v[18:21], v[166:169], v[190:193], v[18:21]
	v_mfma_f32_16x16x32_bf16 v[2:5], v[166:169], v[202:205], v[2:5]
	v_mfma_f32_16x16x32_bf16 v[2:5], v[170:173], v[206:209], v[2:5]
	v_mfma_f32_16x16x32_bf16 v[6:9], v[162:165], v[206:209], v[6:9]
	v_mfma_f32_16x16x32_bf16 v[6:9], v[158:161], v[202:205], v[6:9]
	s_setprio 0
	s_barrier
	s_cmp_gt_u32 s43, 29
	s_mov_b64 s[18:19], s[20:21]
	s_mov_b32 s22, s43
	s_cbranch_scc0 .LBB0_963

.LBB0_1029:
	s_add_u32 s58, s28, 0x100
	s_addc_u32 s59, s29, 0
	s_mov_b32 s60, 2
	s_mov_b64 s[28:29], 0
	s_add_i32 s30, s60, -2
	s_lshr_b32 s44, s30, 2
	s_lshl_b64 s[34:35], s[44:45], 17
	s_lshr_b32 s44, s60, 2
	s_and_b32 s61, s28, 0x100
	s_lshl_b64 s[30:31], s[44:45], 17
	s_add_u32 s44, s26, s30
	s_addc_u32 s62, s27, s31
	s_add_u32 s30, s28, 0x100
	s_addc_u32 s31, s29, 0
	s_and_b32 s63, s30, 0x100
	s_add_u32 s44, s44, s63
	s_addc_u32 s62, s62, 0
	s_add_u32 s28, s58, s28
	s_addc_u32 s29, s59, s29
	s_add_i32 s64, 0, 0x10000
	s_add_u32 s63, s26, s34
	s_addc_u32 s65, s27, s35
	s_cmp_eq_u32 s57, s60
	s_cselect_b32 s35, s23, s62
	s_cselect_b32 s34, s22, s44
	s_cselect_b32 s29, s25, s29
	s_cselect_b32 s28, s24, s28
	s_add_i32 s44, 0, 0x14000
	v_add_u32_e32 v152, s64, v137
	v_add_u32_e32 v168, s44, v137
	ds_read_b128 v[140:143], v152
	ds_read_b128 v[144:147], v152 offset:1024
	ds_read_b128 v[148:151], v152 offset:2048
	ds_read_b128 v[152:155], v152 offset:3072
	ds_read_b128 v[156:159], v168
	ds_read_b128 v[160:163], v168 offset:1024
	ds_read_b128 v[164:167], v168 offset:2048
	ds_read_b128 v[168:171], v168 offset:3072
	s_add_u32 s61, s63, s61
	s_addc_u32 s63, s65, 0
	s_add_u32 s62, s61, 0x10080
	s_addc_u32 s63, s63, 0
	v_lshl_add_u64 v[206:207], s[62:63], 0, v[130:131]
	s_add_i32 m0, s33, 0xc000
	ds_read_b128 v[172:175], v139
	ds_read_b128 v[176:179], v139 offset:1024
	ds_read_b128 v[180:183], v139 offset:2048
	ds_read_b128 v[184:187], v139 offset:3072
	ds_read_b128 v[188:191], v139 offset:4096
	ds_read_b128 v[192:195], v139 offset:5120
	ds_read_b128 v[198:201], v139 offset:6144
	ds_read_b128 v[202:205], v139 offset:7168
	global_load_lds_dwordx4 v[206:207], off
	v_lshl_add_u64 v[206:207], s[62:63], 0, v[132:133]
	s_add_i32 m0, s33, 0xe000
	s_nop 0
	global_load_lds_dwordx4 v[206:207], off
	s_waitcnt vmcnt(8)
	s_waitcnt lgkmcnt(0)
	s_barrier
	s_setprio 1
	s_waitcnt lgkmcnt(0)
	v_mfma_f32_16x16x32_bf16 v[126:129], v[140:143], v[172:175], 0
	v_mfma_f32_16x16x32_bf16 v[126:129], v[144:147], v[176:179], v[126:129]
	v_mfma_f32_16x16x32_bf16 v[122:125], v[152:155], v[176:179], 0
	v_mfma_f32_16x16x32_bf16 v[122:125], v[148:151], v[172:175], v[122:125]
	v_mfma_f32_16x16x32_bf16 v[106:109], v[148:151], v[180:183], 0
	v_mfma_f32_16x16x32_bf16 v[106:109], v[152:155], v[184:187], v[106:109]
	v_mfma_f32_16x16x32_bf16 v[110:113], v[144:147], v[184:187], 0
	v_mfma_f32_16x16x32_bf16 v[110:113], v[140:143], v[180:183], v[110:113]
	v_mfma_f32_16x16x32_bf16 v[94:97], v[140:143], v[188:191], 0
	v_mfma_f32_16x16x32_bf16 v[94:97], v[144:147], v[192:195], v[94:97]
	v_mfma_f32_16x16x32_bf16 v[90:93], v[152:155], v[192:195], 0
	v_mfma_f32_16x16x32_bf16 v[90:93], v[148:151], v[188:191], v[90:93]
	v_mfma_f32_16x16x32_bf16 v[74:77], v[148:151], v[198:201], 0
	v_mfma_f32_16x16x32_bf16 v[74:77], v[152:155], v[202:205], v[74:77]
	v_mfma_f32_16x16x32_bf16 v[78:81], v[144:147], v[202:205], 0
	v_mfma_f32_16x16x32_bf16 v[78:81], v[140:143], v[198:201], v[78:81]
	s_setprio 0
	s_setprio 1
	v_mfma_f32_16x16x32_bf16 v[118:121], v[156:159], v[172:175], 0
	v_mfma_f32_16x16x32_bf16 v[118:121], v[160:163], v[176:179], v[118:121]
	v_mfma_f32_16x16x32_bf16 v[114:117], v[168:171], v[176:179], 0
	v_mfma_f32_16x16x32_bf16 v[114:117], v[164:167], v[172:175], v[114:117]
	v_mfma_f32_16x16x32_bf16 v[98:101], v[164:167], v[180:183], 0
	v_mfma_f32_16x16x32_bf16 v[98:101], v[168:171], v[184:187], v[98:101]
	v_mfma_f32_16x16x32_bf16 v[102:105], v[160:163], v[184:187], 0
	v_mfma_f32_16x16x32_bf16 v[102:105], v[156:159], v[180:183], v[102:105]
	v_mfma_f32_16x16x32_bf16 v[86:89], v[156:159], v[188:191], 0
	v_mfma_f32_16x16x32_bf16 v[86:89], v[160:163], v[192:195], v[86:89]
	v_mfma_f32_16x16x32_bf16 v[82:85], v[168:171], v[192:195], 0
	v_mfma_f32_16x16x32_bf16 v[82:85], v[164:167], v[188:191], v[82:85]
	v_mfma_f32_16x16x32_bf16 v[66:69], v[164:167], v[198:201], 0
	v_mfma_f32_16x16x32_bf16 v[66:69], v[168:171], v[202:205], v[66:69]
	v_mfma_f32_16x16x32_bf16 v[70:73], v[160:163], v[202:205], 0
	v_mfma_f32_16x16x32_bf16 v[70:73], v[156:159], v[198:201], v[70:73]
	s_setprio 0
	s_barrier
	s_add_i32 s61, s64, s9
	v_lshl_add_u64 v[206:207], s[28:29], 0, v[196:197]
	s_mov_b32 m0, s61
	ds_read_b128 v[172:175], v139 offset:16384
	ds_read_b128 v[176:179], v139 offset:17408
	ds_read_b128 v[180:183], v139 offset:18432
	ds_read_b128 v[184:187], v139 offset:19456
	ds_read_b128 v[188:191], v139 offset:20480
	ds_read_b128 v[192:195], v139 offset:21504
	ds_read_b128 v[198:201], v139 offset:22528
	ds_read_b128 v[202:205], v139 offset:23552
	global_load_lds_dwordx4 v[206:207], off
	s_add_i32 m0, s61, 0x2000
	s_add_u32 s62, s28, 0x204000
	v_lshl_add_u64 v[208:209], s[28:29], 0, v[134:135]
	s_addc_u32 s63, s29, 0
	s_add_i32 s44, s44, s9
	global_load_lds_dwordx4 v[208:209], off
	v_lshl_add_u64 v[210:211], s[62:63], 0, v[196:197]
	s_mov_b32 m0, s44
	v_lshl_add_u64 v[212:213], s[34:35], 0, v[132:133]
	global_load_lds_dwordx4 v[210:211], off
	v_lshl_add_u64 v[210:211], s[62:63], 0, v[134:135]
	s_add_i32 m0, s44, 0x2000
	s_nop 0
	global_load_lds_dwordx4 v[210:211], off
	v_lshl_add_u64 v[210:211], s[34:35], 0, v[130:131]
	s_mov_b32 m0, s33
	s_nop 0
	global_load_lds_dwordx4 v[210:211], off
	s_mov_b32 m0, s36
	s_nop 0
	global_load_lds_dwordx4 v[212:213], off
	s_waitcnt vmcnt(8)
	s_waitcnt lgkmcnt(0)
	s_barrier
	s_setprio 1
	v_mfma_f32_16x16x32_bf16 v[62:65], v[140:143], v[172:175], 0
	v_mfma_f32_16x16x32_bf16 v[62:65], v[144:147], v[176:179], v[62:65]
	v_mfma_f32_16x16x32_bf16 v[58:61], v[152:155], v[176:179], 0
	v_mfma_f32_16x16x32_bf16 v[58:61], v[148:151], v[172:175], v[58:61]
	v_mfma_f32_16x16x32_bf16 v[42:45], v[148:151], v[180:183], 0
	v_mfma_f32_16x16x32_bf16 v[42:45], v[152:155], v[184:187], v[42:45]
	v_mfma_f32_16x16x32_bf16 v[46:49], v[144:147], v[184:187], 0
	v_mfma_f32_16x16x32_bf16 v[46:49], v[140:143], v[180:183], v[46:49]
	v_mfma_f32_16x16x32_bf16 v[30:33], v[140:143], v[188:191], 0
	v_mfma_f32_16x16x32_bf16 v[30:33], v[144:147], v[192:195], v[30:33]
	v_mfma_f32_16x16x32_bf16 v[26:29], v[152:155], v[192:195], 0
	v_mfma_f32_16x16x32_bf16 v[26:29], v[148:151], v[188:191], v[26:29]
	v_mfma_f32_16x16x32_bf16 v[10:13], v[148:151], v[198:201], 0
	v_mfma_f32_16x16x32_bf16 v[10:13], v[152:155], v[202:205], v[10:13]
	v_mfma_f32_16x16x32_bf16 v[14:17], v[144:147], v[202:205], 0
	v_mfma_f32_16x16x32_bf16 v[14:17], v[140:143], v[198:201], v[14:17]
	s_setprio 0
	s_setprio 1
	v_mfma_f32_16x16x32_bf16 v[54:57], v[156:159], v[172:175], 0
	v_mfma_f32_16x16x32_bf16 v[54:57], v[160:163], v[176:179], v[54:57]
	v_mfma_f32_16x16x32_bf16 v[50:53], v[168:171], v[176:179], 0
	v_mfma_f32_16x16x32_bf16 v[50:53], v[164:167], v[172:175], v[50:53]
	v_mfma_f32_16x16x32_bf16 v[34:37], v[164:167], v[180:183], 0
	v_mfma_f32_16x16x32_bf16 v[34:37], v[168:171], v[184:187], v[34:37]
	v_mfma_f32_16x16x32_bf16 v[38:41], v[160:163], v[184:187], 0
	v_mfma_f32_16x16x32_bf16 v[38:41], v[156:159], v[180:183], v[38:41]
	v_mfma_f32_16x16x32_bf16 v[22:25], v[156:159], v[188:191], 0
	v_mfma_f32_16x16x32_bf16 v[22:25], v[160:163], v[192:195], v[22:25]
	v_mfma_f32_16x16x32_bf16 v[18:21], v[168:171], v[192:195], 0
	v_mfma_f32_16x16x32_bf16 v[18:21], v[164:167], v[188:191], v[18:21]
	v_mfma_f32_16x16x32_bf16 v[2:5], v[164:167], v[198:201], 0
	v_mfma_f32_16x16x32_bf16 v[2:5], v[168:171], v[202:205], v[2:5]
	v_mfma_f32_16x16x32_bf16 v[6:9], v[160:163], v[202:205], 0
	v_mfma_f32_16x16x32_bf16 v[6:9], v[156:159], v[198:201], v[6:9]
	s_setprio 0
	s_barrier
	s_add_i32 s44, 0, 0x18000
	s_add_i32 s61, 0, 0x1c000
	v_add_u32_e32 v152, s44, v137
	v_add_u32_e32 v168, s61, v137
	ds_read_b128 v[140:143], v152
	ds_read_b128 v[144:147], v152 offset:1024
	ds_read_b128 v[148:151], v152 offset:2048
	ds_read_b128 v[152:155], v152 offset:3072
	ds_read_b128 v[156:159], v168
	ds_read_b128 v[160:163], v168 offset:1024
	ds_read_b128 v[164:167], v168 offset:2048
	ds_read_b128 v[168:171], v168 offset:3072
	s_add_u32 s34, s34, 0x10000
	s_addc_u32 s35, s35, 0
	s_mov_b32 m0, s37
	v_lshl_add_u64 v[214:215], s[34:35], 0, v[130:131]
	ds_read_b128 v[172:175], v139 offset:32768
	ds_read_b128 v[176:179], v139 offset:33792
	ds_read_b128 v[180:183], v139 offset:34816
	ds_read_b128 v[184:187], v139 offset:35840
	ds_read_b128 v[188:191], v139 offset:36864
	ds_read_b128 v[192:195], v139 offset:37888
	ds_read_b128 v[198:201], v139 offset:38912
	ds_read_b128 v[202:205], v139 offset:39936
	global_load_lds_dwordx4 v[214:215], off
	v_lshl_add_u64 v[214:215], s[34:35], 0, v[132:133]
	s_mov_b32 m0, s38
	s_nop 0
	global_load_lds_dwordx4 v[214:215], off
	s_waitcnt vmcnt(8)
	s_waitcnt lgkmcnt(0)
	s_barrier
	s_setprio 1
	v_mfma_f32_16x16x32_bf16 v[126:129], v[140:143], v[172:175], v[126:129]
	v_mfma_f32_16x16x32_bf16 v[126:129], v[144:147], v[176:179], v[126:129]
	v_mfma_f32_16x16x32_bf16 v[122:125], v[152:155], v[176:179], v[122:125]
	v_mfma_f32_16x16x32_bf16 v[122:125], v[148:151], v[172:175], v[122:125]
	v_mfma_f32_16x16x32_bf16 v[106:109], v[148:151], v[180:183], v[106:109]
	v_mfma_f32_16x16x32_bf16 v[106:109], v[152:155], v[184:187], v[106:109]
	v_mfma_f32_16x16x32_bf16 v[110:113], v[144:147], v[184:187], v[110:113]
	v_mfma_f32_16x16x32_bf16 v[110:113], v[140:143], v[180:183], v[110:113]
	v_mfma_f32_16x16x32_bf16 v[94:97], v[140:143], v[188:191], v[94:97]
	v_mfma_f32_16x16x32_bf16 v[94:97], v[144:147], v[192:195], v[94:97]
	v_mfma_f32_16x16x32_bf16 v[90:93], v[152:155], v[192:195], v[90:93]
	v_mfma_f32_16x16x32_bf16 v[90:93], v[148:151], v[188:191], v[90:93]
	v_mfma_f32_16x16x32_bf16 v[74:77], v[148:151], v[198:201], v[74:77]
	v_mfma_f32_16x16x32_bf16 v[74:77], v[152:155], v[202:205], v[74:77]
	v_mfma_f32_16x16x32_bf16 v[78:81], v[144:147], v[202:205], v[78:81]
	v_mfma_f32_16x16x32_bf16 v[78:81], v[140:143], v[198:201], v[78:81]
	s_setprio 0
	s_setprio 1
	v_mfma_f32_16x16x32_bf16 v[118:121], v[156:159], v[172:175], v[118:121]
	v_mfma_f32_16x16x32_bf16 v[118:121], v[160:163], v[176:179], v[118:121]
	v_mfma_f32_16x16x32_bf16 v[114:117], v[168:171], v[176:179], v[114:117]
	v_mfma_f32_16x16x32_bf16 v[114:117], v[164:167], v[172:175], v[114:117]
	v_mfma_f32_16x16x32_bf16 v[98:101], v[164:167], v[180:183], v[98:101]
	v_mfma_f32_16x16x32_bf16 v[98:101], v[168:171], v[184:187], v[98:101]
	v_mfma_f32_16x16x32_bf16 v[102:105], v[160:163], v[184:187], v[102:105]
	v_mfma_f32_16x16x32_bf16 v[102:105], v[156:159], v[180:183], v[102:105]
	v_mfma_f32_16x16x32_bf16 v[86:89], v[156:159], v[188:191], v[86:89]
	v_mfma_f32_16x16x32_bf16 v[86:89], v[160:163], v[192:195], v[86:89]
	v_mfma_f32_16x16x32_bf16 v[82:85], v[168:171], v[192:195], v[82:85]
	v_mfma_f32_16x16x32_bf16 v[82:85], v[164:167], v[188:191], v[82:85]
	v_mfma_f32_16x16x32_bf16 v[66:69], v[164:167], v[198:201], v[66:69]
	v_mfma_f32_16x16x32_bf16 v[66:69], v[168:171], v[202:205], v[66:69]
	v_mfma_f32_16x16x32_bf16 v[70:73], v[160:163], v[202:205], v[70:73]
	v_mfma_f32_16x16x32_bf16 v[70:73], v[156:159], v[198:201], v[70:73]
	s_setprio 0
	s_barrier
	s_add_i32 s34, s44, s9
	v_lshl_add_u64 v[206:207], v[206:207], 0, s[2:3]
	s_mov_b32 m0, s34
	ds_read_b128 v[172:175], v139 offset:49152
	ds_read_b128 v[176:179], v139 offset:50176
	ds_read_b128 v[180:183], v139 offset:51200
	ds_read_b128 v[184:187], v139 offset:52224
	ds_read_b128 v[188:191], v139 offset:53248
	ds_read_b128 v[192:195], v139 offset:54272
	ds_read_b128 v[198:201], v139 offset:55296
	ds_read_b128 v[202:205], v139 offset:56320
	global_load_lds_dwordx4 v[206:207], off
	s_add_i32 m0, s34, 0x2000
	s_add_u32 s28, s28, 0x204080
	v_lshl_add_u64 v[206:207], v[208:209], 0, s[2:3]
	s_addc_u32 s29, s29, 0
	s_add_i32 s34, s61, s9
	global_load_lds_dwordx4 v[206:207], off
	v_lshl_add_u64 v[206:207], s[28:29], 0, v[196:197]
	s_mov_b32 m0, s34
	s_nop 0
	global_load_lds_dwordx4 v[206:207], off
	v_lshl_add_u64 v[206:207], s[28:29], 0, v[134:135]
	s_add_i32 m0, s34, 0x2000
	s_nop 0
	global_load_lds_dwordx4 v[206:207], off
	v_lshl_add_u64 v[206:207], v[210:211], 0, s[2:3]
	s_mov_b32 m0, s47
	s_nop 0
	global_load_lds_dwordx4 v[206:207], off
	v_lshl_add_u64 v[206:207], v[212:213], 0, s[2:3]
	s_mov_b32 m0, s49
	s_nop 0
	global_load_lds_dwordx4 v[206:207], off
	s_waitcnt vmcnt(8)
	s_waitcnt lgkmcnt(0)
	s_barrier
	s_setprio 1
	s_waitcnt lgkmcnt(0)
	v_mfma_f32_16x16x32_bf16 v[62:65], v[140:143], v[172:175], v[62:65]
	v_mfma_f32_16x16x32_bf16 v[62:65], v[144:147], v[176:179], v[62:65]
	v_mfma_f32_16x16x32_bf16 v[58:61], v[152:155], v[176:179], v[58:61]
	v_mfma_f32_16x16x32_bf16 v[58:61], v[148:151], v[172:175], v[58:61]
	v_mfma_f32_16x16x32_bf16 v[42:45], v[148:151], v[180:183], v[42:45]
	v_mfma_f32_16x16x32_bf16 v[42:45], v[152:155], v[184:187], v[42:45]
	v_mfma_f32_16x16x32_bf16 v[46:49], v[144:147], v[184:187], v[46:49]
	v_mfma_f32_16x16x32_bf16 v[46:49], v[140:143], v[180:183], v[46:49]
	v_mfma_f32_16x16x32_bf16 v[30:33], v[140:143], v[188:191], v[30:33]
	v_mfma_f32_16x16x32_bf16 v[30:33], v[144:147], v[192:195], v[30:33]
	v_mfma_f32_16x16x32_bf16 v[26:29], v[152:155], v[192:195], v[26:29]
	v_mfma_f32_16x16x32_bf16 v[26:29], v[148:151], v[188:191], v[26:29]
	v_mfma_f32_16x16x32_bf16 v[10:13], v[148:151], v[198:201], v[10:13]
	v_mfma_f32_16x16x32_bf16 v[10:13], v[152:155], v[202:205], v[10:13]
	v_mfma_f32_16x16x32_bf16 v[14:17], v[144:147], v[202:205], v[14:17]
	v_mfma_f32_16x16x32_bf16 v[14:17], v[140:143], v[198:201], v[14:17]
	s_setprio 0
	s_setprio 1
	v_mfma_f32_16x16x32_bf16 v[54:57], v[156:159], v[172:175], v[54:57]
	v_mfma_f32_16x16x32_bf16 v[54:57], v[160:163], v[176:179], v[54:57]
	v_mfma_f32_16x16x32_bf16 v[50:53], v[168:171], v[176:179], v[50:53]
	v_mfma_f32_16x16x32_bf16 v[50:53], v[164:167], v[172:175], v[50:53]
	v_mfma_f32_16x16x32_bf16 v[34:37], v[164:167], v[180:183], v[34:37]
	v_mfma_f32_16x16x32_bf16 v[34:37], v[168:171], v[184:187], v[34:37]
	v_mfma_f32_16x16x32_bf16 v[38:41], v[160:163], v[184:187], v[38:41]
	v_mfma_f32_16x16x32_bf16 v[38:41], v[156:159], v[180:183], v[38:41]
	v_mfma_f32_16x16x32_bf16 v[22:25], v[156:159], v[188:191], v[22:25]
	v_mfma_f32_16x16x32_bf16 v[22:25], v[160:163], v[192:195], v[22:25]
	v_mfma_f32_16x16x32_bf16 v[18:21], v[168:171], v[192:195], v[18:21]
	v_mfma_f32_16x16x32_bf16 v[18:21], v[164:167], v[188:191], v[18:21]
	v_mfma_f32_16x16x32_bf16 v[2:5], v[164:167], v[198:201], v[2:5]
	v_mfma_f32_16x16x32_bf16 v[2:5], v[168:171], v[202:205], v[2:5]
	v_mfma_f32_16x16x32_bf16 v[6:9], v[160:163], v[202:205], v[6:9]
	v_mfma_f32_16x16x32_bf16 v[6:9], v[156:159], v[198:201], v[6:9]
	s_setprio 0
	s_barrier
	s_add_i32 s34, s60, 2
	s_cmp_ge_i32 s60, s57
	s_mov_b64 s[28:29], s[30:31]
	s_mov_b32 s60, s34
	s_cbranch_scc1 .Lpeel_exit_w2
.LBB0_1030:
	s_add_i32 s30, s60, -2
	s_lshr_b32 s44, s30, 2
	s_lshl_b64 s[34:35], s[44:45], 17
	s_lshr_b32 s44, s60, 2
	s_and_b32 s61, s28, 0x100
	s_lshl_b64 s[30:31], s[44:45], 17
	s_add_u32 s44, s26, s30
	s_addc_u32 s62, s27, s31
	s_add_u32 s30, s28, 0x100
	s_addc_u32 s31, s29, 0
	s_and_b32 s63, s30, 0x100
	s_add_u32 s44, s44, s63
	s_addc_u32 s62, s62, 0
	s_add_u32 s28, s58, s28
	s_addc_u32 s29, s59, s29
	s_add_i32 s64, 0, 0x10000
	s_add_u32 s63, s26, s34
	s_addc_u32 s65, s27, s35
	s_cmp_eq_u32 s57, s60
	s_cselect_b32 s35, s23, s62
	s_cselect_b32 s34, s22, s44
	s_cselect_b32 s29, s25, s29
	s_cselect_b32 s28, s24, s28
	s_add_i32 s44, 0, 0x14000
	v_add_u32_e32 v152, s64, v137
	v_add_u32_e32 v168, s44, v137
	ds_read_b128 v[140:143], v152
	ds_read_b128 v[144:147], v152 offset:1024
	ds_read_b128 v[148:151], v152 offset:2048
	ds_read_b128 v[152:155], v152 offset:3072
	ds_read_b128 v[156:159], v168
	ds_read_b128 v[160:163], v168 offset:1024
	ds_read_b128 v[164:167], v168 offset:2048
	ds_read_b128 v[168:171], v168 offset:3072
	s_add_u32 s61, s63, s61
	s_addc_u32 s63, s65, 0
	s_add_u32 s62, s61, 0x10080
	s_addc_u32 s63, s63, 0
	v_lshl_add_u64 v[206:207], s[62:63], 0, v[130:131]
	s_add_i32 m0, s33, 0xc000
	ds_read_b128 v[172:175], v139
	ds_read_b128 v[176:179], v139 offset:1024
	ds_read_b128 v[180:183], v139 offset:2048
	ds_read_b128 v[184:187], v139 offset:3072
	ds_read_b128 v[188:191], v139 offset:4096
	ds_read_b128 v[192:195], v139 offset:5120
	ds_read_b128 v[198:201], v139 offset:6144
	ds_read_b128 v[202:205], v139 offset:7168
	global_load_lds_dwordx4 v[206:207], off
	v_lshl_add_u64 v[206:207], s[62:63], 0, v[132:133]
	s_add_i32 m0, s33, 0xe000
	s_nop 0
	global_load_lds_dwordx4 v[206:207], off
	s_waitcnt vmcnt(8)
	s_waitcnt lgkmcnt(0)
	s_barrier
	s_setprio 1
	v_mfma_f32_16x16x32_bf16 v[126:129], v[140:143], v[172:175], v[126:129]
	v_mfma_f32_16x16x32_bf16 v[126:129], v[144:147], v[176:179], v[126:129]
	v_mfma_f32_16x16x32_bf16 v[122:125], v[152:155], v[176:179], v[122:125]
	v_mfma_f32_16x16x32_bf16 v[122:125], v[148:151], v[172:175], v[122:125]
	v_mfma_f32_16x16x32_bf16 v[106:109], v[148:151], v[180:183], v[106:109]
	v_mfma_f32_16x16x32_bf16 v[106:109], v[152:155], v[184:187], v[106:109]
	v_mfma_f32_16x16x32_bf16 v[110:113], v[144:147], v[184:187], v[110:113]
	v_mfma_f32_16x16x32_bf16 v[110:113], v[140:143], v[180:183], v[110:113]
	v_mfma_f32_16x16x32_bf16 v[94:97], v[140:143], v[188:191], v[94:97]
	v_mfma_f32_16x16x32_bf16 v[94:97], v[144:147], v[192:195], v[94:97]
	v_mfma_f32_16x16x32_bf16 v[90:93], v[152:155], v[192:195], v[90:93]
	v_mfma_f32_16x16x32_bf16 v[90:93], v[148:151], v[188:191], v[90:93]
	v_mfma_f32_16x16x32_bf16 v[74:77], v[148:151], v[198:201], v[74:77]
	v_mfma_f32_16x16x32_bf16 v[74:77], v[152:155], v[202:205], v[74:77]
	v_mfma_f32_16x16x32_bf16 v[78:81], v[144:147], v[202:205], v[78:81]
	v_mfma_f32_16x16x32_bf16 v[78:81], v[140:143], v[198:201], v[78:81]
	s_setprio 0
	s_setprio 1
	v_mfma_f32_16x16x32_bf16 v[118:121], v[156:159], v[172:175], v[118:121]
	v_mfma_f32_16x16x32_bf16 v[118:121], v[160:163], v[176:179], v[118:121]
	v_mfma_f32_16x16x32_bf16 v[114:117], v[168:171], v[176:179], v[114:117]
	v_mfma_f32_16x16x32_bf16 v[114:117], v[164:167], v[172:175], v[114:117]
	v_mfma_f32_16x16x32_bf16 v[98:101], v[164:167], v[180:183], v[98:101]
	v_mfma_f32_16x16x32_bf16 v[98:101], v[168:171], v[184:187], v[98:101]
	v_mfma_f32_16x16x32_bf16 v[102:105], v[160:163], v[184:187], v[102:105]
	v_mfma_f32_16x16x32_bf16 v[102:105], v[156:159], v[180:183], v[102:105]
	v_mfma_f32_16x16x32_bf16 v[86:89], v[156:159], v[188:191], v[86:89]
	v_mfma_f32_16x16x32_bf16 v[86:89], v[160:163], v[192:195], v[86:89]
	v_mfma_f32_16x16x32_bf16 v[82:85], v[168:171], v[192:195], v[82:85]
	v_mfma_f32_16x16x32_bf16 v[82:85], v[164:167], v[188:191], v[82:85]
	v_mfma_f32_16x16x32_bf16 v[66:69], v[164:167], v[198:201], v[66:69]
	v_mfma_f32_16x16x32_bf16 v[66:69], v[168:171], v[202:205], v[66:69]
	v_mfma_f32_16x16x32_bf16 v[70:73], v[160:163], v[202:205], v[70:73]
	v_mfma_f32_16x16x32_bf16 v[70:73], v[156:159], v[198:201], v[70:73]
	s_setprio 0
	s_barrier
	s_add_i32 s61, s64, s9
	v_lshl_add_u64 v[206:207], s[28:29], 0, v[196:197]
	s_mov_b32 m0, s61
	ds_read_b128 v[172:175], v139 offset:16384
	ds_read_b128 v[176:179], v139 offset:17408
	ds_read_b128 v[180:183], v139 offset:18432
	ds_read_b128 v[184:187], v139 offset:19456
	ds_read_b128 v[188:191], v139 offset:20480
	ds_read_b128 v[192:195], v139 offset:21504
	ds_read_b128 v[198:201], v139 offset:22528
	ds_read_b128 v[202:205], v139 offset:23552
	global_load_lds_dwordx4 v[206:207], off
	s_add_i32 m0, s61, 0x2000
	s_add_u32 s62, s28, 0x204000
	v_lshl_add_u64 v[208:209], s[28:29], 0, v[134:135]
	s_addc_u32 s63, s29, 0
	s_add_i32 s44, s44, s9
	global_load_lds_dwordx4 v[208:209], off
	v_lshl_add_u64 v[210:211], s[62:63], 0, v[196:197]
	s_mov_b32 m0, s44
	v_lshl_add_u64 v[212:213], s[34:35], 0, v[132:133]
	global_load_lds_dwordx4 v[210:211], off
	v_lshl_add_u64 v[210:211], s[62:63], 0, v[134:135]
	s_add_i32 m0, s44, 0x2000
	s_nop 0
	global_load_lds_dwordx4 v[210:211], off
	v_lshl_add_u64 v[210:211], s[34:35], 0, v[130:131]
	s_mov_b32 m0, s33
	s_nop 0
	global_load_lds_dwordx4 v[210:211], off
	s_mov_b32 m0, s36
	s_nop 0
	global_load_lds_dwordx4 v[212:213], off
	s_waitcnt vmcnt(8)
	s_waitcnt lgkmcnt(0)
	s_barrier
	s_setprio 1
	v_mfma_f32_16x16x32_bf16 v[62:65], v[140:143], v[172:175], v[62:65]
	v_mfma_f32_16x16x32_bf16 v[62:65], v[144:147], v[176:179], v[62:65]
	v_mfma_f32_16x16x32_bf16 v[58:61], v[152:155], v[176:179], v[58:61]
	v_mfma_f32_16x16x32_bf16 v[58:61], v[148:151], v[172:175], v[58:61]
	v_mfma_f32_16x16x32_bf16 v[42:45], v[148:151], v[180:183], v[42:45]
	v_mfma_f32_16x16x32_bf16 v[42:45], v[152:155], v[184:187], v[42:45]
	v_mfma_f32_16x16x32_bf16 v[46:49], v[144:147], v[184:187], v[46:49]
	v_mfma_f32_16x16x32_bf16 v[46:49], v[140:143], v[180:183], v[46:49]
	v_mfma_f32_16x16x32_bf16 v[30:33], v[140:143], v[188:191], v[30:33]
	v_mfma_f32_16x16x32_bf16 v[30:33], v[144:147], v[192:195], v[30:33]
	v_mfma_f32_16x16x32_bf16 v[26:29], v[152:155], v[192:195], v[26:29]
	v_mfma_f32_16x16x32_bf16 v[26:29], v[148:151], v[188:191], v[26:29]
	v_mfma_f32_16x16x32_bf16 v[10:13], v[148:151], v[198:201], v[10:13]
	v_mfma_f32_16x16x32_bf16 v[10:13], v[152:155], v[202:205], v[10:13]
	v_mfma_f32_16x16x32_bf16 v[14:17], v[144:147], v[202:205], v[14:17]
	v_mfma_f32_16x16x32_bf16 v[14:17], v[140:143], v[198:201], v[14:17]
	s_setprio 0
	s_setprio 1
	v_mfma_f32_16x16x32_bf16 v[54:57], v[156:159], v[172:175], v[54:57]
	v_mfma_f32_16x16x32_bf16 v[54:57], v[160:163], v[176:179], v[54:57]
	v_mfma_f32_16x16x32_bf16 v[50:53], v[168:171], v[176:179], v[50:53]
	v_mfma_f32_16x16x32_bf16 v[50:53], v[164:167], v[172:175], v[50:53]
	v_mfma_f32_16x16x32_bf16 v[34:37], v[164:167], v[180:183], v[34:37]
	v_mfma_f32_16x16x32_bf16 v[34:37], v[168:171], v[184:187], v[34:37]
	v_mfma_f32_16x16x32_bf16 v[38:41], v[160:163], v[184:187], v[38:41]
	v_mfma_f32_16x16x32_bf16 v[38:41], v[156:159], v[180:183], v[38:41]
	v_mfma_f32_16x16x32_bf16 v[22:25], v[156:159], v[188:191], v[22:25]
	v_mfma_f32_16x16x32_bf16 v[22:25], v[160:163], v[192:195], v[22:25]
	v_mfma_f32_16x16x32_bf16 v[18:21], v[168:171], v[192:195], v[18:21]
	v_mfma_f32_16x16x32_bf16 v[18:21], v[164:167], v[188:191], v[18:21]
	v_mfma_f32_16x16x32_bf16 v[2:5], v[164:167], v[198:201], v[2:5]
	v_mfma_f32_16x16x32_bf16 v[2:5], v[168:171], v[202:205], v[2:5]
	v_mfma_f32_16x16x32_bf16 v[6:9], v[160:163], v[202:205], v[6:9]
	v_mfma_f32_16x16x32_bf16 v[6:9], v[156:159], v[198:201], v[6:9]
	s_setprio 0
	s_barrier
	s_add_i32 s44, 0, 0x18000
	s_add_i32 s61, 0, 0x1c000
	v_add_u32_e32 v152, s44, v137
	v_add_u32_e32 v168, s61, v137
	ds_read_b128 v[140:143], v152
	ds_read_b128 v[144:147], v152 offset:1024
	ds_read_b128 v[148:151], v152 offset:2048
	ds_read_b128 v[152:155], v152 offset:3072
	ds_read_b128 v[156:159], v168
	ds_read_b128 v[160:163], v168 offset:1024
	ds_read_b128 v[164:167], v168 offset:2048
	ds_read_b128 v[168:171], v168 offset:3072
	s_add_u32 s34, s34, 0x10000
	s_addc_u32 s35, s35, 0
	s_mov_b32 m0, s37
	v_lshl_add_u64 v[214:215], s[34:35], 0, v[130:131]
	ds_read_b128 v[172:175], v139 offset:32768
	ds_read_b128 v[176:179], v139 offset:33792
	ds_read_b128 v[180:183], v139 offset:34816
	ds_read_b128 v[184:187], v139 offset:35840
	ds_read_b128 v[188:191], v139 offset:36864
	ds_read_b128 v[192:195], v139 offset:37888
	ds_read_b128 v[198:201], v139 offset:38912
	ds_read_b128 v[202:205], v139 offset:39936
	global_load_lds_dwordx4 v[214:215], off
	v_lshl_add_u64 v[214:215], s[34:35], 0, v[132:133]
	s_mov_b32 m0, s38
	s_nop 0
	global_load_lds_dwordx4 v[214:215], off
	s_waitcnt vmcnt(8)
	s_waitcnt lgkmcnt(0)
	s_barrier
	s_setprio 1
	v_mfma_f32_16x16x32_bf16 v[126:129], v[140:143], v[172:175], v[126:129]
	v_mfma_f32_16x16x32_bf16 v[126:129], v[144:147], v[176:179], v[126:129]
	v_mfma_f32_16x16x32_bf16 v[122:125], v[152:155], v[176:179], v[122:125]
	v_mfma_f32_16x16x32_bf16 v[122:125], v[148:151], v[172:175], v[122:125]
	v_mfma_f32_16x16x32_bf16 v[106:109], v[148:151], v[180:183], v[106:109]
	v_mfma_f32_16x16x32_bf16 v[106:109], v[152:155], v[184:187], v[106:109]
	v_mfma_f32_16x16x32_bf16 v[110:113], v[144:147], v[184:187], v[110:113]
	v_mfma_f32_16x16x32_bf16 v[110:113], v[140:143], v[180:183], v[110:113]
	v_mfma_f32_16x16x32_bf16 v[94:97], v[140:143], v[188:191], v[94:97]
	v_mfma_f32_16x16x32_bf16 v[94:97], v[144:147], v[192:195], v[94:97]
	v_mfma_f32_16x16x32_bf16 v[90:93], v[152:155], v[192:195], v[90:93]
	v_mfma_f32_16x16x32_bf16 v[90:93], v[148:151], v[188:191], v[90:93]
	v_mfma_f32_16x16x32_bf16 v[74:77], v[148:151], v[198:201], v[74:77]
	v_mfma_f32_16x16x32_bf16 v[74:77], v[152:155], v[202:205], v[74:77]
	v_mfma_f32_16x16x32_bf16 v[78:81], v[144:147], v[202:205], v[78:81]
	v_mfma_f32_16x16x32_bf16 v[78:81], v[140:143], v[198:201], v[78:81]
	s_setprio 0
	s_setprio 1
	v_mfma_f32_16x16x32_bf16 v[118:121], v[156:159], v[172:175], v[118:121]
	v_mfma_f32_16x16x32_bf16 v[118:121], v[160:163], v[176:179], v[118:121]
	v_mfma_f32_16x16x32_bf16 v[114:117], v[168:171], v[176:179], v[114:117]
	v_mfma_f32_16x16x32_bf16 v[114:117], v[164:167], v[172:175], v[114:117]
	v_mfma_f32_16x16x32_bf16 v[98:101], v[164:167], v[180:183], v[98:101]
	v_mfma_f32_16x16x32_bf16 v[98:101], v[168:171], v[184:187], v[98:101]
	v_mfma_f32_16x16x32_bf16 v[102:105], v[160:163], v[184:187], v[102:105]
	v_mfma_f32_16x16x32_bf16 v[102:105], v[156:159], v[180:183], v[102:105]
	v_mfma_f32_16x16x32_bf16 v[86:89], v[156:159], v[188:191], v[86:89]
	v_mfma_f32_16x16x32_bf16 v[86:89], v[160:163], v[192:195], v[86:89]
	v_mfma_f32_16x16x32_bf16 v[82:85], v[168:171], v[192:195], v[82:85]
	v_mfma_f32_16x16x32_bf16 v[82:85], v[164:167], v[188:191], v[82:85]
	v_mfma_f32_16x16x32_bf16 v[66:69], v[164:167], v[198:201], v[66:69]
	v_mfma_f32_16x16x32_bf16 v[66:69], v[168:171], v[202:205], v[66:69]
	v_mfma_f32_16x16x32_bf16 v[70:73], v[160:163], v[202:205], v[70:73]
	v_mfma_f32_16x16x32_bf16 v[70:73], v[156:159], v[198:201], v[70:73]
	s_setprio 0
	s_barrier
	s_add_i32 s34, s44, s9
	v_lshl_add_u64 v[206:207], v[206:207], 0, s[2:3]
	s_mov_b32 m0, s34
	ds_read_b128 v[172:175], v139 offset:49152
	ds_read_b128 v[176:179], v139 offset:50176
	ds_read_b128 v[180:183], v139 offset:51200
	ds_read_b128 v[184:187], v139 offset:52224
	ds_read_b128 v[188:191], v139 offset:53248
	ds_read_b128 v[192:195], v139 offset:54272
	ds_read_b128 v[198:201], v139 offset:55296
	ds_read_b128 v[202:205], v139 offset:56320
	global_load_lds_dwordx4 v[206:207], off
	s_add_i32 m0, s34, 0x2000
	s_add_u32 s28, s28, 0x204080
	v_lshl_add_u64 v[206:207], v[208:209], 0, s[2:3]
	s_addc_u32 s29, s29, 0
	s_add_i32 s34, s61, s9
	global_load_lds_dwordx4 v[206:207], off
	v_lshl_add_u64 v[206:207], s[28:29], 0, v[196:197]
	s_mov_b32 m0, s34
	s_nop 0
	global_load_lds_dwordx4 v[206:207], off
	v_lshl_add_u64 v[206:207], s[28:29], 0, v[134:135]
	s_add_i32 m0, s34, 0x2000
	s_nop 0
	global_load_lds_dwordx4 v[206:207], off
	v_lshl_add_u64 v[206:207], v[210:211], 0, s[2:3]
	s_mov_b32 m0, s47
	s_nop 0
	global_load_lds_dwordx4 v[206:207], off
	v_lshl_add_u64 v[206:207], v[212:213], 0, s[2:3]
	s_mov_b32 m0, s49
	s_nop 0
	global_load_lds_dwordx4 v[206:207], off
	s_waitcnt vmcnt(8)
	s_waitcnt lgkmcnt(0)
	s_barrier
	s_setprio 1
	s_waitcnt lgkmcnt(0)
	v_mfma_f32_16x16x32_bf16 v[62:65], v[140:143], v[172:175], v[62:65]
	v_mfma_f32_16x16x32_bf16 v[62:65], v[144:147], v[176:179], v[62:65]
	v_mfma_f32_16x16x32_bf16 v[58:61], v[152:155], v[176:179], v[58:61]
	v_mfma_f32_16x16x32_bf16 v[58:61], v[148:151], v[172:175], v[58:61]
	v_mfma_f32_16x16x32_bf16 v[42:45], v[148:151], v[180:183], v[42:45]
	v_mfma_f32_16x16x32_bf16 v[42:45], v[152:155], v[184:187], v[42:45]
	v_mfma_f32_16x16x32_bf16 v[46:49], v[144:147], v[184:187], v[46:49]
	v_mfma_f32_16x16x32_bf16 v[46:49], v[140:143], v[180:183], v[46:49]
	v_mfma_f32_16x16x32_bf16 v[30:33], v[140:143], v[188:191], v[30:33]
	v_mfma_f32_16x16x32_bf16 v[30:33], v[144:147], v[192:195], v[30:33]
	v_mfma_f32_16x16x32_bf16 v[26:29], v[152:155], v[192:195], v[26:29]
	v_mfma_f32_16x16x32_bf16 v[26:29], v[148:151], v[188:191], v[26:29]
	v_mfma_f32_16x16x32_bf16 v[10:13], v[148:151], v[198:201], v[10:13]
	v_mfma_f32_16x16x32_bf16 v[10:13], v[152:155], v[202:205], v[10:13]
	v_mfma_f32_16x16x32_bf16 v[14:17], v[144:147], v[202:205], v[14:17]
	v_mfma_f32_16x16x32_bf16 v[14:17], v[140:143], v[198:201], v[14:17]
	s_setprio 0
	s_setprio 1
	v_mfma_f32_16x16x32_bf16 v[54:57], v[156:159], v[172:175], v[54:57]
	v_mfma_f32_16x16x32_bf16 v[54:57], v[160:163], v[176:179], v[54:57]
	v_mfma_f32_16x16x32_bf16 v[50:53], v[168:171], v[176:179], v[50:53]
	v_mfma_f32_16x16x32_bf16 v[50:53], v[164:167], v[172:175], v[50:53]
	v_mfma_f32_16x16x32_bf16 v[34:37], v[164:167], v[180:183], v[34:37]
	v_mfma_f32_16x16x32_bf16 v[34:37], v[168:171], v[184:187], v[34:37]
	v_mfma_f32_16x16x32_bf16 v[38:41], v[160:163], v[184:187], v[38:41]
	v_mfma_f32_16x16x32_bf16 v[38:41], v[156:159], v[180:183], v[38:41]
	v_mfma_f32_16x16x32_bf16 v[22:25], v[156:159], v[188:191], v[22:25]
	v_mfma_f32_16x16x32_bf16 v[22:25], v[160:163], v[192:195], v[22:25]
	v_mfma_f32_16x16x32_bf16 v[18:21], v[168:171], v[192:195], v[18:21]
	v_mfma_f32_16x16x32_bf16 v[18:21], v[164:167], v[188:191], v[18:21]
	v_mfma_f32_16x16x32_bf16 v[2:5], v[164:167], v[198:201], v[2:5]
	v_mfma_f32_16x16x32_bf16 v[2:5], v[168:171], v[202:205], v[2:5]
	v_mfma_f32_16x16x32_bf16 v[6:9], v[160:163], v[202:205], v[6:9]
	v_mfma_f32_16x16x32_bf16 v[6:9], v[156:159], v[198:201], v[6:9]
	s_setprio 0
	s_barrier
	s_add_i32 s34, s60, 2
	s_cmp_ge_i32 s60, s57
	s_mov_b64 s[28:29], s[30:31]
	s_mov_b32 s60, s34
	s_cbranch_scc0 .LBB0_1030
